# combination + packed f32 ops of P6 and of the P3 chunk-state unit split into scalar pairs
# baseline (speedup 1.0000x reference)
; __device__ __forceinline__ int v_st(int k, int c) { const int kk = (k & ~0xC) | ((k & 4) << 1) | ((k & 8) >> 1); return ((kk >> 3) * 4 + (c >> 5)) * 512 + ((kk & 7) * 32 + (c & 31)) * 2; }
; __device__ __forceinline__ int v_st64(int k, int c) { const int kk = (k & ~0xC) | ((k & 4) << 1) | ((k & 8) >> 1); return ((kk >> 3) * 2 + (c >> 5)) * 512 + ((kk & 7) * 32 + (c & 31)) * 2; }
; __device__ __forceinline__ float log2_sigmoid(float x) { return -log1pf(expf(-x)) * 1.4426950408889634f; }
; __device__ __forceinline__ void state_unit(const bf16* __restrict__ Kc, const bf16* __restrict__ Vc, float* __restrict__ Sf, float* __restrict__ Sb, float lgf2, float lgb2, char* lds) {
;     int tid = threadIdx.x; asm volatile("" : "+v"(tid));
;     const int wid = tid >> 6, lane = tid & 63, r32 = lane & 31, hi = lane >> 5;
;     const int sr = tid >> 4, sc = (tid & 15) * 8, vst0 = v_st(sr, sc), vst1 = v_st(32 + sr, sc);
;     const int kr = tid >> 3, kc = (tid & 7) * 8, kst = v_st64(kr, kc);
; #pragma unroll
;     for (int t = 0; t < 4; ++t) {
;         const bf16x8 a0 = *reinterpret_cast<const bf16x8*>(Vc + (size_t)(64 * t + sr) * 128 + sc), a1 = *reinterpret_cast<const bf16x8*>(Vc + (size_t)(64 * t + 32 + sr) * 128 + sc);
;         const bf16x8 k0 = *reinterpret_cast<const bf16x8*>(Kc + (size_t)(64 * t + kr) * 64 + kc);
;         const int i = 64 * t + kr;
;         const float wf = __builtin_amdgcn_exp2f((float)(255 - i) * lgf2), wb = __builtin_amdgcn_exp2f((float)i * lgb2);
;         *(bf16x8*)(lds + t * 32768 + vst0) = a0; *(bf16x8*)(lds + t * 32768 + vst1) = a1;
;         *(bf16x8*)(lds + t * 32768 + 16384 + kst) = scale8(k0, wf); *(bf16x8*)(lds + t * 32768 + 24576 + kst) = scale8(k0, wb);
; __global__ void __launch_bounds__(NTHR, 2) mega(Args args) {
;     ...
;         for (int idx = blockIdx.x; idx < 288; idx += G) {
;             const int b = idx & 7, rest = idx >> 3, h = rest / 9, c = rest % 9;
;             float* st = (float*)(ws + WS_ST) + ((size_t)((b * 4 + h) * 9 + c) * 2) * 8192;
;             ret::state_unit((const bf16*)(ws + WS_RK) + ((size_t)(b * 4 + h) * LT + 256 * c) * 64, (const bf16*)(ws + WS_RV) + ((size_t)(b * 4 + h) * LT + 256 * c) * 128,
;                             st, st + 8192, ret::log2_sigmoid(decay[h]), ret::log2_sigmoid(decay[4 + h]), (char*)lds_raw);
.LBB0_536:
	s_ashr_i32 s0, s59, 3
	s_mul_hi_i32 s4, s0, 0x38e38e39
	s_lshr_b32 s5, s4, 31
	s_ashr_i32 s4, s4, 1
	s_and_b32 s1, s17, 28
	s_add_i32 s64, s4, s5
	s_mul_i32 s4, s64, 9
	s_add_i32 s1, s1, s64
	s_sub_i32 s6, s0, s4
	s_mul_i32 s0, s1, 9
	s_add_i32 s0, s0, s6
	s_mul_hi_i32 s7, s1, 0x900
	s_mul_i32 s10, s1, 0x900
	s_ashr_i32 s1, s0, 31
	s_lshl_b64 s[0:1], s[0:1], 16
	s_add_u32 s4, s3, s0
	s_addc_u32 s5, s12, s1
	s_lshl_b32 s0, s6, 8
	s_ashr_i32 s1, s0, 31
	s_add_u32 s6, s10, s0
	s_addc_u32 s7, s7, s1
	s_lshl_b64 s[0:1], s[6:7], 7
	s_add_u32 s0, s13, s0
	s_addc_u32 s1, s14, s1
	s_lshl_b64 s[6:7], s[6:7], 8
	s_add_u32 s10, s15, s6
	s_addc_u32 s11, s16, s7
	s_add_u32 s6, s4, 0x8000
	s_addc_u32 s7, s5, 0
	s_ashr_i32 s65, s64, 31
	s_lshl_b64 s[64:65], s[64:65], 2
	s_add_u32 s64, s54, s64
	v_mov_b32_e32 v64, v0
	s_addc_u32 s65, s55, s65
	global_load_dword v37, v35, s[64:65]
	global_load_dword v71, v35, s[64:65] offset:16
	s_cmp_lg_u32 0, -1
	v_ashrrev_i32_e32 v2, 4, v64
	v_lshlrev_b32_e32 v7, 3, v64
	v_ashrrev_i32_e32 v4, 3, v64
	v_and_b32_e32 v11, 0x78, v7
	v_and_b32_e32 v13, 0xfffff0, v2
	v_lshlrev_b32_e32 v14, 1, v2
	v_lshrrev_b32_e32 v15, 1, v2
	v_and_b32_e32 v16, 3, v2
	v_add_u32_e32 v6, 32, v2
	v_and_b32_e32 v19, 0x1fffff0, v4
	v_lshlrev_b32_e32 v20, 1, v4
	v_lshrrev_b32_e32 v21, 1, v4
	v_and_b32_e32 v23, 3, v4
	v_ashrrev_i32_e32 v3, 31, v2
	v_sub_u32_e32 v24, 0xff, v4
	v_and_or_b32 v14, v14, 8, v13
	v_and_or_b32 v15, v15, 4, v16
	v_lshlrev_b32_e32 v34, 1, v11
	v_bfe_u32 v18, v7, 5, 2
	v_and_b32_e32 v17, 56, v7
	v_bfe_u32 v22, v7, 5, 1
	v_and_b32_e32 v28, 24, v7
	v_and_b32_e32 v31, 0x100, v7
	v_and_or_b32 v19, v20, 8, v19
	v_and_or_b32 v20, v21, 4, v23
	v_lshlrev_b64 v[2:3], 8, v[2:3]
	v_ashrrev_i32_e32 v7, 31, v6
	v_cvt_f32_i32_e32 v115, v24
	v_lshrrev_b32_e32 v23, 1, v14
	v_lshlrev_b32_e32 v24, 6, v15
	v_lshl_add_u64 v[14:15], s[10:11], 0, v[34:35]
	v_lshlrev_b32_e32 v65, 4, v64
	v_and_b32_e32 v16, 0xfffff0, v6
	v_lshlrev_b32_e32 v32, 1, v6
	v_lshlrev_b64 v[6:7], 8, v[6:7]
	v_lshl_add_u64 v[2:3], v[14:15], 0, v[2:3]
	v_lshlrev_b32_e32 v9, 1, v64
	s_cselect_b32 s64, 0, 0
	v_and_b32_e32 v29, 0xc0, v65
	v_lshl_add_u64 v[6:7], v[14:15], 0, v[6:7]
	v_add_co_u32_e32 v14, vcc, s47, v2
	v_sub_u32_e32 v26, 0x7f, v4
	v_sub_u32_e32 v27, 63, v4
	v_and_b32_e32 v30, 32, v9
	v_add3_u32 v21, v29, s64, v28
	v_addc_co_u32_e32 v15, vcc, 0, v3, vcc
	v_cvt_f32_i32_e32 v118, v26
	v_cvt_f32_i32_e32 v120, v27
	v_and_or_b32 v16, v32, 8, v16
	v_add3_u32 v70, v21, v30, v31
	global_load_dwordx4 v[26:29], v[2:3], off
	global_load_dwordx4 v[30:33], v[6:7], off
	v_add_co_u32_e32 v6, vcc, s48, v2
	v_and_b32_e32 v48, 48, v65
	v_lshrrev_b32_e32 v19, 2, v19
	v_or_b32_e32 v21, v23, v18
	v_lshrrev_b32_e32 v23, 1, v16
	v_addc_co_u32_e32 v7, vcc, 0, v3, vcc
	v_lshl_or_b32 v20, v20, 6, v48
	v_or_b32_e32 v19, v19, v22
	v_or_b32_e32 v22, v23, v18
	v_add_co_u32_e32 v18, vcc, s49, v2
	v_lshl_or_b32 v23, v19, 9, v20
	s_nop 0
	v_addc_co_u32_e32 v19, vcc, 0, v3, vcc
	v_add_co_u32_e32 v20, vcc, s50, v2
	v_lshlrev_b32_e32 v52, 9, v21
	s_nop 0
	v_addc_co_u32_e32 v21, vcc, 0, v3, vcc
	v_add_u32_e32 v8, 64, v4
	v_add_co_u32_e32 v46, vcc, s51, v2
	v_ashrrev_i32_e32 v5, 31, v4
	v_add_u32_e32 v10, 0x80, v4
	v_add_u32_e32 v12, 0xc0, v4
	v_ashrrev_i32_e32 v9, 31, v8
	v_lshlrev_b32_e32 v34, 1, v17
	v_addc_co_u32_e32 v47, vcc, 0, v3, vcc
	v_cvt_f32_i32_e32 v114, v4
	v_sub_u32_e32 v25, 0xbf, v4
	v_lshlrev_b64 v[4:5], 7, v[4:5]
	v_cvt_f32_i32_e32 v117, v8
	v_ashrrev_i32_e32 v11, 31, v10
	v_ashrrev_i32_e32 v13, 31, v12
	v_lshlrev_b64 v[8:9], 7, v[8:9]
	v_lshl_add_u64 v[16:17], s[0:1], 0, v[34:35]
	v_add_co_u32_e32 v2, vcc, s52, v2
	v_cvt_f32_i32_e32 v119, v10
	v_cvt_f32_i32_e32 v121, v12
	v_lshlrev_b64 v[10:11], 7, v[10:11]
	v_lshlrev_b64 v[12:13], 7, v[12:13]
	v_lshl_add_u64 v[4:5], v[16:17], 0, v[4:5]
	v_lshl_add_u64 v[8:9], v[16:17], 0, v[8:9]
	v_addc_co_u32_e32 v3, vcc, 0, v3, vcc
	v_lshl_add_u64 v[10:11], v[16:17], 0, v[10:11]
	v_lshl_add_u64 v[12:13], v[16:17], 0, v[12:13]
	global_load_dwordx4 v[38:41], v[4:5], off
	global_load_dwordx4 v[42:45], v[8:9], off
	global_load_dwordx4 v[84:87], v[10:11], off
	global_load_dwordx4 v[88:91], v[12:13], off
	s_nop 0
	global_load_dwordx4 v[6:9], v[6:7], off
	s_nop 0
	global_load_dwordx4 v[2:5], v[2:3], off
	v_cvt_f32_i32_e32 v116, v25
	v_add_u32_e32 v49, 0, v24
	v_add_u32_e32 v50, s53, v24
	v_add_u32_e32 v51, s58, v24
	v_lshlrev_b32_e32 v53, 9, v22
	v_add_u32_e32 v73, 0, v23
	global_load_dwordx4 v[22:25], v[14:15], off
	s_nop 0
	global_load_dwordx4 v[14:17], v[18:19], off
	s_nop 0
	global_load_dwordx4 v[18:21], v[20:21], off
	v_add3_u32 v75, v49, v52, v48
	global_load_dwordx4 v[10:13], v[46:47], off
	s_waitcnt vmcnt(13)
	v_mul_f32_e32 v46, 0xbfb8aa3b, v37
	v_add3_u32 v76, v50, v52, v48
	v_add3_u32 v74, v51, v52, v48
	v_add3_u32 v83, v49, v53, v48
	v_add3_u32 v80, v50, v53, v48
	v_add3_u32 v77, v51, v53, v48
	s_waitcnt vmcnt(12)
	v_mul_f32_e32 v47, 0xbfb8aa3b, v71
	v_fma_f32 v48, v37, s22, -v46
	v_rndne_f32_e32 v49, v46
	v_fma_f32 v50, v71, s22, -v47
	v_rndne_f32_e32 v51, v47
	v_fmac_f32_e32 v48, 0xb2a5705f, v37
	v_sub_f32_e32 v46, v46, v49
	v_fmac_f32_e32 v50, 0xb2a5705f, v71
	v_sub_f32_e32 v47, v47, v51
	v_add_f32_e32 v46, v46, v48
	v_cvt_i32_f32_e32 v92, v49
	v_add_f32_e32 v47, v47, v50
	v_exp_f32_e32 v94, v46
	v_cvt_i32_f32_e32 v93, v51
	v_exp_f32_e32 v95, v47
	v_cmp_nlt_f32_e64 s[0:1], s23, v37
	v_cmp_nlt_f32_e32 vcc, s23, v71
	s_waitcnt vmcnt(11)
	ds_write_b128 v75, v[26:29]
	s_waitcnt vmcnt(10)
; __device__ __forceinline__ unsigned pk2(float lo, float hi) { return f2bf(lo) | (f2bf(hi) << 16); }
; __device__ __forceinline__ float log2_sigmoid(float x) { return -log1pf(expf(-x)) * 1.4426950408889634f; }
; __device__ __forceinline__ bf16x8 scale8(bf16x8 v, float s) {
;     v4u w = *reinterpret_cast<v4u*>(&v), o;
; #pragma unroll
;     for (int i = 0; i < 4; ++i) { const float lo = __builtin_bit_cast(float, w[i] << 16) * s, hi = __builtin_bit_cast(float, w[i] & 0xffff0000u) * s; o[i] = pk2(lo, hi); }
;     return *reinterpret_cast<bf16x8*>(&o);
; __device__ __forceinline__ void state_unit(const bf16* __restrict__ Kc, const bf16* __restrict__ Vc, float* __restrict__ Sf, float* __restrict__ Sb, float lgf2, float lgb2, char* lds) {
;     ...
;         const bf16x8 a0 = *reinterpret_cast<const bf16x8*>(Vc + (size_t)(64 * t + sr) * 128 + sc), a1 = *reinterpret_cast<const bf16x8*>(Vc + (size_t)(64 * t + 32 + sr) * 128 + sc);
;         const bf16x8 k0 = *reinterpret_cast<const bf16x8*>(Kc + (size_t)(64 * t + kr) * 64 + kc);
;         const int i = 64 * t + kr;
;         const float wf = __builtin_amdgcn_exp2f((float)(255 - i) * lgf2), wb = __builtin_amdgcn_exp2f((float)i * lgb2);
;         *(bf16x8*)(lds + t * 32768 + vst0) = a0; *(bf16x8*)(lds + t * 32768 + vst1) = a1;
;         *(bf16x8*)(lds + t * 32768 + 16384 + kst) = scale8(k0, wf); *(bf16x8*)(lds + t * 32768 + 24576 + kst) = scale8(k0, wb);
	ds_write_b128 v83, v[30:33]
	v_bfe_u32 v67, v64, 6, 2
	v_lshlrev_b32_e32 v69, 9, v67
	v_ashrrev_i32_e32 v66, 8, v64
	v_add_u32_e32 v72, v70, v69
	v_add_u32_e32 v81, 0x14000, v73
	v_add_u32_e32 v82, 0x16000, v73
	v_add_u32_e32 v78, 0x1c000, v73
	v_add_u32_e32 v79, 0x1e000, v73
	v_lshl_add_u32 v68, v66, 9, v63
	v_add_u32_e32 v34, v70, v68
	s_waitcnt vmcnt(9)
	v_lshlrev_b32_e32 v54, 16, v38
	v_and_b32_e32 v56, 0xffff0000, v38
	v_lshlrev_b32_e32 v58, 16, v40
	v_and_b32_e32 v60, 0xffff0000, v40
	s_waitcnt vmcnt(7)
	v_lshlrev_b32_e32 v38, 16, v84
	v_and_b32_e32 v40, 0xffff0000, v84
	v_ldexp_f32 v84, v94, v92
	v_lshlrev_b32_e32 v55, 16, v39
	v_and_b32_e32 v57, 0xffff0000, v39
	v_lshlrev_b32_e32 v59, 16, v41
	v_and_b32_e32 v61, 0xffff0000, v41
	v_lshlrev_b32_e32 v39, 16, v85
	v_and_b32_e32 v41, 0xffff0000, v85
	v_ldexp_f32 v85, v95, v93
	v_cndmask_b32_e64 v84, 0, v84, s[0:1]
	v_cmp_ngt_f32_e64 s[0:1], s34, v37
	v_cndmask_b32_e32 v85, 0, v85, vcc
	v_cmp_ngt_f32_e32 vcc, s34, v71
	v_cndmask_b32_e64 v71, v1, v84, s[0:1]
	v_add_f32_e32 v37, 1.0, v71
	v_cndmask_b32_e32 v122, v1, v85, vcc
	s_waitcnt vmcnt(6)
	v_lshlrev_b32_e32 v27, 16, v89
	v_lshlrev_b32_e32 v26, 16, v88
	v_and_b32_e32 v29, 0xffff0000, v89
	v_and_b32_e32 v28, 0xffff0000, v88
	v_lshlrev_b32_e32 v30, 16, v90
	v_and_b32_e32 v32, 0xffff0000, v90
	v_add_f32_e32 v88, 1.0, v122
	v_add_f32_e32 v89, -1.0, v37
	v_frexp_mant_f32_e32 v90, v37
	v_cvt_f64_f32_e32 v[84:85], v37
	v_lshlrev_b32_e32 v47, 16, v43
	v_lshlrev_b32_e32 v46, 16, v42
	v_and_b32_e32 v49, 0xffff0000, v43
	v_and_b32_e32 v48, 0xffff0000, v42
	v_lshlrev_b32_e32 v51, 16, v45
	v_lshlrev_b32_e32 v50, 16, v44
	v_and_b32_e32 v53, 0xffff0000, v45
	v_and_b32_e32 v52, 0xffff0000, v44
	v_lshlrev_b32_e32 v43, 16, v87
	v_lshlrev_b32_e32 v42, 16, v86
	v_and_b32_e32 v45, 0xffff0000, v87
	v_and_b32_e32 v44, 0xffff0000, v86
	v_lshlrev_b32_e32 v31, 16, v91
	v_and_b32_e32 v33, 0xffff0000, v91
	v_add_f32_e32 v91, -1.0, v88
	v_frexp_mant_f32_e32 v92, v88
	v_cvt_f64_f32_e32 v[86:87], v88
	v_sub_f32_e32 v93, v89, v37
	v_frexp_exp_i32_f64_e32 v84, v[84:85]
	v_cmp_gt_f32_e32 vcc, s40, v90
	v_sub_f32_e32 v89, v71, v89
	v_sub_f32_e32 v85, v91, v88
	v_frexp_exp_i32_f64_e32 v86, v[86:87]
	v_cmp_gt_f32_e64 s[0:1], s40, v92
	v_add_f32_e32 v87, 1.0, v93
	v_subbrev_co_u32_e32 v84, vcc, 0, v84, vcc
	v_sub_f32_e32 v90, v122, v91
	v_add_f32_e32 v85, 1.0, v85
	v_subbrev_co_u32_e64 v86, vcc, 0, v86, s[0:1]
	v_add_f32_e32 v87, v89, v87
	v_sub_u32_e32 v89, 0, v84
	v_add_f32_e32 v85, v90, v85
	v_sub_u32_e32 v90, 0, v86
	v_ldexp_f32 v37, v37, v89
	v_ldexp_f32 v88, v88, v90
	v_ldexp_f32 v85, v85, v90
	v_add_f32_e32 v90, -1.0, v37
	v_add_f32_e32 v92, 1.0, v37
	v_ldexp_f32 v87, v87, v89
	v_add_f32_e32 v93, -1.0, v88
	v_add_f32_e32 v94, 1.0, v88
	v_add_f32_e32 v89, 1.0, v90
	v_add_f32_e32 v91, -1.0, v92
	v_add_f32_e32 v95, 1.0, v93
	v_add_f32_e32 v96, -1.0, v94
	v_sub_f32_e32 v89, v37, v89
	v_sub_f32_e32 v37, v37, v91
	v_sub_f32_e32 v91, v88, v95
	v_sub_f32_e32 v88, v88, v96
	v_add_f32_e32 v37, v87, v37
	v_add_f32_e32 v95, v87, v89
	v_add_f32_e32 v87, v85, v91
	v_add_f32_e32 v85, v85, v88
	v_add_f32_e32 v100, v92, v37
	v_add_f32_e32 v101, v94, v85
	v_rcp_f32_e32 v102, v100
	v_rcp_f32_e32 v103, v101
	v_add_f32_e32 v89, v90, v95
	v_add_f32_e32 v91, v93, v87
	v_sub_f32_e32 v88, v92, v100
	v_sub_f32_e32 v92, v94, v101
	v_mul_f32_e32 v105, v89, v102
	v_add_f32_e32 v85, v85, v92
	v_mul_f32_e32 v106, v91, v103
	v_mul_f32_e32 v92, v100, v105
	v_add_f32_e32 v37, v37, v88
	v_mul_f32_e32 v94, v101, v106
	v_fma_f32 v96, v105, v100, -v92
	v_fma_f32 v98, v106, v101, -v94
	v_fmac_f32_e32 v96, v105, v37
	v_sub_f32_e32 v90, v90, v89
	v_sub_f32_e32 v93, v93, v91
	v_fmac_f32_e32 v98, v106, v85
	v_add_f32_e32 v88, v92, v96
	v_add_f32_e32 v104, v95, v90
	v_add_f32_e32 v87, v87, v93
	v_add_f32_e32 v90, v94, v98
	v_sub_f32_e32 v93, v89, v88
	v_mov_b32_e32 v97, v88
	v_sub_f32_e32 v95, v91, v90
	v_add_f32_e64 v88, v88, -v92
	v_add_f32_e64 v89, v89, -v93
	v_mov_b32_e32 v99, v90
	v_add_f32_e64 v90, v90, -v94
	v_add_f32_e64 v91, v91, -v95
	v_add_f32_e64 v88, v88, -v96
	v_add_f32_e64 v89, v89, -v97
	v_add_f32_e64 v90, v90, -v98
	v_add_f32_e64 v91, v91, -v99
	v_add_f32_e32 v89, v104, v89
	v_add_f32_e32 v87, v87, v91
	v_add_f32_e32 v88, v88, v89
	v_add_f32_e32 v87, v90, v87
	v_add_f32_e32 v89, v93, v88
	v_add_f32_e32 v91, v95, v87
	v_mul_f32_e32 v90, v102, v89
	v_mul_f32_e32 v97, v103, v91
	v_mul_f32_e32 v92, v100, v90
	v_sub_f32_e32 v93, v93, v89
	v_add_f32_e32 v107, v105, v90
	v_mul_f32_e32 v94, v101, v97
	v_fma_f32 v96, v90, v100, -v92
	v_add_f32_e32 v104, v88, v93
	v_add_f32_e32 v108, v106, v97
	v_sub_f32_e32 v88, v107, v105
	v_fma_f32 v98, v97, v101, -v94
	v_fmac_f32_e32 v96, v90, v37
	v_sub_f32_e32 v93, v108, v106
	v_sub_f32_e32 v37, v90, v88
	v_fmac_f32_e32 v98, v97, v85
	v_add_f32_e32 v88, v92, v96
	v_sub_f32_e32 v95, v95, v91
	v_sub_f32_e32 v85, v97, v93
	v_add_f32_e32 v90, v94, v98
	v_sub_f32_e32 v93, v89, v88
	v_add_f32_e32 v87, v87, v95
	v_mov_b32_e32 v97, v88
	v_sub_f32_e32 v95, v91, v90
	v_add_f32_e64 v88, v88, -v92
	v_add_f32_e64 v89, v89, -v93
	v_mov_b32_e32 v99, v90
	v_add_f32_e64 v90, v90, -v94
	v_add_f32_e64 v91, v91, -v95
	v_add_f32_e64 v88, v88, -v96
	v_add_f32_e64 v89, v89, -v97
	v_add_f32_e64 v90, v90, -v98
	v_add_f32_e64 v91, v91, -v99
	v_add_f32_e32 v89, v104, v89
	v_add_f32_e32 v87, v87, v91
	v_add_f32_e32 v88, v88, v89
	v_add_f32_e32 v87, v90, v87
	v_add_f32_e32 v88, v93, v88
	v_add_f32_e32 v87, v95, v87
	v_mul_f32_e32 v88, v102, v88
	v_mul_f32_e32 v87, v103, v87
	v_add_f32_e32 v37, v37, v88
	v_cvt_f32_i32_e32 v84, v84
	v_add_f32_e32 v87, v85, v87
	v_add_f32_e32 v85, v107, v37
; __device__ __forceinline__ unsigned pk2(float lo, float hi) { return f2bf(lo) | (f2bf(hi) << 16); }
; __device__ __forceinline__ float log2_sigmoid(float x) { return -log1pf(expf(-x)) * 1.4426950408889634f; }
; __device__ __forceinline__ bf16x8 scale8(bf16x8 v, float s) {
;     v4u w = *reinterpret_cast<v4u*>(&v), o;
; #pragma unroll
;     for (int i = 0; i < 4; ++i) { const float lo = __builtin_bit_cast(float, w[i] << 16) * s, hi = __builtin_bit_cast(float, w[i] & 0xffff0000u) * s; o[i] = pk2(lo, hi); }
;     return *reinterpret_cast<bf16x8*>(&o);
; __device__ __forceinline__ void state_unit(const bf16* __restrict__ Kc, const bf16* __restrict__ Vc, float* __restrict__ Sf, float* __restrict__ Sb, float lgf2, float lgb2, char* lds) {
;     ...
;         const int i = 64 * t + kr;
;         const float wf = __builtin_amdgcn_exp2f((float)(255 - i) * lgf2), wb = __builtin_amdgcn_exp2f((float)i * lgb2);
;         *(bf16x8*)(lds + t * 32768 + vst0) = a0; *(bf16x8*)(lds + t * 32768 + vst1) = a1;
;         *(bf16x8*)(lds + t * 32768 + 16384 + kst) = scale8(k0, wf); *(bf16x8*)(lds + t * 32768 + 24576 + kst) = scale8(k0, wb);
	v_add_f32_e32 v88, v108, v87
	v_mul_f32_e32 v90, v85, v85
	v_cvt_f32_i32_e32 v86, v86
	v_sub_f32_e32 v92, v85, v107
	v_sub_f32_e32 v93, v88, v108
	v_fmamk_f32 v95, v90, 0x3e9b6dac, v62
	v_ldexp_f32 v89, v85, 1
	v_mul_f32_e32 v94, v88, v88
	v_sub_f32_e32 v92, v37, v92
	v_mul_f32_e32 v85, v85, v90
	v_sub_f32_e32 v93, v87, v93
	v_fmaak_f32 v37, v90, v95, 0x3f2aaada
	v_fmamk_f32 v96, v94, 0x3e9b6dac, v62
	v_ldexp_f32 v95, v92, 1
	v_ldexp_f32 v106, v93, 1
	v_mul_f32_e32 v92, v84, v36
	v_mul_f32_e32 v93, v85, v37
	v_ldexp_f32 v91, v88, 1
	v_mul_f32_e32 v87, v88, v94
	v_fmaak_f32 v37, v94, v96, 0x3f2aaada
	v_fma_f32 v88, v84, s41, -v92
	v_mul_f32_e32 v96, v86, v36
	v_mul_f32_e32 v97, v87, v37
	v_fmac_f32_e32 v88, 0xb102e308, v84
	v_fma_f32 v90, v86, s41, -v96
	v_add_f32_e32 v98, v92, v88
	v_add_f32_e32 v99, v93, v89
	v_fmac_f32_e32 v90, 0xb102e308, v86
	v_sub_f32_e32 v37, v99, v89
	v_add_f32_e32 v102, v96, v90
	v_add_f32_e32 v103, v97, v91
	v_sub_f32_e32 v37, v93, v37
	v_mov_b32_e32 v94, v92
	v_sub_f32_e32 v85, v103, v91
	v_add_f32_e32 v95, v95, v37
	v_add_f32_e64 v86, v98, -v92
	v_add_f32_e64 v87, v99, -v93
	v_sub_f32_e32 v37, v97, v85
	v_add_f32_e32 v108, v98, v94
	v_add_f32_e32 v109, v99, v95
	v_mov_b32_e32 v84, v96
	v_mov_b32_e32 v89, v98
	v_add_f32_e32 v85, v106, v37
	v_mov_b32_e32 v87, v109
	v_add_f32_e64 v104, v102, -v96
	v_add_f32_e64 v105, v103, -v97
	v_add_f32_e32 v110, v102, v84
	v_add_f32_e32 v111, v103, v85
	v_mov_b32_e32 v106, v85
	v_add_f32_e64 v84, v88, -v86
	v_add_f32_e64 v85, v89, -v87
	v_add_f32_e32 v86, v88, v86
	v_add_f32_e32 v87, v89, v87
	v_mov_b32_e32 v92, v99
	v_mov_b32_e32 v101, v98
	v_mov_b32_e32 v91, v102
	v_mov_b32_e32 v105, v111
	v_add_f32_e64 v98, v87, -v98
	v_add_f32_e64 v99, v86, -v99
	v_mov_b32_e32 v100, v95
	v_mov_b32_e32 v94, v109
	v_mov_b32_e32 v95, v87
	v_add_f32_e64 v112, v90, -v104
	v_add_f32_e64 v113, v91, -v105
	v_add_f32_e32 v90, v90, v104
	v_add_f32_e32 v91, v91, v105
	v_mov_b32_e32 v93, v98
	v_add_f32_e64 v104, v108, -v98
	v_add_f32_e64 v105, v109, -v98
	v_add_f32_e64 v98, v91, -v102
	v_add_f32_e64 v99, v90, -v103
	v_add_f32_e64 v92, v94, -v92
	v_add_f32_e64 v93, v95, -v93
	v_mov_b32_e32 v96, v103
	v_mov_b32_e32 v88, v111
	v_mov_b32_e32 v89, v91
	v_mov_b32_e32 v104, v84
	v_mov_b32_e32 v97, v98
	v_add_f32_e64 v92, v100, -v92
	v_add_f32_e64 v93, v101, -v93
	v_mov_b32_e32 v107, v102
	v_add_f32_e64 v94, v110, -v98
	v_add_f32_e64 v95, v111, -v98
	v_add_f32_e64 v88, v88, -v96
	v_add_f32_e64 v89, v89, -v97
	v_add_f32_e32 v96, v104, v92
	v_add_f32_e32 v97, v105, v93
	v_mov_b32_e32 v94, v112
	v_add_f32_e64 v88, v106, -v88
	v_add_f32_e64 v89, v107, -v89
	v_add_f32_e32 v98, v96, v97
	v_add_f32_e32 v99, v97, v96
	v_mov_b32_e32 v85, v87
	v_add_f32_e32 v94, v94, v88
	v_add_f32_e32 v95, v95, v89
	v_pk_add_f32 v[86:87], v[86:87], v[98:99] op_sel:[1,0] op_sel_hi:[0,1]
	v_mov_b32_e32 v93, v98
	v_add_f32_e32 v98, v94, v95
	v_add_f32_e32 v99, v95, v94
	v_mov_b32_e32 v97, v86
	v_mov_b32_e32 v113, v91
	v_pk_add_f32 v[90:91], v[90:91], v[98:99] op_sel:[1,0] op_sel_hi:[0,1]
	v_mov_b32_e32 v89, v98
	v_add_f32_e64 v98, v96, -v84
	v_add_f32_e64 v99, v97, -v85
	v_mov_b32_e32 v95, v90
	v_sub_f32_e32 v37, v96, v98
	v_add_f32_e64 v92, v92, -v98
	v_add_f32_e64 v93, v93, -v99
	v_add_f32_e64 v96, v94, -v112
	v_add_f32_e64 v97, v95, -v113
	v_sub_f32_e32 v37, v84, v37
	v_sub_f32_e32 v87, v94, v96
	v_add_f32_e32 v37, v92, v37
	v_add_f32_e64 v84, v88, -v96
	v_add_f32_e64 v85, v89, -v97
	v_sub_f32_e32 v87, v112, v87
	v_add_f32_e32 v37, v37, v93
	v_add_f32_e32 v84, v84, v87
	v_add_f32_e32 v37, v86, v37
	v_cmp_neq_f32_e32 vcc, s35, v71
	v_add_f32_e32 v84, v84, v85
	v_cmp_lt_f32_e64 s[0:1], |v71|, s42
	v_cndmask_b32_e32 v37, v1, v37, vcc
	v_add_f32_e32 v84, v90, v84
	v_cmp_neq_f32_e32 vcc, s35, v122
	v_cndmask_b32_e64 v37, v37, v71, s[0:1]
	v_mul_f32_e32 v37, 0xbfb8aa3b, v37
	v_cndmask_b32_e32 v71, v1, v84, vcc
	v_cmp_lt_f32_e64 vcc, |v122|, s42
	v_mul_f32_e32 v84, v37, v115
	v_exp_f32_e32 v84, v84
	v_cndmask_b32_e32 v71, v71, v122, vcc
	v_mul_f32_e32 v71, 0xbfb8aa3b, v71
	v_mul_f32_e32 v85, v37, v116
	v_mul_f32_e32 v87, v37, v118
	v_mul_f32_e32 v37, v37, v120
	v_mul_f32_e32 v89, v71, v114
	v_exp_f32_e32 v86, v85
	v_mul_f32_e32 v85, v71, v117
	v_exp_f32_e32 v88, v87
	v_mul_f32_e32 v87, v71, v119
	v_exp_f32_e32 v90, v37
	v_mul_f32_e32 v37, v71, v121
	v_exp_f32_e32 v92, v89
	v_exp_f32_e32 v94, v85
	v_exp_f32_e32 v96, v87
	v_exp_f32_e32 v98, v37
	v_mul_f32_e32 v102, v84, v56
	v_mul_f32_e32 v103, v84, v57
	v_mul_f32_e32 v100, v84, v54
	v_mul_f32_e32 v101, v84, v55
	v_mul_f32_e32 v104, v84, v58
	v_mul_f32_e32 v105, v84, v59
	v_mul_f32_e32 v85, v84, v61
	v_mul_f32_e32 v84, v84, v60
	v_bfe_u32 v93, v103, 16, 1
	v_mul_f32_e32 v106, v86, v46
	v_mul_f32_e32 v107, v86, v47
	v_mul_f32_e32 v108, v86, v48
	v_mul_f32_e32 v109, v86, v49
	v_mul_f32_e32 v110, v86, v50
	v_mul_f32_e32 v111, v86, v51
	v_mul_f32_e32 v87, v86, v53
	v_mul_f32_e32 v86, v86, v52
	v_mul_f32_e32 v112, v88, v38
	v_mul_f32_e32 v113, v88, v39
	v_mul_f32_e32 v114, v88, v40
	v_mul_f32_e32 v115, v88, v41
	v_mul_f32_e32 v116, v88, v42
	v_mul_f32_e32 v117, v88, v43
	v_mul_f32_e32 v89, v88, v45
	v_mul_f32_e32 v88, v88, v44
	v_mul_f32_e32 v118, v90, v26
	v_mul_f32_e32 v119, v90, v27
	v_mul_f32_e32 v120, v90, v28
	v_mul_f32_e32 v121, v90, v29
	v_mul_f32_e32 v122, v90, v30
	v_mul_f32_e32 v123, v90, v31
	v_mul_f32_e32 v91, v90, v33
	v_mul_f32_e32 v90, v90, v32
	v_bfe_u32 v37, v85, 16, 1
	v_bfe_u32 v71, v84, 16, 1
	v_bfe_u32 v95, v102, 16, 1
	v_bfe_u32 v97, v100, 16, 1
	v_bfe_u32 v99, v101, 16, 1
	v_bfe_u32 v124, v104, 16, 1
	v_bfe_u32 v125, v105, 16, 1
	v_mul_f32_e32 v54, v92, v54
; __device__ __forceinline__ unsigned f2bf(float f) { unsigned u = __builtin_bit_cast(unsigned, f); return (u + 0x7fffu + ((u >> 16) & 1u)) >> 16; }
; __device__ __forceinline__ unsigned pk2(float lo, float hi) { return f2bf(lo) | (f2bf(hi) << 16); }
; __device__ __forceinline__ bf16x8 scale8(bf16x8 v, float s) {
;     v4u w = *reinterpret_cast<v4u*>(&v), o;
; #pragma unroll
;     for (int i = 0; i < 4; ++i) { const float lo = __builtin_bit_cast(float, w[i] << 16) * s, hi = __builtin_bit_cast(float, w[i] & 0xffff0000u) * s; o[i] = pk2(lo, hi); }
;     return *reinterpret_cast<bf16x8*>(&o);
; __device__ __forceinline__ void state_unit(const bf16* __restrict__ Kc, const bf16* __restrict__ Vc, float* __restrict__ Sf, float* __restrict__ Sb, float lgf2, float lgb2, char* lds) {
;     ...
;         *(bf16x8*)(lds + t * 32768 + vst0) = a0; *(bf16x8*)(lds + t * 32768 + vst1) = a1;
;         *(bf16x8*)(lds + t * 32768 + 16384 + kst) = scale8(k0, wf); *(bf16x8*)(lds + t * 32768 + 24576 + kst) = scale8(k0, wb);
	v_mul_f32_e32 v55, v92, v55
	v_mul_f32_e32 v58, v92, v58
	v_mul_f32_e32 v59, v92, v59
	v_mul_f32_e32 v56, v92, v56
	v_mul_f32_e32 v57, v92, v57
	v_mul_f32_e32 v60, v92, v60
	v_mul_f32_e32 v61, v92, v61
	v_bfe_u32 v92, v87, 16, 1
	v_bfe_u32 v126, v86, 16, 1
	v_bfe_u32 v127, v109, 16, 1
	v_bfe_u32 v128, v108, 16, 1
	v_bfe_u32 v129, v106, 16, 1
	v_bfe_u32 v130, v107, 16, 1
	v_bfe_u32 v131, v110, 16, 1
	v_bfe_u32 v132, v111, 16, 1
	v_mul_f32_e32 v46, v94, v46
	v_mul_f32_e32 v47, v94, v47
	v_mul_f32_e32 v48, v94, v48
	v_mul_f32_e32 v49, v94, v49
	v_mul_f32_e32 v50, v94, v50
	v_mul_f32_e32 v51, v94, v51
	v_mul_f32_e32 v52, v94, v52
	v_mul_f32_e32 v53, v94, v53
	v_bfe_u32 v94, v89, 16, 1
	v_bfe_u32 v135, v114, 16, 1
	v_bfe_u32 v136, v112, 16, 1
	v_bfe_u32 v137, v113, 16, 1
	v_bfe_u32 v138, v116, 16, 1
	v_bfe_u32 v139, v117, 16, 1
	v_mul_f32_e32 v38, v96, v38
	v_mul_f32_e32 v39, v96, v39
	v_mul_f32_e32 v40, v96, v40
	v_mul_f32_e32 v41, v96, v41
	v_mul_f32_e32 v42, v96, v42
	v_mul_f32_e32 v43, v96, v43
	v_mul_f32_e32 v44, v96, v44
	v_mul_f32_e32 v45, v96, v45
	v_bfe_u32 v96, v91, 16, 1
	v_bfe_u32 v140, v90, 16, 1
	v_bfe_u32 v141, v121, 16, 1
	v_bfe_u32 v142, v120, 16, 1
	v_bfe_u32 v143, v118, 16, 1
	v_bfe_u32 v144, v119, 16, 1
	v_bfe_u32 v145, v122, 16, 1
	v_bfe_u32 v146, v123, 16, 1
	v_mul_f32_e32 v26, v98, v26
	v_mul_f32_e32 v27, v98, v27
	v_mul_f32_e32 v28, v98, v28
	v_mul_f32_e32 v29, v98, v29
	v_mul_f32_e32 v30, v98, v30
	v_mul_f32_e32 v31, v98, v31
	v_mul_f32_e32 v32, v98, v32
	v_mul_f32_e32 v33, v98, v33
	v_add3_u32 v93, v103, v93, s46
	v_add3_u32 v71, v84, v71, s46
	v_add3_u32 v37, v85, v37, s46
	v_add3_u32 v84, v105, v125, s46
	v_add3_u32 v85, v104, v124, s46
	v_add3_u32 v98, v101, v99, s46
	v_add3_u32 v97, v100, v97, s46
	v_bfe_u32 v103, v54, 16, 1
	v_bfe_u32 v104, v55, 16, 1
	v_bfe_u32 v105, v58, 16, 1
	v_bfe_u32 v124, v59, 16, 1
	v_bfe_u32 v133, v88, 16, 1
	v_bfe_u32 v134, v115, 16, 1
	v_add3_u32 v95, v102, v95, s46
	v_bfe_u32 v99, v61, 16, 1
	v_bfe_u32 v100, v60, 16, 1
	v_bfe_u32 v101, v57, 16, 1
	v_bfe_u32 v102, v56, 16, 1
	v_add3_u32 v108, v108, v128, s46
	v_add3_u32 v109, v109, v127, s46
	v_add3_u32 v86, v86, v126, s46
	v_add3_u32 v87, v87, v92, s46
	v_add3_u32 v92, v111, v132, s46
	v_add3_u32 v110, v110, v131, s46
	v_add3_u32 v107, v107, v130, s46
	v_add3_u32 v106, v106, v129, s46
	v_bfe_u32 v111, v53, 16, 1
	v_bfe_u32 v125, v52, 16, 1
	v_bfe_u32 v126, v49, 16, 1
	v_bfe_u32 v127, v48, 16, 1
	v_bfe_u32 v128, v46, 16, 1
	v_bfe_u32 v129, v47, 16, 1
	v_bfe_u32 v130, v50, 16, 1
	v_bfe_u32 v131, v51, 16, 1
	v_add3_u32 v114, v114, v135, s46
	v_add3_u32 v89, v89, v94, s46
	v_add3_u32 v94, v117, v139, s46
	v_add3_u32 v116, v116, v138, s46
	v_add3_u32 v113, v113, v137, s46
	v_add3_u32 v112, v112, v136, s46
	v_bfe_u32 v117, v45, 16, 1
	v_bfe_u32 v132, v44, 16, 1
	v_bfe_u32 v135, v38, 16, 1
	v_bfe_u32 v136, v39, 16, 1
	v_bfe_u32 v137, v42, 16, 1
	v_bfe_u32 v138, v43, 16, 1
	v_add3_u32 v120, v120, v142, s46
	v_add3_u32 v121, v121, v141, s46
	v_add3_u32 v90, v90, v140, s46
	v_add3_u32 v91, v91, v96, s46
	v_add3_u32 v96, v123, v146, s46
	v_add3_u32 v122, v122, v145, s46
	v_add3_u32 v119, v119, v144, s46
	v_add3_u32 v118, v118, v143, s46
	v_bfe_u32 v123, v33, 16, 1
	v_bfe_u32 v140, v29, 16, 1
	v_bfe_u32 v141, v28, 16, 1
	v_bfe_u32 v142, v26, 16, 1
	v_bfe_u32 v143, v27, 16, 1
	v_bfe_u32 v144, v30, 16, 1
	v_bfe_u32 v145, v31, 16, 1
	v_lshrrev_b32_e32 v97, 16, v97
	v_lshrrev_b32_e32 v98, 16, v98
	v_lshrrev_b32_e32 v85, 16, v85
	v_lshrrev_b32_e32 v84, 16, v84
	v_add3_u32 v59, v59, v124, s46
	v_add3_u32 v58, v58, v105, s46
	v_add3_u32 v55, v55, v104, s46
	v_add3_u32 v54, v54, v103, s46
	v_add3_u32 v115, v115, v134, s46
	v_add3_u32 v88, v88, v133, s46
	v_bfe_u32 v133, v41, 16, 1
	v_bfe_u32 v134, v40, 16, 1
	v_bfe_u32 v139, v32, 16, 1
	v_add3_u32 v56, v56, v102, s46
	v_add3_u32 v57, v57, v101, s46
	v_add3_u32 v60, v60, v100, s46
	v_add3_u32 v61, v61, v99, s46
	v_lshrrev_b32_e32 v100, 16, v107
	v_lshrrev_b32_e32 v101, 16, v110
	v_lshrrev_b32_e32 v92, 16, v92
	v_add3_u32 v102, v48, v127, s46
	v_add3_u32 v103, v49, v126, s46
	v_add3_u32 v48, v52, v125, s46
	v_add3_u32 v49, v53, v111, s46
	v_add3_u32 v51, v51, v131, s46
	v_add3_u32 v50, v50, v130, s46
	v_add3_u32 v47, v47, v129, s46
	v_add3_u32 v46, v46, v128, s46
	v_lshrrev_b32_e32 v52, 16, v112
	v_lshrrev_b32_e32 v53, 16, v113
	v_lshrrev_b32_e32 v104, 16, v116
	v_add3_u32 v107, v44, v132, s46
	v_add3_u32 v110, v45, v117, s46
	v_add3_u32 v43, v43, v138, s46
	v_add3_u32 v42, v42, v137, s46
	v_add3_u32 v44, v39, v136, s46
	v_add3_u32 v45, v38, v135, s46
	v_lshrrev_b32_e32 v112, 16, v119
	v_lshrrev_b32_e32 v113, 16, v122
	v_add3_u32 v116, v28, v141, s46
	v_add3_u32 v117, v29, v140, s46
	v_add3_u32 v119, v33, v123, s46
	v_add3_u32 v122, v31, v145, s46
	v_add3_u32 v123, v30, v144, s46
	v_add3_u32 v124, v27, v143, s46
	v_add3_u32 v125, v26, v142, s46
	v_and_or_b32 v29, v37, s43, v84
	v_and_or_b32 v28, v71, s43, v85
	v_and_or_b32 v27, v93, s43, v98
	v_and_or_b32 v26, v95, s43, v97
	v_lshrrev_b32_e32 v37, 16, v54
	v_lshrrev_b32_e32 v54, 16, v55
	v_lshrrev_b32_e32 v55, 16, v58
	v_lshrrev_b32_e32 v58, 16, v59
	v_lshrrev_b32_e32 v99, 16, v106
	v_lshrrev_b32_e32 v94, 16, v94
	v_add3_u32 v105, v40, v134, s46
	v_add3_u32 v106, v41, v133, s46
	v_lshrrev_b32_e32 v111, 16, v118
	v_lshrrev_b32_e32 v96, 16, v96
	v_add3_u32 v118, v32, v139, s46
	v_and_or_b32 v33, v87, s43, v92
	v_and_or_b32 v32, v86, s43, v101
	v_lshrrev_b32_e32 v46, 16, v46
	v_lshrrev_b32_e32 v47, 16, v47
	v_lshrrev_b32_e32 v50, 16, v50
	v_lshrrev_b32_e32 v51, 16, v51
	v_and_or_b32 v39, v115, s43, v53
	v_and_or_b32 v38, v114, s43, v52
	v_lshrrev_b32_e32 v59, 16, v45
	v_lshrrev_b32_e32 v71, 16, v44
	v_lshrrev_b32_e32 v52, 16, v42
	v_lshrrev_b32_e32 v53, 16, v43
	v_lshrrev_b32_e32 v84, 16, v125
	v_lshrrev_b32_e32 v85, 16, v124
	v_lshrrev_b32_e32 v86, 16, v123
	v_lshrrev_b32_e32 v87, 16, v122
	ds_write_b128 v73, v[26:29] offset:16384
	v_and_or_b32 v29, v61, s43, v58
	v_and_or_b32 v28, v60, s43, v55
	v_and_or_b32 v27, v57, s43, v54
	v_and_or_b32 v26, v56, s43, v37
	v_and_or_b32 v31, v109, s43, v100
	v_and_or_b32 v30, v108, s43, v99
	v_and_or_b32 v41, v89, s43, v94
	v_and_or_b32 v40, v88, s43, v104
	v_and_or_b32 v45, v91, s43, v96
	v_and_or_b32 v44, v90, s43, v113
	v_and_or_b32 v43, v121, s43, v112
	v_and_or_b32 v42, v120, s43, v111
	v_and_or_b32 v49, v49, s43, v51
	v_and_or_b32 v48, v48, s43, v50
	v_and_or_b32 v47, v103, s43, v47
	v_and_or_b32 v46, v102, s43, v46
	v_and_or_b32 v53, v110, s43, v53
	v_and_or_b32 v52, v107, s43, v52
	v_and_or_b32 v51, v106, s43, v71
	v_and_or_b32 v50, v105, s43, v59
	v_and_or_b32 v57, v119, s43, v87
	v_and_or_b32 v56, v118, s43, v86
	v_and_or_b32 v55, v117, s43, v85
	v_and_or_b32 v54, v116, s43, v84
	ds_write_b128 v73, v[26:29] offset:24576
	s_waitcnt vmcnt(3)
; #define SBAR() __builtin_amdgcn_sched_barrier(0)
; __device__ __forceinline__ int v_rd_base(int lane) { return ((lane & 3) << 3) | (((lane >> 2) & 3) << 6) | (((lane >> 4) & 1) << 5) | (((lane >> 5) & 1) << 8); }
; #define SBAR() __builtin_amdgcn_sched_barrier(0)
; __device__ __forceinline__ void state_unit(const bf16* __restrict__ Kc, const bf16* __restrict__ Vc, float* __restrict__ Sf, float* __restrict__ Sb, float lgf2, float lgb2, char* lds) {
;     ...
;         *(bf16x8*)(lds + t * 32768 + vst0) = a0; *(bf16x8*)(lds + t * 32768 + vst1) = a1;
;         *(bf16x8*)(lds + t * 32768 + 16384 + kst) = scale8(k0, wf); *(bf16x8*)(lds + t * 32768 + 24576 + kst) = scale8(k0, wb);
;     }
;     __syncthreads();
;     const int dblk = wid >> 2, eblk = wid & 3;
;     const int vb = (int)(uintptr_t)lds + v_rd_base(lane);
;     f32x16 accf = {}, accb = {};
; #pragma unroll
;     for (int t = 0; t < 4; ++t) {
; #pragma unroll
;         for (int ks = 0; ks < 4; ++ks) {
;             s16x4 vl, vh, fl, fh, bl, bh;
;             const int vo = vb + t * 32768 + eblk * 512 + ks * 4096, ko = vb + t * 32768 + 16384 + dblk * 512 + ks * 2048;
;             asm volatile("ds_read_b64_tr_b16 %0, %1" : "=&v"(vl) : "v"(vo) : "memory");
;             asm volatile("ds_read_b64_tr_b16 %0, %1 offset:2048" : "=&v"(vh) : "v"(vo) : "memory");
;             asm volatile("ds_read_b64_tr_b16 %0, %1" : "=&v"(fl) : "v"(ko) : "memory");
;             asm volatile("ds_read_b64_tr_b16 %0, %1 offset:1024" : "=&v"(fh) : "v"(ko) : "memory");
;             asm volatile("ds_read_b64_tr_b16 %0, %1 offset:8192" : "=&v"(bl) : "v"(ko) : "memory");
;             asm volatile("ds_read_b64_tr_b16 %0, %1 offset:9216" : "=&v"(bh) : "v"(ko) : "memory");
;             asm volatile("s_waitcnt lgkmcnt(0)" ::: "memory"); SBAR();
;             const bf16x8 vf = (bf16x8){vl[0], vl[1], vl[2], vl[3], vh[0], vh[1], vh[2], vh[3]};
;             const bf16x8 kf = (bf16x8){fl[0], fl[1], fl[2], fl[3], fh[0], fh[1], fh[2], fh[3]};
;             const bf16x8 kb = (bf16x8){bl[0], bl[1], bl[2], bl[3], bh[0], bh[1], bh[2], bh[3]};
;             accf = __builtin_amdgcn_mfma_f32_32x32x16_bf16(kf, vf, accf, 0, 0, 0);
;             accb = __builtin_amdgcn_mfma_f32_32x32x16_bf16(kb, vf, accb, 0, 0, 0);
;         }
	ds_write_b128 v75, v[22:25] offset:32768
	ds_write_b128 v83, v[6:9] offset:32768
	ds_write_b128 v73, v[30:33] offset:49152
	ds_write_b128 v73, v[46:49] offset:57344
	s_waitcnt vmcnt(2)
	ds_write_b128 v76, v[14:17]
	s_waitcnt vmcnt(1)
	ds_write_b128 v80, v[18:21]
	ds_write_b128 v81, v[38:41]
	ds_write_b128 v82, v[50:53]
	s_waitcnt vmcnt(0)
	ds_write_b128 v74, v[10:13]
	ds_write_b128 v77, v[2:5]
	ds_write_b128 v78, v[42:45]
	ds_write_b128 v79, v[54:57]
	s_waitcnt lgkmcnt(0)
	s_barrier
	ds_read_b64_tr_b16 v[18:19], v72
	ds_read_b64_tr_b16 v[20:21], v72 offset:2048
	ds_read_b64_tr_b16 v[2:3], v34
	ds_read_b64_tr_b16 v[4:5], v34 offset:1024
	ds_read_b64_tr_b16 v[22:23], v34 offset:8192
	ds_read_b64_tr_b16 v[24:25], v34 offset:9216
	s_waitcnt lgkmcnt(0)
	v_add_u32_e32 v26, 0x1000, v72
	ds_read_b64_tr_b16 v[38:39], v26
	ds_read_b64_tr_b16 v[40:41], v26 offset:2048
	v_add_u32_e32 v27, 0x800, v34
	ds_read_b64_tr_b16 v[42:43], v27
	ds_read_b64_tr_b16 v[44:45], v27 offset:1024
	ds_read_b64_tr_b16 v[46:47], v27 offset:8192
	ds_read_b64_tr_b16 v[48:49], v27 offset:9216
	s_waitcnt lgkmcnt(0)
	v_mfma_f32_32x32x16_bf16 v[2:17], v[2:5], v[18:21], 0
	v_mfma_f32_32x32x16_bf16 v[18:33], v[22:25], v[18:21], 0
	v_add_u32_e32 v37, 0x2000, v72
	v_mfma_f32_32x32x16_bf16 v[2:17], v[42:45], v[38:41], v[2:17]
	ds_read_b64_tr_b16 v[42:43], v37
	ds_read_b64_tr_b16 v[44:45], v37 offset:2048
	v_add_u32_e32 v58, 0x1000, v34
	ds_read_b64_tr_b16 v[50:51], v58
	ds_read_b64_tr_b16 v[52:53], v58 offset:1024
	ds_read_b64_tr_b16 v[54:55], v58 offset:8192
	ds_read_b64_tr_b16 v[56:57], v58 offset:9216
	s_waitcnt lgkmcnt(0)
	v_mfma_f32_32x32x16_bf16 v[18:33], v[46:49], v[38:41], v[18:33]
	v_add_u32_e32 v37, 0x3000, v72
	ds_read_b64_tr_b16 v[38:39], v37
	ds_read_b64_tr_b16 v[40:41], v37 offset:2048
	v_add_u32_e32 v34, 0x1800, v34
	ds_read_b64_tr_b16 v[46:47], v34
	ds_read_b64_tr_b16 v[48:49], v34 offset:1024
	v_mfma_f32_32x32x16_bf16 v[2:17], v[50:53], v[42:45], v[2:17]
	ds_read_b64_tr_b16 v[50:51], v34 offset:8192
	ds_read_b64_tr_b16 v[52:53], v34 offset:9216
	s_waitcnt lgkmcnt(0)
	v_mfma_f32_32x32x16_bf16 v[18:33], v[54:57], v[42:45], v[18:33]
	v_add_u32_e32 v34, 0x8000, v70
	v_add_u32_e32 v37, v34, v69
	ds_read_b64_tr_b16 v[42:43], v37
	ds_read_b64_tr_b16 v[44:45], v37 offset:2048
	v_mfma_f32_32x32x16_bf16 v[2:17], v[46:49], v[38:41], v[2:17]
	v_add_u32_e32 v34, v34, v68
	ds_read_b64_tr_b16 v[46:47], v34
	ds_read_b64_tr_b16 v[48:49], v34 offset:1024
	ds_read_b64_tr_b16 v[54:55], v34 offset:8192
	ds_read_b64_tr_b16 v[56:57], v34 offset:9216
	s_waitcnt lgkmcnt(0)
	v_mfma_f32_32x32x16_bf16 v[18:33], v[50:53], v[38:41], v[18:33]
	v_add_u32_e32 v50, 0x1000, v37
	ds_read_b64_tr_b16 v[38:39], v50
	ds_read_b64_tr_b16 v[40:41], v50 offset:2048
	v_mfma_f32_32x32x16_bf16 v[2:17], v[46:49], v[42:45], v[2:17]
	v_add_u32_e32 v58, 0x800, v34
	ds_read_b64_tr_b16 v[46:47], v58
	ds_read_b64_tr_b16 v[48:49], v58 offset:1024
	ds_read_b64_tr_b16 v[50:51], v58 offset:8192
	ds_read_b64_tr_b16 v[52:53], v58 offset:9216
	s_waitcnt lgkmcnt(0)
	v_mfma_f32_32x32x16_bf16 v[18:33], v[54:57], v[42:45], v[18:33]
	v_add_u32_e32 v54, 0x2000, v37
	ds_read_b64_tr_b16 v[42:43], v54
	ds_read_b64_tr_b16 v[44:45], v54 offset:2048
	v_mfma_f32_32x32x16_bf16 v[2:17], v[46:49], v[38:41], v[2:17]
	v_add_u32_e32 v58, 0x1000, v34
	ds_read_b64_tr_b16 v[46:47], v58
	ds_read_b64_tr_b16 v[48:49], v58 offset:1024
	ds_read_b64_tr_b16 v[54:55], v58 offset:8192
	ds_read_b64_tr_b16 v[56:57], v58 offset:9216
	s_waitcnt lgkmcnt(0)
	v_mfma_f32_32x32x16_bf16 v[18:33], v[50:53], v[38:41], v[18:33]
	v_add_u32_e32 v37, 0x3000, v37
	ds_read_b64_tr_b16 v[38:39], v37
	ds_read_b64_tr_b16 v[40:41], v37 offset:2048
	v_mfma_f32_32x32x16_bf16 v[2:17], v[46:49], v[42:45], v[2:17]
	v_add_u32_e32 v34, 0x1800, v34
	ds_read_b64_tr_b16 v[46:47], v34
	ds_read_b64_tr_b16 v[48:49], v34 offset:1024
	ds_read_b64_tr_b16 v[50:51], v34 offset:8192
	ds_read_b64_tr_b16 v[52:53], v34 offset:9216
	s_waitcnt lgkmcnt(0)
	v_mfma_f32_32x32x16_bf16 v[18:33], v[54:57], v[42:45], v[18:33]
	v_add_u32_e32 v34, 0x10000, v70
	v_add_u32_e32 v37, v34, v69
	ds_read_b64_tr_b16 v[42:43], v37
	ds_read_b64_tr_b16 v[44:45], v37 offset:2048
	v_mfma_f32_32x32x16_bf16 v[2:17], v[46:49], v[38:41], v[2:17]
	v_add_u32_e32 v34, v34, v68
	ds_read_b64_tr_b16 v[46:47], v34
	ds_read_b64_tr_b16 v[48:49], v34 offset:1024
	ds_read_b64_tr_b16 v[54:55], v34 offset:8192
	ds_read_b64_tr_b16 v[56:57], v34 offset:9216
	s_waitcnt lgkmcnt(0)
	v_mfma_f32_32x32x16_bf16 v[18:33], v[50:53], v[38:41], v[18:33]
	v_add_u32_e32 v50, 0x1000, v37
	ds_read_b64_tr_b16 v[38:39], v50
	ds_read_b64_tr_b16 v[40:41], v50 offset:2048
	v_mfma_f32_32x32x16_bf16 v[2:17], v[46:49], v[42:45], v[2:17]
	v_add_u32_e32 v58, 0x800, v34
	ds_read_b64_tr_b16 v[46:47], v58
	ds_read_b64_tr_b16 v[48:49], v58 offset:1024
	ds_read_b64_tr_b16 v[50:51], v58 offset:8192
	ds_read_b64_tr_b16 v[52:53], v58 offset:9216
	s_waitcnt lgkmcnt(0)
	v_mfma_f32_32x32x16_bf16 v[18:33], v[54:57], v[42:45], v[18:33]
	v_add_u32_e32 v54, 0x2000, v37
	ds_read_b64_tr_b16 v[42:43], v54
	ds_read_b64_tr_b16 v[44:45], v54 offset:2048
	v_mfma_f32_32x32x16_bf16 v[2:17], v[46:49], v[38:41], v[2:17]
	v_add_u32_e32 v58, 0x1000, v34
	ds_read_b64_tr_b16 v[46:47], v58
	ds_read_b64_tr_b16 v[48:49], v58 offset:1024
	ds_read_b64_tr_b16 v[54:55], v58 offset:8192
	ds_read_b64_tr_b16 v[56:57], v58 offset:9216
	s_waitcnt lgkmcnt(0)
	v_mfma_f32_32x32x16_bf16 v[18:33], v[50:53], v[38:41], v[18:33]
	v_add_u32_e32 v37, 0x3000, v37
	ds_read_b64_tr_b16 v[38:39], v37
	ds_read_b64_tr_b16 v[40:41], v37 offset:2048
	v_mfma_f32_32x32x16_bf16 v[2:17], v[46:49], v[42:45], v[2:17]
	v_add_u32_e32 v34, 0x1800, v34
	ds_read_b64_tr_b16 v[46:47], v34
	ds_read_b64_tr_b16 v[48:49], v34 offset:1024
	ds_read_b64_tr_b16 v[50:51], v34 offset:8192
	ds_read_b64_tr_b16 v[52:53], v34 offset:9216
	s_waitcnt lgkmcnt(0)
; #define SBAR() __builtin_amdgcn_sched_barrier(0)
; __device__ __forceinline__ int crow(int r, int hi) { return (r & 3) + 8 * (r >> 2) + 4 * hi; }
; #define SBAR() __builtin_amdgcn_sched_barrier(0)
; __device__ __forceinline__ void state_unit(const bf16* __restrict__ Kc, const bf16* __restrict__ Vc, float* __restrict__ Sf, float* __restrict__ Sb, float lgf2, float lgb2, char* lds) {
;     ...
;     for (int t = 0; t < 4; ++t) {
; #pragma unroll
;         for (int ks = 0; ks < 4; ++ks) {
;             s16x4 vl, vh, fl, fh, bl, bh;
;             const int vo = vb + t * 32768 + eblk * 512 + ks * 4096, ko = vb + t * 32768 + 16384 + dblk * 512 + ks * 2048;
;             asm volatile("ds_read_b64_tr_b16 %0, %1" : "=&v"(vl) : "v"(vo) : "memory");
;             asm volatile("ds_read_b64_tr_b16 %0, %1 offset:2048" : "=&v"(vh) : "v"(vo) : "memory");
;             asm volatile("ds_read_b64_tr_b16 %0, %1" : "=&v"(fl) : "v"(ko) : "memory");
;             asm volatile("ds_read_b64_tr_b16 %0, %1 offset:1024" : "=&v"(fh) : "v"(ko) : "memory");
;             asm volatile("ds_read_b64_tr_b16 %0, %1 offset:8192" : "=&v"(bl) : "v"(ko) : "memory");
;             asm volatile("ds_read_b64_tr_b16 %0, %1 offset:9216" : "=&v"(bh) : "v"(ko) : "memory");
;             asm volatile("s_waitcnt lgkmcnt(0)" ::: "memory"); SBAR();
;             const bf16x8 vf = (bf16x8){vl[0], vl[1], vl[2], vl[3], vh[0], vh[1], vh[2], vh[3]};
;             const bf16x8 kf = (bf16x8){fl[0], fl[1], fl[2], fl[3], fh[0], fh[1], fh[2], fh[3]};
;             const bf16x8 kb = (bf16x8){bl[0], bl[1], bl[2], bl[3], bh[0], bh[1], bh[2], bh[3]};
;             accf = __builtin_amdgcn_mfma_f32_32x32x16_bf16(kf, vf, accf, 0, 0, 0);
;             accb = __builtin_amdgcn_mfma_f32_32x32x16_bf16(kb, vf, accb, 0, 0, 0);
;         }
;     }
; #pragma unroll
;     for (int r = 0; r < 16; ++r) { const int d = 32 * dblk + crow(r, hi), e = 32 * eblk + r32;
;         Sf[d * 128 + e] = accf[r]; Sb[d * 128 + e] = accb[r]; }
;     __syncthreads();
; __global__ void __launch_bounds__(NTHR, 2) mega(Args args) {
;     ...
;         for (int idx = blockIdx.x; idx < 288; idx += G) {
	v_mfma_f32_32x32x16_bf16 v[18:33], v[54:57], v[42:45], v[18:33]
	v_add_u32_e32 v34, 0x18000, v70
	v_add_u32_e32 v37, v34, v69
	ds_read_b64_tr_b16 v[42:43], v37
	ds_read_b64_tr_b16 v[44:45], v37 offset:2048
	v_mfma_f32_32x32x16_bf16 v[2:17], v[46:49], v[38:41], v[2:17]
	v_add_u32_e32 v34, v34, v68
	ds_read_b64_tr_b16 v[46:47], v34
	ds_read_b64_tr_b16 v[48:49], v34 offset:1024
	ds_read_b64_tr_b16 v[54:55], v34 offset:8192
	ds_read_b64_tr_b16 v[56:57], v34 offset:9216
	s_waitcnt lgkmcnt(0)
	v_mfma_f32_32x32x16_bf16 v[18:33], v[50:53], v[38:41], v[18:33]
	v_add_u32_e32 v50, 0x1000, v37
	ds_read_b64_tr_b16 v[38:39], v50
	ds_read_b64_tr_b16 v[40:41], v50 offset:2048
	v_mfma_f32_32x32x16_bf16 v[2:17], v[46:49], v[42:45], v[2:17]
	v_add_u32_e32 v58, 0x800, v34
	ds_read_b64_tr_b16 v[46:47], v58
	ds_read_b64_tr_b16 v[48:49], v58 offset:1024
	ds_read_b64_tr_b16 v[50:51], v58 offset:8192
	ds_read_b64_tr_b16 v[52:53], v58 offset:9216
	s_waitcnt lgkmcnt(0)
	v_mfma_f32_32x32x16_bf16 v[18:33], v[54:57], v[42:45], v[18:33]
	v_add_u32_e32 v54, 0x2000, v37
	ds_read_b64_tr_b16 v[42:43], v54
	ds_read_b64_tr_b16 v[44:45], v54 offset:2048
	v_mfma_f32_32x32x16_bf16 v[2:17], v[46:49], v[38:41], v[2:17]
	v_add_u32_e32 v58, 0x1000, v34
	ds_read_b64_tr_b16 v[46:47], v58
	ds_read_b64_tr_b16 v[48:49], v58 offset:1024
	ds_read_b64_tr_b16 v[54:55], v58 offset:8192
	ds_read_b64_tr_b16 v[56:57], v58 offset:9216
	s_waitcnt lgkmcnt(0)
	v_mfma_f32_32x32x16_bf16 v[18:33], v[50:53], v[38:41], v[18:33]
	v_add_u32_e32 v37, 0x3000, v37
	ds_read_b64_tr_b16 v[38:39], v37
	ds_read_b64_tr_b16 v[40:41], v37 offset:2048
	v_mfma_f32_32x32x16_bf16 v[2:17], v[46:49], v[42:45], v[2:17]
	v_add_u32_e32 v34, 0x1800, v34
	ds_read_b64_tr_b16 v[46:47], v34
	ds_read_b64_tr_b16 v[48:49], v34 offset:1024
	ds_read_b64_tr_b16 v[50:51], v34 offset:8192
	ds_read_b64_tr_b16 v[52:53], v34 offset:9216
	s_waitcnt lgkmcnt(0)
	v_mfma_f32_32x32x16_bf16 v[18:33], v[54:57], v[42:45], v[18:33]
	v_mfma_f32_32x32x16_bf16 v[2:17], v[46:49], v[38:41], v[2:17]
	v_and_b32_e32 v34, 31, v64
	v_lshl_or_b32 v34, v67, 5, v34
	v_lshlrev_b32_e32 v37, 12, v66
	v_and_b32_e32 v42, 0x200, v65
	v_or3_b32 v42, v34, v37, v42
	v_ashrrev_i32_e32 v43, 31, v42
	v_lshlrev_b64 v[44:45], 2, v[42:43]
	v_mfma_f32_32x32x16_bf16 v[18:33], v[50:53], v[38:41], v[18:33]
	v_or_b32_e32 v38, 0x80, v42
	v_lshl_add_u64 v[46:47], s[4:5], 0, v[44:45]
	v_ashrrev_i32_e32 v39, 31, v38
	s_nop 0
	global_store_dword v[46:47], v2, off
	global_store_dword v[46:47], v3, off offset:512
	v_lshl_add_u64 v[2:3], v[38:39], 2, s[6:7]
	global_store_dword v[46:47], v4, off offset:1024
	s_nop 3
	global_store_dword v[2:3], v19, off
	v_or_b32_e32 v2, 0x100, v42
	v_ashrrev_i32_e32 v3, 31, v2
	v_lshl_add_u64 v[2:3], v[2:3], 2, s[6:7]
	global_store_dword v[2:3], v20, off
	v_or_b32_e32 v2, 0x180, v42
	v_ashrrev_i32_e32 v3, 31, v2
	v_lshl_add_u64 v[2:3], v[2:3], 2, s[6:7]
	global_store_dword v[2:3], v21, off
	v_or_b32_e32 v2, 0x400, v42
	v_ashrrev_i32_e32 v3, 31, v2
	v_lshlrev_b64 v[2:3], 2, v[2:3]
	global_store_dword v[46:47], v5, off offset:1536
	v_lshl_add_u64 v[4:5], s[4:5], 0, v[2:3]
	v_lshl_add_u64 v[2:3], s[6:7], 0, v[2:3]
	global_store_dword v[2:3], v22, off
	v_or_b32_e32 v2, 0x480, v42
	v_ashrrev_i32_e32 v3, 31, v2
	v_lshlrev_b64 v[2:3], 2, v[2:3]
	global_store_dword v[4:5], v6, off
	v_lshl_add_u64 v[4:5], s[4:5], 0, v[2:3]
	v_lshl_add_u64 v[2:3], s[6:7], 0, v[2:3]
	global_store_dword v[2:3], v23, off
	v_or_b32_e32 v2, 0x500, v42
	v_ashrrev_i32_e32 v3, 31, v2
	v_lshlrev_b64 v[2:3], 2, v[2:3]
	global_store_dword v[4:5], v7, off
	v_lshl_add_u64 v[4:5], s[4:5], 0, v[2:3]
	v_lshl_add_u64 v[2:3], s[6:7], 0, v[2:3]
	global_store_dword v[2:3], v24, off
	v_or_b32_e32 v2, 0x580, v42
	v_ashrrev_i32_e32 v3, 31, v2
	v_lshlrev_b64 v[2:3], 2, v[2:3]
	global_store_dword v[4:5], v8, off
	v_lshl_add_u64 v[4:5], s[4:5], 0, v[2:3]
	v_lshl_add_u64 v[2:3], s[6:7], 0, v[2:3]
	global_store_dword v[2:3], v25, off
	v_or_b32_e32 v2, 0x800, v42
	v_ashrrev_i32_e32 v3, 31, v2
	v_lshlrev_b64 v[2:3], 2, v[2:3]
	global_store_dword v[4:5], v9, off
	v_lshl_add_u64 v[4:5], s[4:5], 0, v[2:3]
	v_lshl_add_u64 v[2:3], s[6:7], 0, v[2:3]
	global_store_dword v[2:3], v26, off
	v_or_b32_e32 v2, 0x880, v42
	v_ashrrev_i32_e32 v3, 31, v2
	v_lshlrev_b64 v[2:3], 2, v[2:3]
	global_store_dword v[4:5], v10, off
	v_lshl_add_u64 v[4:5], s[4:5], 0, v[2:3]
	v_lshl_add_u64 v[2:3], s[6:7], 0, v[2:3]
	global_store_dword v[2:3], v27, off
	v_or_b32_e32 v2, 0x900, v42
	v_ashrrev_i32_e32 v3, 31, v2
	v_lshlrev_b64 v[2:3], 2, v[2:3]
	global_store_dword v[4:5], v11, off
	v_lshl_add_u64 v[4:5], s[4:5], 0, v[2:3]
	v_lshl_add_u64 v[2:3], s[6:7], 0, v[2:3]
	global_store_dword v[2:3], v28, off
	v_or_b32_e32 v2, 0x980, v42
	v_ashrrev_i32_e32 v3, 31, v2
	v_lshlrev_b64 v[2:3], 2, v[2:3]
	global_store_dword v[4:5], v12, off
	v_lshl_add_u64 v[4:5], s[4:5], 0, v[2:3]
	v_lshl_add_u64 v[2:3], s[6:7], 0, v[2:3]
	global_store_dword v[2:3], v29, off
	v_or_b32_e32 v2, 0xc00, v42
	v_ashrrev_i32_e32 v3, 31, v2
	v_lshlrev_b64 v[2:3], 2, v[2:3]
	global_store_dword v[4:5], v13, off
	v_lshl_add_u64 v[4:5], s[4:5], 0, v[2:3]
	v_lshl_add_u64 v[2:3], s[6:7], 0, v[2:3]
	global_store_dword v[2:3], v30, off
	v_or_b32_e32 v2, 0xc80, v42
	v_ashrrev_i32_e32 v3, 31, v2
	v_lshlrev_b64 v[2:3], 2, v[2:3]
	global_store_dword v[4:5], v14, off
	v_lshl_add_u64 v[4:5], s[4:5], 0, v[2:3]
	v_lshl_add_u64 v[2:3], s[6:7], 0, v[2:3]
	global_store_dword v[2:3], v31, off
	v_or_b32_e32 v2, 0xd00, v42
	v_ashrrev_i32_e32 v3, 31, v2
	v_lshlrev_b64 v[2:3], 2, v[2:3]
	global_store_dword v[4:5], v15, off
	v_lshl_add_u64 v[4:5], s[4:5], 0, v[2:3]
	v_lshl_add_u64 v[2:3], s[6:7], 0, v[2:3]
	global_store_dword v[2:3], v32, off
	v_or_b32_e32 v2, 0xd80, v42
	v_ashrrev_i32_e32 v3, 31, v2
	v_lshlrev_b64 v[2:3], 2, v[2:3]
	s_add_i32 s59, s59, s18
	s_add_i32 s17, s17, s19
	v_lshl_add_u64 v[44:45], s[6:7], 0, v[44:45]
	global_store_dword v[4:5], v16, off
	v_lshl_add_u64 v[4:5], s[4:5], 0, v[2:3]
	v_lshl_add_u64 v[2:3], s[6:7], 0, v[2:3]
	s_cmpk_gt_i32 s59, 0x11f
	global_store_dword v[44:45], v18, off
	global_store_dword v[4:5], v17, off
	global_store_dword v[2:3], v33, off
	s_barrier
	s_cbranch_scc0 .LBB0_536

;     __device__ __forceinline__ void fused(pg8::f32x4 (&acc)[2][2][4][2], const pg8::Unit& u, int wr, int wc, int fr, int fq, PG8_LAS unsigned char* lds, int wid, int lane) const {
;         const int b = u.pm >> 3;
;         const int col0 = u.pn * 256 + wc * 32 + 8 * fq, kg = 4 * wc + fq;
;         f32x4 bv[2][2];
; #pragma unroll
;         for (int bj = 0; bj < 2; ++bj)
; #pragma unroll
;             for (int n = 0; n < 2; ++n) bv[bj][n] = *(const f32x4*)(biasq + (size_t)b * 2048 + col0 + bj * 128 + 4 * n);
; #pragma unroll
;         for (int ai = 0; ai < 2; ++ai)
; #pragma unroll
;             for (int m = 0; m < 4; ++m) {
;                 const int rl = ai * 128 + wr * 64 + m * 16 + fr; const size_t row = (size_t)u.pm * 256 + rl;
;                 const f32x4 s0 = *(const f32x4*)(ssq + row * 16), s1 = *(const f32x4*)(ssq + row * 16 + 4), s2 = *(const f32x4*)(ssq + row * 16 + 8), s3 = *(const f32x4*)(ssq + row * 16 + 12);
;                 const float tot = ((s0.x + s0.y) + (s0.z + s0.w)) + ((s1.x + s1.y) + (s1.z + s1.w)) + ((s2.x + s2.y) + (s2.z + s2.w)) + ((s3.x + s3.y) + (s3.z + s3.w));
;                 const float rstd = rsqrtf(tot * (1.f / D) + EPS);
.LBB0_807:
	s_barrier
	s_mov_b32 s58, vcc_lo
	v_bfe_u32 v234, v167, 4, 2
	v_and_b32_e32 v235, 15, v100
	s_ashr_i32 s0, s24, 3
	s_lshl_b32 s0, s0, 13
	v_readlane_b32 s16, v240, 12
	v_readlane_b32 s17, v240, 13
	s_add_u32 s36, s16, s0
	s_addc_u32 s37, s17, 0
	s_lshl_b32 s0, s58, 5
	s_lshl_b32 s1, s22, 8
	s_or_b32 s0, s0, s1
	v_lshl_or_b32 v244, v234, 3, s0
	v_lshlrev_b32_e32 v244, 2, v244
	global_load_dwordx4 v[170:173], v244, s[36:37]
	global_load_dwordx4 v[174:177], v244, s[36:37] offset:16
	global_load_dwordx4 v[178:181], v244, s[36:37] offset:512
	global_load_dwordx4 v[182:185], v244, s[36:37] offset:528
	s_lshl_b32 s0, s24, 14
	s_add_u32 s40, s8, s0
	s_addc_u32 s41, s9, 0
	v_lshlrev_b32_e32 v243, 6, v100
	v_lshl_or_b32 v243, v234, 4, v243
	v_add_u32_e32 v246, 0x2000, v243
	global_load_dwordx4 v[186:189], v243, s[40:41]
	global_load_dwordx4 v[190:193], v243, s[40:41] offset:1024
	global_load_dwordx4 v[194:197], v243, s[40:41] offset:2048
	global_load_dwordx4 v[198:201], v243, s[40:41] offset:3072
	global_load_dwordx4 v[202:205], v246, s[40:41]
	global_load_dwordx4 v[206:209], v246, s[40:41] offset:1024
	global_load_dwordx4 v[210:213], v246, s[40:41] offset:2048
	global_load_dwordx4 v[214:217], v246, s[40:41] offset:3072
	v_lshlrev_b32_e32 v236, 2, v235
	v_add_u32_e32 v237, 64, v236
	v_add_u32_e32 v238, 0x80, v236
	v_add_u32_e32 v239, 0xc0, v236
	v_lshrrev_b32_e32 v241, 6, v100
	v_lshlrev_b32_e32 v241, 15, v241
	v_lshl_or_b32 v241, v235, 4, v241
	s_lshl_b32 s0, s58, 11
	v_lshl_or_b32 v241, v234, 9, v241
	v_or_b32_e32 v241, s0, v241
	v_add_u32_e32 v242, 0x10000, v241
	v_mov_b32_e32 v245, 0x358637bd
	s_waitcnt vmcnt(0)
	v_add_f32_e32 v186, v186, v187
	v_add_f32_e32 v188, v188, v189
	v_add_f32_e32 v218, v186, v188
	v_add_f32_e32 v190, v190, v191
	v_add_f32_e32 v192, v192, v193
	v_add_f32_e32 v220, v190, v192
	v_add_f32_e32 v194, v194, v195
	v_add_f32_e32 v196, v196, v197
	v_add_f32_e32 v222, v194, v196
	v_add_f32_e32 v198, v198, v199
	v_add_f32_e32 v200, v200, v201
	v_add_f32_e32 v224, v198, v200
	v_add_f32_e32 v202, v202, v203
	v_add_f32_e32 v204, v204, v205
	v_add_f32_e32 v226, v202, v204
	v_add_f32_e32 v206, v206, v207
	v_add_f32_e32 v208, v208, v209
	v_add_f32_e32 v228, v206, v208
	v_add_f32_e32 v210, v210, v211
	v_add_f32_e32 v212, v212, v213
	v_add_f32_e32 v230, v210, v212
	v_add_f32_e32 v214, v214, v215
	v_add_f32_e32 v216, v216, v217
	v_add_f32_e32 v232, v214, v216
	ds_bpermute_b32 v186, v236, v218
	ds_bpermute_b32 v187, v237, v218
	ds_bpermute_b32 v188, v238, v218
	ds_bpermute_b32 v189, v239, v218
	ds_bpermute_b32 v190, v236, v220
	ds_bpermute_b32 v191, v237, v220
	ds_bpermute_b32 v192, v238, v220
	ds_bpermute_b32 v193, v239, v220
	ds_bpermute_b32 v194, v236, v222
	ds_bpermute_b32 v195, v237, v222
	ds_bpermute_b32 v196, v238, v222
	ds_bpermute_b32 v197, v239, v222
	ds_bpermute_b32 v198, v236, v224
	ds_bpermute_b32 v199, v237, v224
	ds_bpermute_b32 v200, v238, v224
	ds_bpermute_b32 v201, v239, v224
	s_waitcnt lgkmcnt(12)
	v_add_f32_e32 v186, v186, v187
	v_add_f32_e32 v186, v186, v188
	v_add_f32_e32 v186, v186, v189
	v_fmamk_f32 v186, v186, 0x3a800000, v245
	v_rsq_f32_e32 v218, v186
	s_waitcnt lgkmcnt(8)
	v_add_f32_e32 v190, v190, v191
	v_add_f32_e32 v190, v190, v192
	v_add_f32_e32 v190, v190, v193
	v_fmamk_f32 v190, v190, 0x3a800000, v245
	v_rsq_f32_e32 v220, v190
	s_waitcnt lgkmcnt(4)
	v_add_f32_e32 v194, v194, v195
	v_add_f32_e32 v194, v194, v196
	v_add_f32_e32 v194, v194, v197
	v_fmamk_f32 v194, v194, 0x3a800000, v245
	v_rsq_f32_e32 v222, v194
	s_waitcnt lgkmcnt(0)
	v_add_f32_e32 v198, v198, v199
	v_add_f32_e32 v198, v198, v200
	v_add_f32_e32 v198, v198, v201
	v_fmamk_f32 v198, v198, 0x3a800000, v245
	v_rsq_f32_e32 v224, v198
	ds_bpermute_b32 v202, v236, v226
	ds_bpermute_b32 v203, v237, v226
	ds_bpermute_b32 v204, v238, v226
	ds_bpermute_b32 v205, v239, v226
	ds_bpermute_b32 v206, v236, v228
	ds_bpermute_b32 v207, v237, v228
	ds_bpermute_b32 v208, v238, v228
	ds_bpermute_b32 v209, v239, v228
	ds_bpermute_b32 v210, v236, v230
	ds_bpermute_b32 v211, v237, v230
	ds_bpermute_b32 v212, v238, v230
	ds_bpermute_b32 v213, v239, v230
	ds_bpermute_b32 v214, v236, v232
	ds_bpermute_b32 v215, v237, v232
	ds_bpermute_b32 v216, v238, v232
	ds_bpermute_b32 v217, v239, v232
	s_waitcnt lgkmcnt(12)
	v_add_f32_e32 v202, v202, v203
	v_add_f32_e32 v202, v202, v204
	v_add_f32_e32 v202, v202, v205
	v_fmamk_f32 v202, v202, 0x3a800000, v245
	v_rsq_f32_e32 v226, v202
	s_waitcnt lgkmcnt(8)
	v_add_f32_e32 v206, v206, v207
	v_add_f32_e32 v206, v206, v208
	v_add_f32_e32 v206, v206, v209
	v_fmamk_f32 v206, v206, 0x3a800000, v245
	v_rsq_f32_e32 v228, v206
	s_waitcnt lgkmcnt(4)
	v_add_f32_e32 v210, v210, v211
	v_add_f32_e32 v210, v210, v212
	v_add_f32_e32 v210, v210, v213
	v_fmamk_f32 v210, v210, 0x3a800000, v245
	v_rsq_f32_e32 v230, v210
	s_waitcnt lgkmcnt(0)
; #define LAS __attribute__((address_space(3)))
; __device__ __forceinline__ unsigned pk2(float lo, float hi) { return f2bf(lo) | (f2bf(hi) << 16); }
;     __device__ __forceinline__ void fused(pg8::f32x4 (&acc)[2][2][4][2], const pg8::Unit& u, int wr, int wc, int fr, int fq, PG8_LAS unsigned char* lds, int wid, int lane) const {
;     ...
; #pragma unroll
;                 for (int bj = 0; bj < 2; ++bj) { const f32x4 v0 = acc[ai][bj][m][0] * rstd + bv[bj][0], v1 = acc[ai][bj][m][1] * rstd + bv[bj][1];
;                     v4u w; w.x = pk2(v0.x, v0.y); w.y = pk2(v0.z, v0.w); w.z = pk2(v1.x, v1.y); w.w = pk2(v1.z, v1.w);
;                     *(LAS v4u*)(lds + ((((rl >> 5) * 2 + bj) * 16 + kg) * 512 + (rl & 31) * 16)) = w; }
	v_add_f32_e32 v214, v214, v215
	v_add_f32_e32 v214, v214, v216
	v_add_f32_e32 v214, v214, v217
	v_fmamk_f32 v214, v214, 0x3a800000, v245
	v_rsq_f32_e32 v232, v214
	s_nop 0
	v_fma_f32 v142, v142, v218, v170
	v_fma_f32 v143, v143, v218, v171
	v_fma_f32 v144, v144, v218, v172
	v_fma_f32 v145, v145, v218, v173
	v_fma_f32 v138, v138, v218, v174
	v_fma_f32 v139, v139, v218, v175
	v_fma_f32 v140, v140, v218, v176
	v_fma_f32 v141, v141, v218, v177
	v_cvt_pk_bf16_f32 v142, v142, v143
	v_cvt_pk_bf16_f32 v143, v144, v145
	v_cvt_pk_bf16_f32 v144, v138, v139
	v_cvt_pk_bf16_f32 v145, v140, v141
	ds_write_b128 v241, v[142:145]
	v_fma_f32 v134, v134, v218, v178
	v_fma_f32 v135, v135, v218, v179
	v_fma_f32 v136, v136, v218, v180
	v_fma_f32 v137, v137, v218, v181
	v_fma_f32 v130, v130, v218, v182
	v_fma_f32 v131, v131, v218, v183
	v_fma_f32 v132, v132, v218, v184
	v_fma_f32 v133, v133, v218, v185
	v_cvt_pk_bf16_f32 v134, v134, v135
	v_cvt_pk_bf16_f32 v135, v136, v137
	v_cvt_pk_bf16_f32 v136, v130, v131
	v_cvt_pk_bf16_f32 v137, v132, v133
	ds_write_b128 v241, v[134:137] offset:8192
	v_fma_f32 v126, v126, v220, v170
	v_fma_f32 v127, v127, v220, v171
	v_fma_f32 v128, v128, v220, v172
	v_fma_f32 v129, v129, v220, v173
	v_fma_f32 v122, v122, v220, v174
	v_fma_f32 v123, v123, v220, v175
	v_fma_f32 v124, v124, v220, v176
	v_fma_f32 v125, v125, v220, v177
	v_cvt_pk_bf16_f32 v126, v126, v127
	v_cvt_pk_bf16_f32 v127, v128, v129
	v_cvt_pk_bf16_f32 v128, v122, v123
	v_cvt_pk_bf16_f32 v129, v124, v125
	ds_write_b128 v241, v[126:129] offset:256
	v_fma_f32 v118, v118, v220, v178
	v_fma_f32 v119, v119, v220, v179
	v_fma_f32 v120, v120, v220, v180
	v_fma_f32 v121, v121, v220, v181
	v_fma_f32 v114, v114, v220, v182
	v_fma_f32 v115, v115, v220, v183
	v_fma_f32 v116, v116, v220, v184
	v_fma_f32 v117, v117, v220, v185
	v_cvt_pk_bf16_f32 v118, v118, v119
	v_cvt_pk_bf16_f32 v119, v120, v121
	v_cvt_pk_bf16_f32 v120, v114, v115
	v_cvt_pk_bf16_f32 v121, v116, v117
	ds_write_b128 v241, v[118:121] offset:8448
	v_fma_f32 v94, v94, v222, v170
	v_fma_f32 v95, v95, v222, v171
	v_fma_f32 v96, v96, v222, v172
	v_fma_f32 v97, v97, v222, v173
	v_fma_f32 v90, v90, v222, v174
	v_fma_f32 v91, v91, v222, v175
	v_fma_f32 v92, v92, v222, v176
	v_fma_f32 v93, v93, v222, v177
	v_cvt_pk_bf16_f32 v94, v94, v95
	v_cvt_pk_bf16_f32 v95, v96, v97
	v_cvt_pk_bf16_f32 v96, v90, v91
	v_cvt_pk_bf16_f32 v97, v92, v93
	ds_write_b128 v241, v[94:97] offset:16384
	v_fma_f32 v86, v86, v222, v178
	v_fma_f32 v87, v87, v222, v179
	v_fma_f32 v88, v88, v222, v180
	v_fma_f32 v89, v89, v222, v181
	v_fma_f32 v82, v82, v222, v182
	v_fma_f32 v83, v83, v222, v183
	v_fma_f32 v84, v84, v222, v184
	v_fma_f32 v85, v85, v222, v185
	v_cvt_pk_bf16_f32 v86, v86, v87
	v_cvt_pk_bf16_f32 v87, v88, v89
	v_cvt_pk_bf16_f32 v88, v82, v83
	v_cvt_pk_bf16_f32 v89, v84, v85
	ds_write_b128 v241, v[86:89] offset:24576
	v_fma_f32 v78, v78, v224, v170
	v_fma_f32 v79, v79, v224, v171
	v_fma_f32 v80, v80, v224, v172
	v_fma_f32 v81, v81, v224, v173
	v_fma_f32 v74, v74, v224, v174
	v_fma_f32 v75, v75, v224, v175
	v_fma_f32 v76, v76, v224, v176
	v_fma_f32 v77, v77, v224, v177
	v_cvt_pk_bf16_f32 v78, v78, v79
	v_cvt_pk_bf16_f32 v79, v80, v81
	v_cvt_pk_bf16_f32 v80, v74, v75
	v_cvt_pk_bf16_f32 v81, v76, v77
	ds_write_b128 v241, v[78:81] offset:16640
	v_fma_f32 v70, v70, v224, v178
	v_fma_f32 v71, v71, v224, v179
	v_fma_f32 v72, v72, v224, v180
	v_fma_f32 v73, v73, v224, v181
	v_fma_f32 v66, v66, v224, v182
	v_fma_f32 v67, v67, v224, v183
	v_fma_f32 v68, v68, v224, v184
	v_fma_f32 v69, v69, v224, v185
	v_cvt_pk_bf16_f32 v70, v70, v71
	v_cvt_pk_bf16_f32 v71, v72, v73
	v_cvt_pk_bf16_f32 v72, v66, v67
	v_cvt_pk_bf16_f32 v73, v68, v69
	ds_write_b128 v241, v[70:73] offset:24832
	v_fma_f32 v62, v62, v226, v170
	v_fma_f32 v63, v63, v226, v171
	v_fma_f32 v64, v64, v226, v172
	v_fma_f32 v65, v65, v226, v173
	v_fma_f32 v58, v58, v226, v174
	v_fma_f32 v59, v59, v226, v175
	v_fma_f32 v60, v60, v226, v176
	v_fma_f32 v61, v61, v226, v177
	v_cvt_pk_bf16_f32 v62, v62, v63
	v_cvt_pk_bf16_f32 v63, v64, v65
	v_cvt_pk_bf16_f32 v64, v58, v59
	v_cvt_pk_bf16_f32 v65, v60, v61
	ds_write_b128 v242, v[62:65]
	v_fma_f32 v54, v54, v226, v178
	v_fma_f32 v55, v55, v226, v179
	v_fma_f32 v56, v56, v226, v180
	v_fma_f32 v57, v57, v226, v181
	v_fma_f32 v50, v50, v226, v182
	v_fma_f32 v51, v51, v226, v183
	v_fma_f32 v52, v52, v226, v184
	v_fma_f32 v53, v53, v226, v185
	v_cvt_pk_bf16_f32 v54, v54, v55
	v_cvt_pk_bf16_f32 v55, v56, v57
	v_cvt_pk_bf16_f32 v56, v50, v51
	v_cvt_pk_bf16_f32 v57, v52, v53
	ds_write_b128 v242, v[54:57] offset:8192
	v_fma_f32 v46, v46, v228, v170
	v_fma_f32 v47, v47, v228, v171
	v_fma_f32 v48, v48, v228, v172
	v_fma_f32 v49, v49, v228, v173
	v_fma_f32 v42, v42, v228, v174
	v_fma_f32 v43, v43, v228, v175
	v_fma_f32 v44, v44, v228, v176
	v_fma_f32 v45, v45, v228, v177
	v_cvt_pk_bf16_f32 v46, v46, v47
	v_cvt_pk_bf16_f32 v47, v48, v49
	v_cvt_pk_bf16_f32 v48, v42, v43
	v_cvt_pk_bf16_f32 v49, v44, v45
	ds_write_b128 v242, v[46:49] offset:256
	v_fma_f32 v38, v38, v228, v178
	v_fma_f32 v39, v39, v228, v179
	v_fma_f32 v40, v40, v228, v180
	v_fma_f32 v41, v41, v228, v181
	v_fma_f32 v34, v34, v228, v182
	v_fma_f32 v35, v35, v228, v183
	v_fma_f32 v36, v36, v228, v184
	v_fma_f32 v37, v37, v228, v185
	v_cvt_pk_bf16_f32 v38, v38, v39
	v_cvt_pk_bf16_f32 v39, v40, v41
	v_cvt_pk_bf16_f32 v40, v34, v35
	v_cvt_pk_bf16_f32 v41, v36, v37
	ds_write_b128 v242, v[38:41] offset:8448
	v_fma_f32 v30, v30, v230, v170
	v_fma_f32 v31, v31, v230, v171
	v_fma_f32 v32, v32, v230, v172
	v_fma_f32 v33, v33, v230, v173
	v_fma_f32 v26, v26, v230, v174
	v_fma_f32 v27, v27, v230, v175
	v_fma_f32 v28, v28, v230, v176
; #define LAS __attribute__((address_space(3)))
; __device__ __forceinline__ unsigned pk2(float lo, float hi) { return f2bf(lo) | (f2bf(hi) << 16); }
; __device__ __forceinline__ int crow(int r, int hi) { return (r & 3) + 8 * (r >> 2) + 4 * hi; }
; __device__ __forceinline__ void topk_p_lds(const bf16* __restrict__ skf, const char* qlds, int r32, int hi, unsigned (&Lst)[16]) {
;     bf16x8 bq[8];
; #pragma unroll
;     for (int ks = 0; ks < 8; ++ks) bq[ks] = *reinterpret_cast<const bf16x8*>(qlds + ((2 * ks + hi) * 32 + r32) * 16);
; #pragma unroll
;     for (int kb = 0; kb < 4; ++kb) {
;         bf16x8 a[8];
; #pragma unroll
;         for (int ks = 0; ks < 8; ++ks) a[ks] = *reinterpret_cast<const bf16x8*>(skf + (size_t)((((kb * 8 + ks) * 2 + hi) * 32 + r32) * 8));
;         f32x16 acc = {};
; #pragma unroll
;         for (int ks = 0; ks < 8; ++ks) acc = __builtin_amdgcn_mfma_f32_32x32x16_bf16(a[ks], bq[ks], acc, 0, 0, 0);
;         unsigned S[16];
; #pragma unroll
;         for (int r = 0; r < 16; ++r) S[r] = (__float_as_uint(acc[r]) & ~127u) | (unsigned)(32 * kb + crow(r, hi));
;     __device__ __forceinline__ void fused(pg8::f32x4 (&acc)[2][2][4][2], const pg8::Unit& u, int wr, int wc, int fr, int fq, PG8_LAS unsigned char* lds, int wid, int lane) const {
;     ...
;                 for (int bj = 0; bj < 2; ++bj) { const f32x4 v0 = acc[ai][bj][m][0] * rstd + bv[bj][0], v1 = acc[ai][bj][m][1] * rstd + bv[bj][1];
;                     v4u w; w.x = pk2(v0.x, v0.y); w.y = pk2(v0.z, v0.w); w.z = pk2(v1.x, v1.y); w.w = pk2(v1.z, v1.w);
;                     *(LAS v4u*)(lds + ((((rl >> 5) * 2 + bj) * 16 + kg) * 512 + (rl & 31) * 16)) = w; }
;             }
;         asm volatile("s_waitcnt lgkmcnt(0)" ::: "memory"); __builtin_amdgcn_s_barrier(); asm volatile("" ::: "memory");
	v_fma_f32 v29, v29, v230, v177
	v_cvt_pk_bf16_f32 v30, v30, v31
	v_cvt_pk_bf16_f32 v31, v32, v33
	v_cvt_pk_bf16_f32 v32, v26, v27
	v_cvt_pk_bf16_f32 v33, v28, v29
	ds_write_b128 v242, v[30:33] offset:16384
	v_fma_f32 v22, v22, v230, v178
	v_fma_f32 v23, v23, v230, v179
	v_fma_f32 v24, v24, v230, v180
	v_fma_f32 v25, v25, v230, v181
	v_fma_f32 v18, v18, v230, v182
	v_fma_f32 v19, v19, v230, v183
	v_fma_f32 v20, v20, v230, v184
	v_fma_f32 v21, v21, v230, v185
	v_cvt_pk_bf16_f32 v22, v22, v23
	v_cvt_pk_bf16_f32 v23, v24, v25
	v_cvt_pk_bf16_f32 v24, v18, v19
	v_cvt_pk_bf16_f32 v25, v20, v21
	ds_write_b128 v242, v[22:25] offset:24576
	v_fma_f32 v14, v14, v232, v170
	v_fma_f32 v15, v15, v232, v171
	v_fma_f32 v16, v16, v232, v172
	v_fma_f32 v17, v17, v232, v173
	v_fma_f32 v10, v10, v232, v174
	v_fma_f32 v11, v11, v232, v175
	v_fma_f32 v12, v12, v232, v176
	v_fma_f32 v13, v13, v232, v177
	v_cvt_pk_bf16_f32 v14, v14, v15
	v_cvt_pk_bf16_f32 v15, v16, v17
	v_cvt_pk_bf16_f32 v16, v10, v11
	v_cvt_pk_bf16_f32 v17, v12, v13
	ds_write_b128 v242, v[14:17] offset:16640
	v_fma_f32 v6, v6, v232, v178
	v_fma_f32 v7, v7, v232, v179
	v_fma_f32 v8, v8, v232, v180
	v_fma_f32 v9, v9, v232, v181
	v_fma_f32 v2, v2, v232, v182
	v_fma_f32 v3, v3, v232, v183
	v_fma_f32 v4, v4, v232, v184
	v_fma_f32 v5, v5, v232, v185
	v_cvt_pk_bf16_f32 v6, v6, v7
	v_cvt_pk_bf16_f32 v7, v8, v9
	v_cvt_pk_bf16_f32 v8, v2, v3
	v_cvt_pk_bf16_f32 v9, v4, v5
	ds_write_b128 v242, v[6:9] offset:24832
	s_movk_i32 s19, 0x3000
	s_movk_i32 s33, 0x49
	v_and_b32_e32 v70, 63, v167
	v_bfe_u32 v62, v167, 5, 1
	v_lshlrev_b32_e32 v72, 2, v62
	s_movk_i32 s15, 0xff80
	s_lshl_b64 s[0:1], s[22:23], 16
	v_readlane_b32 s16, v240, 17
	v_readlane_b32 s17, v240, 18
	s_nop 3
	s_add_u32 s0, s16, s0
	v_and_b32_e32 v2, 0x1f0, v168
	s_waitcnt lgkmcnt(0)
	s_barrier
	s_addc_u32 s1, s17, s1
	v_lshl_or_b32 v148, v62, 9, v2
	global_load_dwordx4 v[2:5], v148, s[0:1]
	global_load_dwordx4 v[22:25], v148, s[0:1] offset:1024
	s_lshl_b32 s3, s72, 14
	s_add_i32 s3, s3, 0
	v_lshl_add_u32 v71, v70, 4, s3
	ds_read_b128 v[30:33], v71
	ds_read_b128 v[18:21], v71 offset:1024
	global_load_dwordx4 v[34:37], v148, s[0:1] offset:2048
	global_load_dwordx4 v[42:45], v148, s[0:1] offset:3072
	s_waitcnt vmcnt(3) lgkmcnt(1)
	v_mfma_f32_32x32x16_bf16 v[2:17], v[2:5], v[30:33], 0
	ds_read_b128 v[38:41], v71 offset:2048
	ds_read_b128 v[26:29], v71 offset:3072
	v_lshl_add_u64 v[66:67], s[0:1], 0, v[148:149]
	s_movk_i32 s0, 0x2000
	v_add_co_u32_e32 v54, vcc, s0, v66
	s_movk_i32 s0, 0x1000
	s_nop 0
	v_addc_co_u32_e32 v55, vcc, 0, v67, vcc
	s_waitcnt vmcnt(2) lgkmcnt(2)
	v_mfma_f32_32x32x16_bf16 v[2:17], v[22:25], v[18:21], v[2:17]
	global_load_dwordx4 v[46:49], v[54:55], off offset:-4096
	v_add_co_u32_e32 v60, vcc, s0, v66
	s_movk_i32 s0, 0x4000
	s_nop 0
	v_addc_co_u32_e32 v61, vcc, 0, v67, vcc
	v_add_co_u32_e32 v64, vcc, s19, v66
	s_waitcnt vmcnt(2) lgkmcnt(1)
	v_mfma_f32_32x32x16_bf16 v[2:17], v[34:37], v[38:41], v[2:17]
	v_addc_co_u32_e32 v65, vcc, 0, v67, vcc
	s_movk_i32 s16, 0x4b
	s_movk_i32 s17, 0x53
	s_movk_i32 s3, 0x41
	s_movk_i32 s23, 0x58
	s_waitcnt vmcnt(1) lgkmcnt(0)
	v_mfma_f32_32x32x16_bf16 v[2:17], v[42:45], v[26:29], v[2:17]
	global_load_dwordx4 v[42:45], v[60:61], off offset:1024
	ds_read_b128 v[34:37], v71 offset:4096
	ds_read_b128 v[22:25], v71 offset:5120
	global_load_dwordx4 v[50:53], v[54:55], off
	global_load_dwordx4 v[56:59], v[60:61], off offset:2048
	s_waitcnt vmcnt(3) lgkmcnt(1)
	v_mfma_f32_32x32x16_bf16 v[2:17], v[46:49], v[34:37], v[2:17]
	s_waitcnt vmcnt(2) lgkmcnt(0)
	v_mfma_f32_32x32x16_bf16 v[2:17], v[42:45], v[22:25], v[2:17]
	ds_read_b128 v[46:49], v71 offset:6144
	ds_read_b128 v[42:45], v71 offset:7168
	global_load_dwordx4 v[78:81], v[54:55], off offset:3072
	global_load_dwordx4 v[74:77], v[54:55], off offset:2048
	s_waitcnt vmcnt(2) lgkmcnt(1)
	v_mfma_f32_32x32x16_bf16 v[2:17], v[56:59], v[46:49], v[2:17]
	global_load_dwordx4 v[56:59], v[60:61], off offset:3072
	s_nop 0
	global_load_dwordx4 v[60:63], v[64:65], off offset:1024
	s_waitcnt vmcnt(1) lgkmcnt(0)
	v_mfma_f32_32x32x16_bf16 v[2:17], v[56:59], v[42:45], v[2:17]
	global_load_dwordx4 v[56:59], v[54:55], off offset:1024
	v_add_co_u32_e32 v54, vcc, s0, v66
	s_movk_i32 s0, 0x6000
	s_nop 0
	v_addc_co_u32_e32 v55, vcc, 0, v67, vcc
	global_load_dwordx4 v[82:85], v[54:55], off offset:-4096
	s_nop 5
	v_and_b32_e32 v7, 0xffffff80, v7
	v_and_b32_e32 v8, 0xffffff80, v8
	v_and_b32_e32 v15, 0xffffff80, v15
	v_and_b32_e32 v6, 0xffffff80, v6
	v_and_b32_e32 v10, 0xffffff80, v10
	v_and_b32_e32 v5, 0xffffff80, v5
	v_and_b32_e32 v16, 0xffffff80, v16
	v_or3_b32 v7, v72, v7, 9
	v_or3_b32 v8, v72, v8, 10
	v_and_or_b32 v2, v2, s15, v72
	v_or3_b32 v15, v72, v15, 25
	v_or3_b32 v6, v72, v6, 8
	v_or3_b32 v10, v72, v10, 16
	v_or3_b32 v5, v72, v5, 3
	v_or3_b32 v16, v72, v16, 26
	v_max_f32_e32 v8, v8, v8
	v_max_f32_e32 v7, v7, v7
	v_max_f32_e32 v2, v2, v2
	v_max_f32_e32 v15, v15, v15
	v_max_f32_e32 v10, v10, v10
	v_max_f32_e32 v6, v6, v6
	v_max_f32_e32 v16, v16, v16
	v_max_f32_e32 v5, v5, v5
	v_min_f32_e32 v86, v7, v8
	v_min_f32_e32 v87, v2, v15
	v_min_f32_e32 v88, v6, v10
	v_min_f32_e32 v89, v5, v16
	v_min_f32_e32 v94, v86, v87
	v_min_f32_e32 v96, v88, v89
	v_max_f32_e32 v100, v86, v87
	v_max_f32_e32 v101, v88, v89
	global_load_dwordx4 v[86:89], v[64:65], off offset:2048
	v_and_b32_e32 v11, 0xffffff80, v11
	v_and_b32_e32 v12, 0xffffff80, v12
	v_and_b32_e32 v4, 0xffffff80, v4
	v_and_b32_e32 v17, 0xffffff80, v17
	v_or3_b32 v11, v72, v11, 17
	v_or3_b32 v12, v72, v12, 18
	v_or3_b32 v4, v72, v4, 2
	v_or3_b32 v17, v72, v17, 27
	v_max_f32_e32 v12, v12, v12
	v_max_f32_e32 v11, v11, v11
; __device__ __forceinline__ int crow(int r, int hi) { return (r & 3) + 8 * (r >> 2) + 4 * hi; }
; __device__ __forceinline__ unsigned kmax(unsigned a, unsigned b) { return __float_as_uint(__builtin_fmaxf(__uint_as_float(a), __uint_as_float(b))); }
; __device__ __forceinline__ void sort16_desc(unsigned (&a)[16]) {
;     ...
;     PEER_CE(0, 13); PEER_CE(1, 12); PEER_CE(2, 15); PEER_CE(3, 14); PEER_CE(4, 8); PEER_CE(5, 6); PEER_CE(7, 11); PEER_CE(9, 10);
;     PEER_CE(0, 5); PEER_CE(1, 7); PEER_CE(2, 9); PEER_CE(3, 4); PEER_CE(6, 13); PEER_CE(8, 14); PEER_CE(10, 15); PEER_CE(11, 12);
;     PEER_CE(0, 1); PEER_CE(2, 3); PEER_CE(4, 5); PEER_CE(6, 8); PEER_CE(7, 9); PEER_CE(10, 11); PEER_CE(12, 13); PEER_CE(14, 15);
;     PEER_CE(0, 2); PEER_CE(1, 3); PEER_CE(4, 10); PEER_CE(5, 11); PEER_CE(6, 7); PEER_CE(8, 9); PEER_CE(12, 14); PEER_CE(13, 15);
;     PEER_CE(1, 2); PEER_CE(3, 12); PEER_CE(4, 6); PEER_CE(5, 7); PEER_CE(8, 10); PEER_CE(9, 11); PEER_CE(13, 14);
;     PEER_CE(1, 4); PEER_CE(2, 6); PEER_CE(5, 8); PEER_CE(7, 10); PEER_CE(9, 13); PEER_CE(11, 14);
;     PEER_CE(2, 4); PEER_CE(3, 6); PEER_CE(9, 12); PEER_CE(11, 13);
;     PEER_CE(3, 5); PEER_CE(6, 8); PEER_CE(7, 9); PEER_CE(10, 12);
;     PEER_CE(3, 4); PEER_CE(5, 6); PEER_CE(7, 8); PEER_CE(9, 10); PEER_CE(11, 12);
;     PEER_CE(6, 7); PEER_CE(8, 9);
;     ...
; }
; __device__ __forceinline__ void merge_top16(unsigned (&Lst)[16], const unsigned (&S)[16]) {
; #pragma unroll
;     for (int i = 0; i < 16; ++i) Lst[i] = kmax(Lst[i], S[15 - i]);
;     bitonic_merge_desc<16>(Lst);
; }
; __device__ __forceinline__ void topk_p_lds(const bf16* __restrict__ skf, const char* qlds, int r32, int hi, unsigned (&Lst)[16]) {
;     ...
;     for (int kb = 0; kb < 4; ++kb) {
;         bf16x8 a[8];
; #pragma unroll
;         for (int ks = 0; ks < 8; ++ks) a[ks] = *reinterpret_cast<const bf16x8*>(skf + (size_t)((((kb * 8 + ks) * 2 + hi) * 32 + r32) * 8));
;         f32x16 acc = {};
; #pragma unroll
;         for (int ks = 0; ks < 8; ++ks) acc = __builtin_amdgcn_mfma_f32_32x32x16_bf16(a[ks], bq[ks], acc, 0, 0, 0);
;         unsigned S[16];
; #pragma unroll
;         for (int r = 0; r < 16; ++r) S[r] = (__float_as_uint(acc[r]) & ~127u) | (unsigned)(32 * kb + crow(r, hi));
;         sort16_desc(S);
;         if (kb == 0) {
; #pragma unroll
;             for (int r = 0; r < 16; ++r) Lst[r] = S[r];
;         } else merge_top16(Lst, S);
	v_max_f32_e32 v17, v17, v17
	v_max_f32_e32 v4, v4, v4
	v_min_f32_e32 v90, v11, v12
	v_min_f32_e32 v91, v4, v17
	v_min_f32_e32 v97, v90, v91
	v_max_f32_e32 v108, v6, v10
	v_max_f32_e32 v10, v90, v91
	global_load_dwordx4 v[90:93], v[64:65], off offset:3072
	v_and_b32_e32 v9, 0xffffff80, v9
	v_and_b32_e32 v13, 0xffffff80, v13
	v_and_b32_e32 v3, 0xffffff80, v3
	v_and_b32_e32 v14, 0xffffff80, v14
	v_or3_b32 v9, v72, v9, 11
	v_or3_b32 v13, v72, v13, 19
	v_or3_b32 v3, v72, v3, 1
	v_or3_b32 v14, v72, v14, 24
	v_max_f32_e32 v13, v13, v13
	v_max_f32_e32 v9, v9, v9
	v_max_f32_e32 v14, v14, v14
	v_max_f32_e32 v3, v3, v3
	v_min_f32_e32 v68, v9, v13
	v_min_f32_e32 v69, v3, v14
	v_max_f32_e32 v103, v3, v14
	v_max_f32_e32 v104, v9, v13
	v_max_f32_e32 v105, v4, v17
	v_max_f32_e32 v106, v11, v12
	v_max_f32_e32 v107, v5, v16
	v_max_f32_e32 v2, v2, v15
	v_max_f32_e32 v6, v7, v8
	v_min_f32_e32 v73, v68, v69
	v_min_f32_e32 v3, v103, v104
	v_min_f32_e32 v4, v105, v106
	v_min_f32_e32 v5, v107, v108
	v_min_f32_e32 v7, v2, v6
	v_max_f32_e32 v12, v68, v69
	v_min_f32_e32 v95, v73, v94
	v_min_f32_e32 v98, v96, v97
	v_min_f32_e32 v102, v100, v101
	v_min_f32_e32 v9, v3, v4
	v_min_f32_e32 v8, v5, v7
	v_min_f32_e32 v13, v10, v12
	v_max_f32_e32 v64, v73, v94
	v_max_f32_e32 v65, v96, v97
	v_min_f32_e32 v11, v102, v9
	v_min_f32_e32 v14, v8, v13
	v_max_f32_e32 v16, v95, v98
	v_min_f32_e32 v17, v64, v65
	v_min_f32_e32 v15, v11, v14
	v_min_f32_e32 v68, v16, v17
	v_max_f32_e32 v11, v11, v14
	v_max_f32_e32 v14, v16, v17
	v_min_f32_e32 v73, v15, v68
	v_max_f32_e32 v15, v15, v68
	v_min_f32_e32 v16, v11, v14
	v_min_f32_e32 v99, v95, v98
	v_min_f32_e32 v94, v15, v16
	v_max_f32_e32 v95, v15, v16
	v_max_f32_e32 v68, v8, v13
	v_max_f32_e32 v69, v100, v101
	v_max_f32_e32 v96, v3, v4
	v_max_f32_e32 v100, v102, v9
	v_max_f32_e32 v101, v5, v7
	v_max_f32_e32 v102, v10, v12
	v_max_f32_e32 v112, v11, v14
	v_max_f32_e32 v113, v2, v6
	v_mfma_f32_32x32x16_bf16 v[2:17], v[50:53], v[30:33], 0
	v_max_f32_e32 v50, v103, v104
	v_max_f32_e32 v52, v105, v106
	v_max_f32_e32 v53, v107, v108
	v_min_f32_e32 v51, v113, v50
	v_min_f32_e32 v103, v52, v53
	v_min_f32_e32 v97, v69, v96
	v_min_f32_e32 v109, v101, v102
	s_waitcnt vmcnt(3)
	v_mfma_f32_32x32x16_bf16 v[2:17], v[56:59], v[18:21], v[2:17]
	v_min_f32_e32 v104, v51, v103
	v_max_f32_e32 v64, v64, v65
	v_min_f32_e32 v98, v68, v97
	v_min_f32_e32 v110, v100, v109
	v_min_f32_e32 v56, v104, v64
	v_max_f32_e32 v50, v113, v50
	v_max_f32_e32 v52, v52, v53
	v_mfma_f32_32x32x16_bf16 v[2:17], v[74:77], v[38:41], v[2:17]
	v_min_f32_e32 v57, v112, v56
	v_max_f32_e32 v58, v98, v110
	v_max_f32_e32 v56, v112, v56
	v_max_f32_e32 v51, v51, v103
	v_min_f32_e32 v53, v50, v52
	v_max_f32_e32 v65, v101, v102
	v_max_f32_e32 v69, v69, v96
	v_mfma_f32_32x32x16_bf16 v[2:17], v[78:81], v[26:29], v[2:17]
	v_min_f32_e32 v59, v58, v56
	v_max_f32_e32 v56, v58, v56
	v_max_f32_e32 v58, v104, v64
	v_min_f32_e32 v64, v51, v53
	v_min_f32_e32 v74, v65, v69
	v_min_f32_e32 v75, v64, v74
	v_max_f32_e32 v68, v68, v97
	v_max_f32_e32 v77, v100, v109
	v_min_f32_e32 v76, v58, v75
	v_min_f32_e32 v78, v68, v77
	v_min_f32_e32 v79, v76, v78
	v_min_f32_e32 v96, v56, v79
	v_max_f32_e32 v102, v76, v78
	v_max_f32_e32 v104, v56, v79
	global_load_dwordx4 v[78:81], v[54:55], off offset:2048
	s_waitcnt vmcnt(3)
	v_mfma_f32_32x32x16_bf16 v[2:17], v[82:85], v[34:37], v[2:17]
	v_min_f32_e32 v111, v98, v110
	v_min_f32_e32 v105, v111, v57
	v_max_f32_e32 v57, v111, v57
	v_min_f32_e32 v98, v59, v57
	v_max_f32_e32 v97, v59, v57
	v_max_f32_e32 v57, v58, v75
	v_max_f32_e32 v58, v68, v77
	v_mfma_f32_32x32x16_bf16 v[2:17], v[60:63], v[22:25], v[2:17]
	v_min_f32_e32 v101, v57, v58
	v_max_f32_e32 v51, v51, v53
	v_max_f32_e32 v53, v65, v69
	global_load_dwordx4 v[82:85], v[54:55], off offset:3072
	v_min_f32_e32 v103, v101, v102
	v_min_f32_e32 v106, v95, v105
	v_min_f32_e32 v100, v96, v97
	s_waitcnt vmcnt(3)
	v_mfma_f32_32x32x16_bf16 v[2:17], v[86:89], v[46:49], v[2:17]
	v_max_f32_e32 v86, v57, v58
	v_max_f32_e32 v87, v64, v74
	v_min_f32_e32 v88, v51, v53
	v_min_f32_e32 v89, v87, v88
	v_min_f32_e32 v107, v103, v104
	v_min_f32_e32 v108, v86, v89
	s_waitcnt vmcnt(2)
	v_mfma_f32_32x32x16_bf16 v[2:17], v[90:93], v[42:45], v[2:17]
	s_nop 11
	v_and_b32_e32 v9, 0xffffff80, v9
	v_and_b32_e32 v13, 0xffffff80, v13
	v_and_b32_e32 v3, 0xffffff80, v3
	v_and_b32_e32 v14, 0xffffff80, v14
	v_and_b32_e32 v7, 0xffffff80, v7
	v_and_b32_e32 v8, 0xffffff80, v8
	v_and_b32_e32 v2, 0xffffff80, v2
	v_and_b32_e32 v15, 0xffffff80, v15
	v_and_b32_e32 v6, 0xffffff80, v6
	v_and_b32_e32 v10, 0xffffff80, v10
	v_and_b32_e32 v5, 0xffffff80, v5
	v_and_b32_e32 v16, 0xffffff80, v16
	v_and_b32_e32 v11, 0xffffff80, v11
	v_and_b32_e32 v12, 0xffffff80, v12
	v_and_b32_e32 v4, 0xffffff80, v4
	v_and_b32_e32 v17, 0xffffff80, v17
	v_or3_b32 v9, v72, v9, 43
	v_or3_b32 v13, v72, v13, 51
	v_or3_b32 v3, v72, v3, 33
	v_or3_b32 v14, v72, v14, 56
	v_or3_b32 v7, v72, v7, 41
	v_or3_b32 v8, v72, v8, 42
	v_or3_b32 v2, v72, v2, 32
	v_or3_b32 v15, v72, v15, 57
	v_or3_b32 v6, v72, v6, 40
	v_or3_b32 v10, v72, v10, 48
	v_or3_b32 v5, v72, v5, 35
	v_or3_b32 v16, v72, v16, 58
	v_or3_b32 v11, v72, v11, 49
	v_or3_b32 v12, v72, v12, 50
	v_or3_b32 v4, v72, v4, 34
	v_or3_b32 v17, v72, v17, 59
	v_max_f32_e32 v13, v13, v13
	v_max_f32_e32 v9, v9, v9
	v_max_f32_e32 v14, v14, v14
	v_max_f32_e32 v3, v3, v3
	v_max_f32_e32 v8, v8, v8
	v_max_f32_e32 v7, v7, v7
	v_max_f32_e32 v15, v15, v15
	v_max_f32_e32 v2, v2, v2
	v_max_f32_e32 v10, v10, v10
	v_max_f32_e32 v6, v6, v6
	v_max_f32_e32 v16, v16, v16
	v_max_f32_e32 v5, v5, v5
	v_max_f32_e32 v12, v12, v12
	v_max_f32_e32 v11, v11, v11
	v_max_f32_e32 v17, v17, v17
; template <int N> __device__ __forceinline__ void bitonic_sort_desc(unsigned (&a)[N]) {
;     ...
;                 if (l > i) { const bool desc = (i & k) == 0; const unsigned mx = kmax(a[i], a[l]), mn = kmin(a[i], a[l]); a[i] = desc ? mx : mn; a[l] = desc ? mn : mx; } }
; }
; template <int N> __device__ __forceinline__ void bitonic_merge_desc(unsigned (&a)[N]) {
; #pragma unroll
;     for (int j = N >> 1; j > 0; j >>= 1)
; #pragma unroll
;         for (int i = 0; i < N; ++i) { const int l = i ^ j;
;             if (l > i) { const unsigned mx = kmax(a[i], a[l]), mn = kmin(a[i], a[l]); a[i] = mx; a[l] = mn; } }
; }
; __device__ __forceinline__ void sort16_desc(unsigned (&a)[16]) {
;     ...
;     PEER_CE(0, 13); PEER_CE(1, 12); PEER_CE(2, 15); PEER_CE(3, 14); PEER_CE(4, 8); PEER_CE(5, 6); PEER_CE(7, 11); PEER_CE(9, 10);
;     PEER_CE(0, 5); PEER_CE(1, 7); PEER_CE(2, 9); PEER_CE(3, 4); PEER_CE(6, 13); PEER_CE(8, 14); PEER_CE(10, 15); PEER_CE(11, 12);
;     PEER_CE(0, 1); PEER_CE(2, 3); PEER_CE(4, 5); PEER_CE(6, 8); PEER_CE(7, 9); PEER_CE(10, 11); PEER_CE(12, 13); PEER_CE(14, 15);
;     PEER_CE(0, 2); PEER_CE(1, 3); PEER_CE(4, 10); PEER_CE(5, 11); PEER_CE(6, 7); PEER_CE(8, 9); PEER_CE(12, 14); PEER_CE(13, 15);
;     PEER_CE(1, 2); PEER_CE(3, 12); PEER_CE(4, 6); PEER_CE(5, 7); PEER_CE(8, 10); PEER_CE(9, 11); PEER_CE(13, 14);
;     PEER_CE(1, 4); PEER_CE(2, 6); PEER_CE(5, 8); PEER_CE(7, 10); PEER_CE(9, 13); PEER_CE(11, 14);
;     PEER_CE(2, 4); PEER_CE(3, 6); PEER_CE(9, 12); PEER_CE(11, 13);
;     PEER_CE(3, 5); PEER_CE(6, 8); PEER_CE(7, 9); PEER_CE(10, 12);
;     PEER_CE(3, 4); PEER_CE(5, 6); PEER_CE(7, 8); PEER_CE(9, 10); PEER_CE(11, 12);
;     PEER_CE(6, 7); PEER_CE(8, 9);
;     ...
; }
; __device__ __forceinline__ void merge_top16(unsigned (&Lst)[16], const unsigned (&S)[16]) {
; #pragma unroll
;     for (int i = 0; i < 16; ++i) Lst[i] = kmax(Lst[i], S[15 - i]);
;     bitonic_merge_desc<16>(Lst);
; }
; __device__ __forceinline__ void topk_p_lds(const bf16* __restrict__ skf, const char* qlds, int r32, int hi, unsigned (&Lst)[16]) {
;     ...
;     for (int kb = 0; kb < 4; ++kb) {
;         bf16x8 a[8];
; #pragma unroll
;         for (int ks = 0; ks < 8; ++ks) a[ks] = *reinterpret_cast<const bf16x8*>(skf + (size_t)((((kb * 8 + ks) * 2 + hi) * 32 + r32) * 8));
;         f32x16 acc = {};
; #pragma unroll
	v_max_f32_e32 v4, v4, v4
	v_min_f32_e32 v56, v9, v13
	v_min_f32_e32 v57, v3, v14
	v_min_f32_e32 v59, v7, v8
	v_min_f32_e32 v60, v2, v15
	v_min_f32_e32 v63, v6, v10
	v_min_f32_e32 v64, v5, v16
	v_min_f32_e32 v68, v11, v12
	v_min_f32_e32 v69, v4, v17
	v_max_f32_e32 v3, v3, v14
	v_max_f32_e32 v9, v9, v13
	v_max_f32_e32 v4, v4, v17
	v_max_f32_e32 v11, v11, v12
	v_max_f32_e32 v5, v5, v16
	v_max_f32_e32 v6, v6, v10
	v_max_f32_e32 v2, v2, v15
	v_max_f32_e32 v7, v7, v8
	v_min_f32_e32 v13, v3, v9
	v_min_f32_e32 v12, v4, v11
	v_min_f32_e32 v10, v5, v6
	v_min_f32_e32 v8, v2, v7
	v_max_f32_e32 v7, v2, v7
	v_max_f32_e32 v9, v3, v9
	v_max_f32_e32 v11, v4, v11
	v_max_f32_e32 v6, v5, v6
	global_load_dwordx4 v[2:5], v[54:55], off
	v_min_f32_e32 v58, v56, v57
	v_min_f32_e32 v61, v59, v60
	v_min_f32_e32 v65, v63, v64
	v_min_f32_e32 v74, v68, v69
	v_min_f32_e32 v62, v58, v61
	v_min_f32_e32 v75, v65, v74
	v_min_f32_e32 v90, v62, v75
	v_max_f32_e32 v62, v62, v75
	v_max_f32_e32 v58, v58, v61
	v_max_f32_e32 v61, v65, v74
	global_load_dwordx4 v[74:77], v[54:55], off offset:1024
	v_max_f32_e32 v59, v59, v60
	v_max_f32_e32 v60, v63, v64
	v_max_f32_e32 v16, v68, v69
	v_max_f32_e32 v56, v56, v57
	v_min_f32_e32 v63, v59, v60
	v_min_f32_e32 v14, v13, v12
	v_min_f32_e32 v15, v10, v8
	v_min_f32_e32 v57, v16, v56
	v_min_f32_e32 v17, v63, v14
	v_min_f32_e32 v64, v15, v57
	v_min_f32_e32 v65, v58, v61
	v_min_f32_e32 v68, v17, v64
	v_min_f32_e32 v69, v62, v65
	v_max_f32_e32 v17, v17, v64
	v_max_f32_e32 v62, v62, v65
	v_min_f32_e32 v91, v68, v69
	v_max_f32_e32 v68, v68, v69
	v_min_f32_e32 v64, v17, v62
	v_max_f32_e32 v15, v15, v57
	v_max_f32_e32 v57, v59, v60
	v_max_f32_e32 v12, v13, v12
	v_max_f32_e32 v14, v63, v14
	v_max_f32_e32 v8, v10, v8
	v_max_f32_e32 v10, v16, v56
	v_max_f32_e32 v17, v17, v62
	v_min_f32_e32 v62, v7, v9
	v_min_f32_e32 v63, v11, v6
	v_min_f32_e32 v92, v68, v64
	v_max_f32_e32 v93, v68, v64
	v_min_f32_e32 v13, v57, v12
	v_min_f32_e32 v16, v8, v10
	v_min_f32_e32 v64, v62, v63
	v_max_f32_e32 v58, v58, v61
	v_min_f32_e32 v59, v15, v13
	v_min_f32_e32 v56, v14, v16
	v_min_f32_e32 v61, v64, v58
	v_add_co_u32_e32 v68, vcc, s0, v66
	v_min_f32_e32 v60, v59, v56
	v_min_f32_e32 v65, v17, v61
	v_max_f32_e32 v56, v59, v56
	v_max_f32_e32 v17, v17, v61
	v_addc_co_u32_e32 v69, vcc, 0, v67, vcc
	v_min_f32_e32 v109, v60, v65
	v_min_f32_e32 v59, v56, v17
	v_max_f32_e32 v60, v60, v65
	v_max_f32_e32 v17, v56, v17
	v_max_f32_e32 v56, v64, v58
	v_max_f32_e32 v112, v62, v63
	global_load_dwordx4 v[62:65], v[68:69], off offset:-4096
	v_max_f32_e32 v9, v7, v9
	v_max_f32_e32 v11, v11, v6
	v_min_f32_e32 v113, v9, v11
	v_max_f32_e32 v8, v8, v10
	v_max_f32_e32 v10, v57, v12
	v_min_f32_e32 v58, v112, v113
	v_min_f32_e32 v12, v8, v10
	v_min_f32_e32 v6, v58, v12
	s_movk_i32 s0, 0x5000
	v_min_f32_e32 v111, v59, v60
	v_min_f32_e32 v61, v56, v6
	v_max_f32_e32 v7, v15, v13
	v_max_f32_e32 v13, v14, v16
	v_max_f32_e32 v114, v59, v60
	v_max_f32_e32 v59, v56, v6
	v_add_co_u32_e32 v6, vcc, s0, v66
	v_min_f32_e32 v14, v7, v13
	v_max_f32_e32 v13, v7, v13
	v_addc_co_u32_e32 v7, vcc, 0, v67, vcc
	v_max3_f32 v90, v50, v52, v90
	v_max3_f32 v91, v51, v53, v91
	global_load_dwordx4 v[50:53], v[6:7], off offset:3072
	global_load_dwordx4 v[54:57], v[6:7], off offset:1024
	v_min_f32_e32 v15, v61, v14
	v_min_f32_e32 v116, v59, v13
	v_max_f32_e32 v14, v61, v14
	v_max_f32_e32 v13, v59, v13
	v_max_f32_e32 v12, v58, v12
	global_load_dwordx4 v[58:61], v[6:7], off offset:2048
	v_max_f32_e32 v112, v112, v113
	v_max_f32_e32 v8, v8, v10
	v_min_f32_e32 v10, v112, v8
	v_min_f32_e32 v16, v17, v15
	v_min_f32_e32 v117, v116, v14
	v_max_f32_e32 v15, v17, v15
	v_min_f32_e32 v113, v12, v10
	v_min_f32_e32 v110, v93, v109
	v_min_f32_e32 v17, v117, v15
	v_min_f32_e32 v118, v13, v113
	v_min_f32_e32 v115, v16, v114
	v_max3_f32 v6, v87, v88, v92
	v_max3_f32 v7, v86, v89, v110
	v_max3_f32 v86, v108, v93, v109
	v_max3_f32 v87, v101, v102, v111
	v_max3_f32 v89, v107, v16, v114
	v_max3_f32 v16, v96, v97, v17
	v_max3_f32 v15, v100, v117, v15
	v_max3_f32 v14, v98, v116, v14
	v_max3_f32 v17, v95, v105, v118
	v_max3_f32 v13, v106, v13, v113
	v_max3_f32 v10, v94, v12, v10
	v_max3_f32 v73, v73, v112, v8
	v_max3_f32 v92, v99, v9, v11
	v_max_f32_e32 v93, v90, v16
	v_min_f32_e32 v90, v90, v16
	v_max_f32_e32 v94, v91, v15
	v_min_f32_e32 v91, v91, v15
	v_max_f32_e32 v95, v6, v14
	v_min_f32_e32 v96, v6, v14
	v_max_f32_e32 v97, v7, v17
	v_min_f32_e32 v98, v7, v17
	v_max_f32_e32 v99, v86, v13
	v_min_f32_e32 v86, v86, v13
	v_max_f32_e32 v100, v87, v10
	v_min_f32_e32 v87, v87, v10
	s_waitcnt vmcnt(5)
	v_mfma_f32_32x32x16_bf16 v[2:17], v[2:5], v[30:33], 0
	v_max3_f32 v88, v103, v104, v115
	v_max_f32_e32 v101, v88, v73
	v_min_f32_e32 v73, v88, v73
	v_max_f32_e32 v88, v89, v92
	v_min_f32_e32 v89, v89, v92
	s_movk_i32 s0, 0x7000
	v_max_f32_e32 v92, v93, v99
	s_waitcnt vmcnt(4)
	v_mfma_f32_32x32x16_bf16 v[2:17], v[74:77], v[18:21], v[2:17]
	v_max_f32_e32 v76, v97, v88
	v_min_f32_e32 v77, v97, v88
	v_max_f32_e32 v88, v90, v86
	v_min_f32_e32 v86, v90, v86
	v_max_f32_e32 v90, v91, v87
	v_min_f32_e32 v93, v93, v99
	v_max_f32_e32 v99, v94, v100
	v_mfma_f32_32x32x16_bf16 v[2:17], v[78:81], v[38:41], v[2:17]
	v_max_f32_e32 v80, v98, v89
	v_max_f32_e32 v104, v90, v80
	v_min_f32_e32 v105, v90, v80
	v_add_co_u32_e32 v90, vcc, s0, v66
	v_min_f32_e32 v78, v91, v87
	v_max_f32_e32 v79, v96, v73
	v_mfma_f32_32x32x16_bf16 v[2:17], v[82:85], v[26:29], v[2:17]
	v_min_f32_e32 v73, v96, v73
	v_addc_co_u32_e32 v91, vcc, 0, v67, vcc
	v_min_f32_e32 v81, v98, v89
	v_max_f32_e32 v102, v88, v79
	v_min_f32_e32 v103, v88, v79
	v_max_f32_e32 v106, v86, v73
	v_min_f32_e32 v73, v86, v73
	global_load_dwordx4 v[86:89], v[90:91], off offset:2048
	s_waitcnt vmcnt(4)
; template <int N> __device__ __forceinline__ void bitonic_sort_desc(unsigned (&a)[N]) {
;     ...
;                 if (l > i) { const bool desc = (i & k) == 0; const unsigned mx = kmax(a[i], a[l]), mn = kmin(a[i], a[l]); a[i] = desc ? mx : mn; a[l] = desc ? mn : mx; } }
; }
; template <int N> __device__ __forceinline__ void bitonic_merge_desc(unsigned (&a)[N]) {
; #pragma unroll
;     for (int j = N >> 1; j > 0; j >>= 1)
; #pragma unroll
;         for (int i = 0; i < N; ++i) { const int l = i ^ j;
;             if (l > i) { const unsigned mx = kmax(a[i], a[l]), mn = kmin(a[i], a[l]); a[i] = mx; a[l] = mn; } }
; }
; __device__ __forceinline__ void sort16_desc(unsigned (&a)[16]) {
;     ...
;     PEER_CE(0, 13); PEER_CE(1, 12); PEER_CE(2, 15); PEER_CE(3, 14); PEER_CE(4, 8); PEER_CE(5, 6); PEER_CE(7, 11); PEER_CE(9, 10);
;     PEER_CE(0, 5); PEER_CE(1, 7); PEER_CE(2, 9); PEER_CE(3, 4); PEER_CE(6, 13); PEER_CE(8, 14); PEER_CE(10, 15); PEER_CE(11, 12);
;     PEER_CE(0, 1); PEER_CE(2, 3); PEER_CE(4, 5); PEER_CE(6, 8); PEER_CE(7, 9); PEER_CE(10, 11); PEER_CE(12, 13); PEER_CE(14, 15);
;     PEER_CE(0, 2); PEER_CE(1, 3); PEER_CE(4, 10); PEER_CE(5, 11); PEER_CE(6, 7); PEER_CE(8, 9); PEER_CE(12, 14); PEER_CE(13, 15);
;     PEER_CE(1, 2); PEER_CE(3, 12); PEER_CE(4, 6); PEER_CE(5, 7); PEER_CE(8, 10); PEER_CE(9, 11); PEER_CE(13, 14);
;     PEER_CE(1, 4); PEER_CE(2, 6); PEER_CE(5, 8); PEER_CE(7, 10); PEER_CE(9, 13); PEER_CE(11, 14);
;     PEER_CE(2, 4); PEER_CE(3, 6); PEER_CE(9, 12); PEER_CE(11, 13);
;     PEER_CE(3, 5); PEER_CE(6, 8); PEER_CE(7, 9); PEER_CE(10, 12);
;     PEER_CE(3, 4); PEER_CE(5, 6); PEER_CE(7, 8); PEER_CE(9, 10); PEER_CE(11, 12);
;     PEER_CE(6, 7); PEER_CE(8, 9);
;     ...
; }
; __device__ __forceinline__ void merge_top16(unsigned (&Lst)[16], const unsigned (&S)[16]) {
; #pragma unroll
;     for (int i = 0; i < 16; ++i) Lst[i] = kmax(Lst[i], S[15 - i]);
;     bitonic_merge_desc<16>(Lst);
; }
; __device__ __forceinline__ void topk_p_lds(const bf16* __restrict__ skf, const char* qlds, int r32, int hi, unsigned (&Lst)[16]) {
;     ...
;     for (int kb = 0; kb < 4; ++kb) {
;         bf16x8 a[8];
; #pragma unroll
;         for (int ks = 0; ks < 8; ++ks) a[ks] = *reinterpret_cast<const bf16x8*>(skf + (size_t)((((kb * 8 + ks) * 2 + hi) * 32 + r32) * 8));
;         f32x16 acc = {};
; #pragma unroll
	v_mfma_f32_32x32x16_bf16 v[2:17], v[62:65], v[34:37], v[2:17]
	v_min_f32_e32 v94, v94, v100
	v_max_f32_e32 v74, v95, v101
	v_min_f32_e32 v75, v95, v101
	v_max_f32_e32 v95, v92, v74
	v_min_f32_e32 v96, v92, v74
	v_max_f32_e32 v97, v99, v76
	v_min_f32_e32 v98, v99, v76
	s_waitcnt vmcnt(2)
	v_mfma_f32_32x32x16_bf16 v[2:17], v[54:57], v[22:25], v[2:17]
	v_max_f32_e32 v99, v93, v75
	v_min_f32_e32 v100, v93, v75
	v_max_f32_e32 v101, v94, v77
	v_min_f32_e32 v94, v94, v77
	global_load_dwordx4 v[74:77], v[68:69], off
	v_max_f32_e32 v107, v78, v81
	v_min_f32_e32 v108, v78, v81
	s_waitcnt vmcnt(2)
	v_mfma_f32_32x32x16_bf16 v[2:17], v[58:61], v[46:49], v[2:17]
	global_load_dwordx4 v[54:57], v[90:91], off offset:1024
	s_mov_b32 s0, 0x8000
	v_min_f32_e32 v109, v95, v97
	v_min_f32_e32 v113, v102, v104
	v_min_f32_e32 v112, v100, v94
	v_min_f32_e32 v114, v103, v105
	v_min_f32_e32 v115, v106, v107
	v_mfma_f32_32x32x16_bf16 v[2:17], v[50:53], v[42:45], v[2:17]
	v_min_f32_e32 v116, v73, v108
	v_min_f32_e32 v110, v96, v98
	v_min_f32_e32 v111, v99, v101
	s_nop 8
	v_and_b32_e32 v9, 0xffffff80, v9
	v_and_b32_e32 v13, 0xffffff80, v13
	v_and_b32_e32 v3, 0xffffff80, v3
	v_and_b32_e32 v14, 0xffffff80, v14
	v_and_b32_e32 v7, 0xffffff80, v7
	v_and_b32_e32 v8, 0xffffff80, v8
	v_and_b32_e32 v2, 0xffffff80, v2
	v_and_b32_e32 v15, 0xffffff80, v15
	v_and_b32_e32 v6, 0xffffff80, v6
	v_and_b32_e32 v10, 0xffffff80, v10
	v_and_b32_e32 v5, 0xffffff80, v5
	v_and_b32_e32 v16, 0xffffff80, v16
	v_and_b32_e32 v11, 0xffffff80, v11
	v_and_b32_e32 v12, 0xffffff80, v12
	v_and_b32_e32 v4, 0xffffff80, v4
	v_and_b32_e32 v17, 0xffffff80, v17
	v_or3_b32 v9, v72, v9, s16
	v_or3_b32 v13, v72, v13, s17
	v_or3_b32 v3, v72, v3, s3
	v_or3_b32 v14, v72, v14, s23
	v_or3_b32 v7, v72, v7, s33
	v_or3_b32 v8, v72, v8, s68
	v_or3_b32 v2, v72, v2, 64
	v_or3_b32 v15, v72, v15, s69
	v_or3_b32 v6, v72, v6, s70
	v_or3_b32 v10, v72, v10, s71
	v_or3_b32 v5, v72, v5, s76
	v_or3_b32 v16, v72, v16, s77
	v_or3_b32 v11, v72, v11, s78
	v_or3_b32 v12, v72, v12, s79
	v_or3_b32 v4, v72, v4, s80
	v_or3_b32 v17, v72, v17, s81
	v_max_f32_e32 v13, v13, v13
	v_max_f32_e32 v9, v9, v9
	v_max_f32_e32 v14, v14, v14
	v_max_f32_e32 v3, v3, v3
	v_max_f32_e32 v8, v8, v8
	v_max_f32_e32 v7, v7, v7
	v_max_f32_e32 v15, v15, v15
	v_max_f32_e32 v2, v2, v2
	v_max_f32_e32 v10, v10, v10
	v_max_f32_e32 v6, v6, v6
	v_max_f32_e32 v16, v16, v16
	v_max_f32_e32 v5, v5, v5
	v_max_f32_e32 v12, v12, v12
	v_max_f32_e32 v11, v11, v11
	v_max_f32_e32 v17, v17, v17
	v_max_f32_e32 v4, v4, v4
	v_min_f32_e32 v50, v9, v13
	v_min_f32_e32 v51, v3, v14
	v_min_f32_e32 v53, v7, v8
	v_min_f32_e32 v58, v2, v15
	v_min_f32_e32 v61, v6, v10
	v_min_f32_e32 v62, v5, v16
	v_min_f32_e32 v64, v11, v12
	v_min_f32_e32 v65, v4, v17
	v_max_f32_e32 v3, v3, v14
	v_max_f32_e32 v9, v9, v13
	v_max_f32_e32 v4, v4, v17
	v_max_f32_e32 v11, v11, v12
	v_max_f32_e32 v5, v5, v16
	v_max_f32_e32 v6, v6, v10
	v_max_f32_e32 v2, v2, v15
	v_max_f32_e32 v7, v7, v8
	v_min_f32_e32 v52, v50, v51
	v_min_f32_e32 v59, v53, v58
	v_min_f32_e32 v63, v61, v62
	v_min_f32_e32 v78, v64, v65
	v_max_f32_e32 v53, v53, v58
	v_max_f32_e32 v58, v61, v62
	v_min_f32_e32 v13, v3, v9
	v_min_f32_e32 v12, v4, v11
	v_min_f32_e32 v10, v5, v6
	v_min_f32_e32 v8, v2, v7
	v_max_f32_e32 v16, v64, v65
	v_max_f32_e32 v50, v50, v51
	v_min_f32_e32 v60, v52, v59
	v_min_f32_e32 v79, v63, v78
	v_min_f32_e32 v61, v53, v58
	v_min_f32_e32 v14, v13, v12
	v_min_f32_e32 v15, v10, v8
	v_min_f32_e32 v51, v16, v50
	v_max_f32_e32 v52, v52, v59
	v_max_f32_e32 v59, v63, v78
	v_min_f32_e32 v117, v60, v79
	v_min_f32_e32 v17, v61, v14
	v_min_f32_e32 v62, v15, v51
	v_max_f32_e32 v60, v60, v79
	v_min_f32_e32 v63, v52, v59
	v_min_f32_e32 v64, v17, v62
	v_min_f32_e32 v65, v60, v63
	v_max_f32_e32 v17, v17, v62
	v_max_f32_e32 v60, v60, v63
	v_min_f32_e32 v62, v17, v60
	v_max_f32_e32 v15, v15, v51
	v_max_f32_e32 v51, v53, v58
	v_max_f32_e32 v14, v61, v14
	v_max_f32_e32 v17, v17, v60
	v_max_f32_e32 v4, v4, v11
	v_max_f32_e32 v11, v52, v59
	global_load_dwordx4 v[58:61], v[68:69], off offset:1024
	v_max_f32_e32 v2, v2, v7
	v_max_f32_e32 v3, v3, v9
	v_max_f32_e32 v5, v5, v6
	v_max_f32_e32 v12, v13, v12
	v_max_f32_e32 v8, v10, v8
	v_max_f32_e32 v10, v16, v50
	v_min_f32_e32 v7, v2, v3
	v_min_f32_e32 v6, v4, v5
	v_min_f32_e32 v13, v51, v12
	v_min_f32_e32 v16, v8, v10
	v_min_f32_e32 v9, v7, v6
	v_min_f32_e32 v118, v64, v65
	v_max_f32_e32 v64, v64, v65
	v_min_f32_e32 v53, v15, v13
	v_min_f32_e32 v50, v14, v16
	v_min_f32_e32 v52, v9, v11
	v_min_f32_e32 v119, v64, v62
	v_max_f32_e32 v62, v64, v62
	v_min_f32_e32 v63, v53, v50
	v_min_f32_e32 v64, v17, v52
	v_min_f32_e32 v65, v63, v64
	v_min_f32_e32 v120, v62, v65
	v_max_f32_e32 v121, v62, v65
	v_max_f32_e32 v50, v53, v50
	v_max_f32_e32 v53, v63, v64
	global_load_dwordx4 v[62:65], v[68:69], off offset:2048
	global_load_dwordx4 v[78:81], v[68:69], off offset:3072
	v_max_f32_e32 v17, v17, v52
	v_min_f32_e32 v52, v50, v17
	v_max_f32_e32 v17, v50, v17
	v_add_co_u32_e32 v50, vcc, s0, v66
	v_max_f32_e32 v6, v7, v6
	v_max_f32_e32 v7, v8, v10
	v_max_f32_e32 v8, v51, v12
	v_addc_co_u32_e32 v51, vcc, 0, v67, vcc
	global_load_dwordx4 v[82:85], v[50:51], off offset:-4096
	v_max_f32_e32 v2, v2, v3
	global_load_dwordx4 v[90:93], v[90:91], off offset:3072
	v_max_f32_e32 v3, v4, v5
	v_min_f32_e32 v4, v2, v3
	v_min_f32_e32 v5, v6, v4
	v_min_f32_e32 v10, v7, v8
	v_max_f32_e32 v9, v9, v11
	v_min_f32_e32 v11, v5, v10
	v_max_f32_e32 v13, v15, v13
	v_max_f32_e32 v14, v14, v16
	v_min_f32_e32 v12, v9, v11
	v_min_f32_e32 v15, v13, v14
	v_max_f32_e32 v9, v9, v11
	v_max_f32_e32 v11, v13, v14
	v_min_f32_e32 v16, v12, v15
	v_min_f32_e32 v13, v9, v11
	v_max_f32_e32 v12, v12, v15
	v_max_f32_e32 v4, v6, v4
	v_max_f32_e32 v6, v7, v8
	v_min_f32_e32 v14, v13, v12
	v_max_f32_e32 v15, v17, v16
	v_max_f32_e32 v5, v5, v10
	v_min_f32_e32 v7, v4, v6
	v_min_f32_e32 v122, v52, v53
	v_min_f32_e32 v68, v17, v16
	v_max_f32_e32 v52, v52, v53
	v_min_f32_e32 v16, v14, v15
	v_max_f32_e32 v12, v13, v12
	v_max_f32_e32 v9, v9, v11
	v_min_f32_e32 v8, v5, v7
	v_min_f32_e32 v53, v68, v52
	v_min_f32_e32 v10, v9, v8
	v_max_f32_e32 v8, v9, v8
	v_max_f32_e32 v4, v4, v6
	v_max3_f32 v6, v95, v97, v117
	v_max_f32_e32 v9, v109, v118
	v_max3_f32 v11, v96, v98, v119
	v_max3_f32 v13, v102, v104, v16
	v_max3_f32 v14, v113, v14, v15
	v_max3_f32 v12, v103, v105, v12
	v_max3_f32 v95, v99, v101, v121
	v_max3_f32 v53, v100, v94, v53
	v_max3_f32 v52, v112, v68, v52
	v_max_f32_e32 v68, v114, v10
	v_max3_f32 v94, v106, v107, v8
	v_max3_f32 v97, v115, v5, v7
	v_max3_f32 v73, v73, v108, v4
	v_max3_f32 v98, v116, v2, v3
	v_max_f32_e32 v99, v6, v13
	v_min_f32_e32 v100, v6, v13
	v_max_f32_e32 v101, v9, v14
	v_min_f32_e32 v102, v9, v14
	v_max_f32_e32 v103, v11, v12
	v_min_f32_e32 v104, v11, v12
	s_waitcnt vmcnt(6)
; template <int N> __device__ __forceinline__ void bitonic_sort_desc(unsigned (&a)[N]) {
;     ...
;                 if (l > i) { const bool desc = (i & k) == 0; const unsigned mx = kmax(a[i], a[l]), mn = kmin(a[i], a[l]); a[i] = desc ? mx : mn; a[l] = desc ? mn : mx; } }
; }
; template <int N> __device__ __forceinline__ void bitonic_merge_desc(unsigned (&a)[N]) {
; #pragma unroll
;     for (int j = N >> 1; j > 0; j >>= 1)
; #pragma unroll
;         for (int i = 0; i < N; ++i) { const int l = i ^ j;
;             if (l > i) { const unsigned mx = kmax(a[i], a[l]), mn = kmin(a[i], a[l]); a[i] = mx; a[l] = mn; } }
; }
; __device__ __forceinline__ void sort16_desc(unsigned (&a)[16]) {
;     ...
;     PEER_CE(0, 13); PEER_CE(1, 12); PEER_CE(2, 15); PEER_CE(3, 14); PEER_CE(4, 8); PEER_CE(5, 6); PEER_CE(7, 11); PEER_CE(9, 10);
;     PEER_CE(0, 5); PEER_CE(1, 7); PEER_CE(2, 9); PEER_CE(3, 4); PEER_CE(6, 13); PEER_CE(8, 14); PEER_CE(10, 15); PEER_CE(11, 12);
;     PEER_CE(0, 1); PEER_CE(2, 3); PEER_CE(4, 5); PEER_CE(6, 8); PEER_CE(7, 9); PEER_CE(10, 11); PEER_CE(12, 13); PEER_CE(14, 15);
;     PEER_CE(0, 2); PEER_CE(1, 3); PEER_CE(4, 10); PEER_CE(5, 11); PEER_CE(6, 7); PEER_CE(8, 9); PEER_CE(12, 14); PEER_CE(13, 15);
;     PEER_CE(1, 2); PEER_CE(3, 12); PEER_CE(4, 6); PEER_CE(5, 7); PEER_CE(8, 10); PEER_CE(9, 11); PEER_CE(13, 14);
;     PEER_CE(1, 4); PEER_CE(2, 6); PEER_CE(5, 8); PEER_CE(7, 10); PEER_CE(9, 13); PEER_CE(11, 14);
;     PEER_CE(2, 4); PEER_CE(3, 6); PEER_CE(9, 12); PEER_CE(11, 13);
;     PEER_CE(3, 5); PEER_CE(6, 8); PEER_CE(7, 9); PEER_CE(10, 12);
;     PEER_CE(3, 4); PEER_CE(5, 6); PEER_CE(7, 8); PEER_CE(9, 10); PEER_CE(11, 12);
;     PEER_CE(6, 7); PEER_CE(8, 9);
;     ...
; }
; __device__ __forceinline__ void merge_top16(unsigned (&Lst)[16], const unsigned (&S)[16]) {
; #pragma unroll
;     for (int i = 0; i < 16; ++i) Lst[i] = kmax(Lst[i], S[15 - i]);
;     bitonic_merge_desc<16>(Lst);
; }
; __device__ __forceinline__ void topk_p_lds(const bf16* __restrict__ skf, const char* qlds, int r32, int hi, unsigned (&Lst)[16]) {
;     ...
;     for (int kb = 0; kb < 4; ++kb) {
;         bf16x8 a[8];
; #pragma unroll
;         for (int ks = 0; ks < 8; ++ks) a[ks] = *reinterpret_cast<const bf16x8*>(skf + (size_t)((((kb * 8 + ks) * 2 + hi) * 32 + r32) * 8));
;         f32x16 acc = {};
; #pragma unroll
	v_mfma_f32_32x32x16_bf16 v[2:17], v[74:77], v[30:33], 0
	v_max_f32_e32 v69, v110, v120
	v_max_f32_e32 v105, v69, v68
	v_min_f32_e32 v30, v69, v68
	v_max_f32_e32 v31, v95, v94
	v_max_f32_e32 v69, v53, v73
	v_min_f32_e32 v53, v53, v73
	v_max_f32_e32 v96, v111, v122
	s_waitcnt vmcnt(4)
	v_mfma_f32_32x32x16_bf16 v[2:17], v[58:61], v[18:21], v[2:17]
	v_max_f32_e32 v18, v52, v98
	v_min_f32_e32 v19, v52, v98
	v_max_f32_e32 v20, v99, v31
	v_max_f32_e32 v52, v103, v69
	v_min_f32_e32 v32, v95, v94
	v_min_f32_e32 v68, v96, v97
	v_min_f32_e32 v58, v102, v68
	s_waitcnt vmcnt(3)
	v_mfma_f32_32x32x16_bf16 v[2:17], v[62:65], v[38:41], v[2:17]
	v_max_f32_e32 v40, v100, v32
	v_min_f32_e32 v32, v100, v32
	v_max_f32_e32 v33, v96, v97
	v_min_f32_e32 v21, v99, v31
	v_max_f32_e32 v31, v101, v33
	v_min_f32_e32 v33, v101, v33
	v_min_f32_e32 v38, v103, v69
	s_waitcnt vmcnt(2)
	v_mfma_f32_32x32x16_bf16 v[2:17], v[78:81], v[26:29], v[2:17]
	v_max_f32_e32 v29, v20, v52
	v_min_f32_e32 v20, v20, v52
	v_max_f32_e32 v26, v104, v53
	v_min_f32_e32 v27, v104, v53
	v_max_f32_e32 v28, v30, v19
	v_min_f32_e32 v19, v30, v19
	v_max_f32_e32 v39, v105, v18
	s_waitcnt vmcnt(1)
	v_mfma_f32_32x32x16_bf16 v[2:17], v[82:85], v[34:37], v[2:17]
	v_min_f32_e32 v18, v105, v18
	v_max_f32_e32 v41, v102, v68
	v_max_f32_e32 v30, v31, v39
	v_min_f32_e32 v31, v31, v39
	v_max_f32_e32 v34, v21, v38
	v_min_f32_e32 v21, v21, v38
	v_max_f32_e32 v35, v33, v18
	v_mfma_f32_32x32x16_bf16 v[2:17], v[54:57], v[22:25], v[2:17]
	v_max_f32_e32 v24, v32, v27
	v_min_f32_e32 v25, v32, v27
	v_max_f32_e32 v27, v58, v19
	v_min_f32_e32 v19, v58, v19
	v_min_f32_e32 v18, v33, v18
	v_max_f32_e32 v33, v40, v26
	v_min_f32_e32 v26, v40, v26
	v_mfma_f32_32x32x16_bf16 v[2:17], v[86:89], v[46:49], v[2:17]
	v_max_f32_e32 v22, v41, v28
	v_min_f32_e32 v23, v41, v28
	v_min_f32_e32 v28, v29, v30
	v_min_f32_e32 v32, v20, v31
	v_min_f32_e32 v36, v34, v35
	v_min_f32_e32 v37, v21, v18
	v_min_f32_e32 v38, v33, v22
	s_waitcnt vmcnt(0)
	v_mfma_f32_32x32x16_bf16 v[2:17], v[90:93], v[42:45], v[2:17]
	v_min_f32_e32 v39, v26, v23
	v_min_f32_e32 v40, v24, v27
	v_min_f32_e32 v41, v25, v19
	v_cmp_gt_u32_e32 vcc, 32, v70
	s_mov_b64 s[0:1], 0x8000
	s_nop 6
	v_and_b32_e32 v5, 0xffffff80, v5
	v_and_b32_e32 v16, 0xffffff80, v16
	v_and_b32_e32 v6, 0xffffff80, v6
	v_and_b32_e32 v10, 0xffffff80, v10
	v_and_b32_e32 v2, 0xffffff80, v2
	v_and_b32_e32 v15, 0xffffff80, v15
	v_and_b32_e32 v7, 0xffffff80, v7
	v_and_b32_e32 v8, 0xffffff80, v8
	v_and_b32_e32 v11, 0xffffff80, v11
	v_and_b32_e32 v12, 0xffffff80, v12
	v_and_b32_e32 v4, 0xffffff80, v4
	v_and_b32_e32 v17, 0xffffff80, v17
	v_and_b32_e32 v9, 0xffffff80, v9
	v_and_b32_e32 v13, 0xffffff80, v13
	v_and_b32_e32 v3, 0xffffff80, v3
	v_and_b32_e32 v14, 0xffffff80, v14
	v_or3_b32 v5, v72, v5, s82
	v_or3_b32 v16, v72, v16, s83
	v_or3_b32 v6, v72, v6, s84
	v_or3_b32 v10, v72, v10, s85
	v_or3_b32 v2, v72, v2, s86
	v_or3_b32 v15, v72, v15, s87
	v_or3_b32 v7, v72, v7, s88
	v_or3_b32 v8, v72, v8, s89
	v_or3_b32 v11, v72, v11, s90
	v_or3_b32 v12, v72, v12, s91
	v_or3_b32 v4, v72, v4, s92
	v_or3_b32 v17, v72, v17, s93
	v_or3_b32 v9, v72, v9, s94
	v_or3_b32 v13, v72, v13, s95
	v_or3_b32 v3, v72, v3, s96
	v_or3_b32 v14, v72, v14, s97
	v_max_f32_e32 v16, v16, v16
	v_max_f32_e32 v5, v5, v5
	v_max_f32_e32 v10, v10, v10
	v_max_f32_e32 v6, v6, v6
	v_max_f32_e32 v15, v15, v15
	v_max_f32_e32 v2, v2, v2
	v_max_f32_e32 v8, v8, v8
	v_max_f32_e32 v7, v7, v7
	v_max_f32_e32 v12, v12, v12
	v_max_f32_e32 v11, v11, v11
	v_max_f32_e32 v17, v17, v17
	v_max_f32_e32 v4, v4, v4
	v_max_f32_e32 v13, v13, v13
	v_max_f32_e32 v9, v9, v9
	v_max_f32_e32 v14, v14, v14
	v_max_f32_e32 v3, v3, v3
	v_max_f32_e32 v42, v5, v16
	v_max_f32_e32 v43, v6, v10
	v_max_f32_e32 v45, v2, v15
	v_max_f32_e32 v46, v7, v8
	v_min_f32_e32 v49, v11, v12
	v_min_f32_e32 v52, v4, v17
	v_min_f32_e32 v54, v9, v13
	v_min_f32_e32 v55, v3, v14
	v_min_f32_e32 v7, v7, v8
	v_min_f32_e32 v2, v2, v15
	v_min_f32_e32 v6, v6, v10
	v_min_f32_e32 v5, v5, v16
	v_max_f32_e32 v3, v3, v14
	v_max_f32_e32 v9, v9, v13
	v_max_f32_e32 v4, v4, v17
	v_max_f32_e32 v11, v11, v12
	v_min_f32_e32 v44, v42, v43
	v_min_f32_e32 v47, v45, v46
	v_max_f32_e32 v53, v49, v52
	v_max_f32_e32 v56, v54, v55
	v_max_f32_e32 v8, v7, v2
	v_max_f32_e32 v10, v6, v5
	v_min_f32_e32 v13, v3, v9
	v_min_f32_e32 v12, v4, v11
	v_min_f32_e32 v54, v54, v55
	v_min_f32_e32 v2, v7, v2
	v_min_f32_e32 v5, v6, v5
	v_min_f32_e32 v6, v49, v52
	v_max_f32_e32 v45, v45, v46
	v_max_f32_e32 v3, v3, v9
	v_max_f32_e32 v4, v4, v11
	v_max_f32_e32 v11, v42, v43
	v_min_f32_e32 v48, v44, v47
	v_min_f32_e32 v57, v53, v56
	v_max_f32_e32 v15, v8, v10
	v_max_f32_e32 v14, v13, v12
	v_min_f32_e32 v8, v8, v10
	v_min_f32_e32 v10, v13, v12
	v_max_f32_e32 v13, v44, v47
	v_max_f32_e32 v44, v53, v56
	v_min_f32_e32 v7, v54, v2
	v_min_f32_e32 v49, v5, v6
	v_max_f32_e32 v2, v54, v2
	v_max_f32_e32 v5, v5, v6
	v_min_f32_e32 v9, v45, v3
	v_min_f32_e32 v42, v4, v11
	v_max_f32_e32 v3, v45, v3
	v_max_f32_e32 v4, v4, v11
	v_min_f32_e32 v16, v15, v14
	v_max_f32_e32 v12, v8, v10
	v_min_f32_e32 v47, v13, v44
	v_min_f32_e32 v8, v8, v10
	v_min_f32_e32 v10, v48, v57
	v_max_f32_e32 v52, v7, v49
	v_min_f32_e32 v6, v2, v5
	v_min_f32_e32 v43, v9, v42
	v_max_f32_e32 v9, v9, v42
	v_min_f32_e32 v11, v3, v4
	v_max_f32_e32 v13, v13, v44
	v_max_f32_e32 v14, v15, v14
	v_max_f32_e32 v58, v48, v57
	v_max_f32_e32 v48, v8, v10
	v_max_f32_e32 v54, v52, v6
	v_max_f32_e32 v2, v2, v5
	v_min_f32_e32 v42, v9, v11
	v_min_f32_e32 v15, v13, v14
	v_min_f32_e32 v17, v58, v16
	v_min_f32_e32 v53, v12, v47
	v_max_f32_e32 v55, v48, v54
	v_min_f32_e32 v5, v43, v2
	v_max_f32_e32 v2, v43, v2
; __device__ __forceinline__ unsigned kmax(unsigned a, unsigned b) { return __float_as_uint(__builtin_fmaxf(__uint_as_float(a), __uint_as_float(b))); }
; __device__ __forceinline__ void merge_top16(unsigned (&Lst)[16], const unsigned (&S)[16]) {
; #pragma unroll
;     for (int i = 0; i < 16; ++i) Lst[i] = kmax(Lst[i], S[15 - i]);
;     bitonic_merge_desc<16>(Lst);
; }
; __device__ __forceinline__ void topk_p_lds(const bf16* __restrict__ skf, const char* qlds, int r32, int hi, unsigned (&Lst)[16]) {
;     ...
;     unsigned Y[16];
; #pragma unroll
;     for (int s = 0; s < 16; ++s) { auto rr = __builtin_amdgcn_permlane32_swap(Lst[s], Lst[s], false, false); Y[s] = hi ? rr[0] : rr[1]; }
;     merge_top16(Lst, Y);
	v_min_f32_e32 v43, v42, v15
	v_max_f32_e32 v16, v58, v16
	v_max_f32_e32 v12, v12, v47
	v_max_f32_e32 v56, v17, v53
	v_max_f32_e32 v46, v55, v5
	v_min_f32_e32 v44, v2, v43
	v_min_f32_e32 v45, v16, v12
	v_min_f32_e32 v17, v17, v53
	v_min_f32_e32 v5, v55, v5
	v_max_f32_e32 v2, v2, v43
	v_max_f32_e32 v12, v16, v12
	v_min_f32_e32 v8, v8, v10
	v_min_f32_e32 v6, v52, v6
	v_max_f32_e32 v9, v9, v11
	v_max_f32_e32 v11, v13, v14
	v_max_f32_e32 v57, v56, v46
	v_min_f32_e32 v47, v44, v45
	v_min_f32_e32 v46, v56, v46
	v_max_f32_e32 v53, v17, v5
	v_min_f32_e32 v16, v2, v12
	v_max_f32_e32 v43, v44, v45
	v_max_f32_e32 v10, v8, v6
	v_min_f32_e32 v48, v48, v54
	v_max_f32_e32 v2, v2, v12
	v_max_f32_e32 v12, v42, v15
	v_min_f32_e32 v13, v9, v11
	v_min_f32_e32 v58, v57, v47
	v_max_f32_e32 v55, v46, v53
	v_min_f32_e32 v44, v16, v43
	v_max_f32_e32 v45, v57, v47
	v_max_f32_e32 v52, v10, v48
	v_min_f32_e32 v5, v17, v5
	v_min_f32_e32 v14, v12, v13
	v_min_f32_e32 v56, v58, v55
	v_min_f32_e32 v47, v44, v45
	v_min_f32_e32 v17, v52, v5
	v_max_f32_e32 v5, v52, v5
	v_min_f32_e32 v46, v46, v53
	v_max_f32_e32 v16, v16, v43
	v_min_f32_e32 v15, v2, v14
	v_max_f32_e32 v2, v2, v14
	v_min_f32_e32 v10, v10, v48
	v_min_f32_e32 v6, v8, v6
	v_max_f32_e32 v8, v9, v11
	v_min_f32_e32 v7, v7, v49
	v_max3_f32 v7, v29, v30, v7
	v_max_f32_e32 v6, v28, v6
	v_max3_f32 v9, v20, v31, v10
	v_max_f32_e32 v10, v32, v17
	v_max3_f32 v5, v34, v35, v5
	v_max_f32_e32 v11, v36, v46
	v_max3_f32 v14, v21, v18, v56
	v_max3_f32 v17, v37, v58, v55
	v_max3_f32 v18, v33, v22, v47
	v_max3_f32 v20, v38, v44, v45
	v_max3_f32 v16, v26, v23, v16
	v_max_f32_e32 v15, v39, v15
	v_max3_f32 v2, v24, v27, v2
	v_max3_f32 v12, v40, v12, v13
	v_max3_f32 v8, v25, v19, v8
	v_max3_f32 v3, v41, v3, v4
	v_max_f32_e32 v4, v7, v18
	v_min_f32_e32 v7, v7, v18
	v_max_f32_e32 v13, v6, v20
	v_max_f32_e32 v18, v9, v16
	v_min_f32_e32 v9, v9, v16
	v_max_f32_e32 v16, v10, v15
	v_min_f32_e32 v10, v10, v15
	v_max_f32_e32 v15, v5, v2
	v_min_f32_e32 v2, v5, v2
	v_max_f32_e32 v5, v11, v12
	v_min_f32_e32 v11, v11, v12
	v_max_f32_e32 v12, v14, v8
	v_min_f32_e32 v8, v14, v8
	v_max_f32_e32 v14, v17, v3
	v_min_f32_e32 v6, v6, v20
	v_min_f32_e32 v3, v17, v3
	v_max_f32_e32 v17, v4, v15
	v_min_f32_e32 v4, v4, v15
	v_max_f32_e32 v15, v13, v5
	v_min_f32_e32 v5, v13, v5
	v_max_f32_e32 v13, v18, v12
	v_min_f32_e32 v12, v18, v12
	v_max_f32_e32 v18, v16, v14
	v_min_f32_e32 v14, v16, v14
	v_max_f32_e32 v16, v7, v2
	v_min_f32_e32 v2, v7, v2
	v_max_f32_e32 v7, v6, v11
	v_min_f32_e32 v6, v6, v11
	v_max_f32_e32 v11, v9, v8
	v_min_f32_e32 v8, v9, v8
	v_max_f32_e32 v9, v10, v3
	v_min_f32_e32 v3, v10, v3
	v_max_f32_e32 v10, v17, v13
	v_min_f32_e32 v13, v17, v13
	v_max_f32_e32 v17, v15, v18
	v_min_f32_e32 v15, v15, v18
	v_max_f32_e32 v18, v4, v12
	v_min_f32_e32 v4, v4, v12
	v_max_f32_e32 v12, v5, v14
	v_min_f32_e32 v5, v5, v14
	v_max_f32_e32 v14, v16, v11
	v_min_f32_e32 v11, v16, v11
	v_max_f32_e32 v16, v7, v9
	v_min_f32_e32 v7, v7, v9
	v_max_f32_e32 v9, v2, v8
	v_min_f32_e32 v2, v2, v8
	v_max_f32_e32 v8, v6, v3
	v_min_f32_e32 v3, v6, v3
	v_max_f32_e32 v26, v10, v17
	v_max_f32_e32 v33, v9, v8
	v_min_f32_e32 v8, v9, v8
	v_max_f32_e32 v9, v2, v3
	v_min_f32_e32 v34, v2, v3
	v_mov_b32_e32 v2, v26
	v_mov_b32_e32 v3, v26
	v_min_f32_e32 v10, v10, v17
	s_nop 0
	v_permlane32_swap_b32_e32 v2, v3
	v_cndmask_b32_e32 v35, v2, v3, vcc
	v_mov_b32_e32 v2, v10
	v_mov_b32_e32 v3, v10
	v_max_f32_e32 v17, v13, v15
	s_nop 0
	v_permlane32_swap_b32_e32 v2, v3
	v_cndmask_b32_e32 v36, v2, v3, vcc
	v_mov_b32_e32 v2, v17
	v_mov_b32_e32 v3, v17
	v_min_f32_e32 v13, v13, v15
	s_nop 0
	v_permlane32_swap_b32_e32 v2, v3
	v_cndmask_b32_e32 v37, v2, v3, vcc
	v_mov_b32_e32 v2, v13
	v_mov_b32_e32 v3, v13
	v_max_f32_e32 v15, v18, v12
	s_nop 0
	v_permlane32_swap_b32_e32 v2, v3
	v_cndmask_b32_e32 v38, v2, v3, vcc
	v_mov_b32_e32 v2, v15
	v_mov_b32_e32 v3, v15
	v_min_f32_e32 v12, v18, v12
	s_nop 0
	v_permlane32_swap_b32_e32 v2, v3
	v_cndmask_b32_e32 v39, v2, v3, vcc
	v_mov_b32_e32 v2, v12
	v_mov_b32_e32 v3, v12
	v_max_f32_e32 v30, v4, v5
	s_nop 0
	v_permlane32_swap_b32_e32 v2, v3
	v_cndmask_b32_e32 v40, v2, v3, vcc
	v_mov_b32_e32 v2, v30
	v_mov_b32_e32 v3, v30
	v_min_f32_e32 v31, v4, v5
	s_nop 0
	v_permlane32_swap_b32_e32 v2, v3
	v_cndmask_b32_e32 v41, v2, v3, vcc
	v_mov_b32_e32 v2, v31
	v_mov_b32_e32 v3, v31
	v_max_f32_e32 v32, v14, v16
	s_nop 0
	v_permlane32_swap_b32_e32 v2, v3
	v_cndmask_b32_e32 v46, v2, v3, vcc
	v_mov_b32_e32 v2, v32
	v_mov_b32_e32 v3, v32
	v_min_f32_e32 v14, v14, v16
	s_nop 0
	v_permlane32_swap_b32_e32 v2, v3
	v_cndmask_b32_e32 v47, v2, v3, vcc
	v_mov_b32_e32 v2, v14
	v_mov_b32_e32 v3, v14
	v_max_f32_e32 v16, v11, v7
	s_nop 0
	v_permlane32_swap_b32_e32 v2, v3
	v_cndmask_b32_e32 v48, v2, v3, vcc
	v_mov_b32_e32 v2, v16
	v_mov_b32_e32 v3, v16
	v_min_f32_e32 v11, v11, v7
	s_nop 0
	v_permlane32_swap_b32_e32 v2, v3
	v_cndmask_b32_e32 v42, v2, v3, vcc
	v_mov_b32_e32 v2, v11
	v_mov_b32_e32 v3, v11
	s_nop 1
	v_permlane32_swap_b32_e32 v2, v3
	v_cndmask_b32_e32 v43, v2, v3, vcc
	v_mov_b32_e32 v2, v33
	v_mov_b32_e32 v3, v33
	s_nop 1
	v_permlane32_swap_b32_e32 v2, v3
	v_cndmask_b32_e32 v27, v2, v3, vcc
	global_load_dwordx4 v[2:5], v[50:51], off
	v_mov_b32_e32 v6, v8
	v_mov_b32_e32 v7, v8
	s_nop 1
	v_permlane32_swap_b32_e32 v6, v7
	v_cndmask_b32_e32 v28, v6, v7, vcc
	v_lshl_add_u64 v[6:7], v[66:67], 0, s[0:1]
	global_load_dwordx4 v[18:21], v[6:7], off offset:1024
	v_mov_b32_e32 v22, v9
	v_mov_b32_e32 v23, v9
	s_nop 1
	v_permlane32_swap_b32_e32 v22, v23
	v_cndmask_b32_e32 v29, v22, v23, vcc
	v_mov_b32_e32 v22, v34
	v_mov_b32_e32 v23, v34
	s_nop 1
	v_permlane32_swap_b32_e32 v22, v23
; __device__ __forceinline__ void topk_p_lds(const bf16* __restrict__ skf, const char* qlds, int r32, int hi, unsigned (&Lst)[16]) {
;     bf16x8 bq[8];
; #pragma unroll
;     for (int ks = 0; ks < 8; ++ks) bq[ks] = *reinterpret_cast<const bf16x8*>(qlds + ((2 * ks + hi) * 32 + r32) * 16);
; #pragma unroll
;     for (int kb = 0; kb < 4; ++kb) {
;         bf16x8 a[8];
; #pragma unroll
;         for (int ks = 0; ks < 8; ++ks) a[ks] = *reinterpret_cast<const bf16x8*>(skf + (size_t)((((kb * 8 + ks) * 2 + hi) * 32 + r32) * 8));
;         f32x16 acc = {};
; #pragma unroll
;         for (int ks = 0; ks < 8; ++ks) acc = __builtin_amdgcn_mfma_f32_32x32x16_bf16(a[ks], bq[ks], acc, 0, 0, 0);
;     ...
;     unsigned Y[16];
; #pragma unroll
;     for (int s = 0; s < 16; ++s) { auto rr = __builtin_amdgcn_permlane32_swap(Lst[s], Lst[s], false, false); Y[s] = hi ? rr[0] : rr[1]; }
;     merge_top16(Lst, Y);
; }
; __device__ __forceinline__ void select_wave_lds(const bf16* __restrict__ skf_h, char* qtile, int h, int* __restrict__ pidx, float* __restrict__ pgate, int wid, int lane) {
;     const int r32 = lane & 31, hi = lane >> 5;
;     unsigned T0[16], T1[16];
;     topk_p_lds(skf_h, qtile + (wid * 2 + 0) * 8192, r32, hi, T0);
;     topk_p_lds(skf_h + 4 * 8 * 2 * 32 * 8, qtile + (wid * 2 + 1) * 8192, r32, hi, T1);
	v_cndmask_b32_e32 v22, v22, v23, vcc
	v_max_f32_e32 v44, v22, v22
	global_load_dwordx4 v[22:25], v[6:7], off offset:2048
	v_max_f32_e32 v49, v26, v44
	v_max_f32_e32 v26, v29, v29
	v_max_f32_e32 v10, v10, v26
	v_max_f32_e32 v26, v28, v28
	v_max_f32_e32 v17, v17, v26
	v_max_f32_e32 v26, v27, v27
	v_max_f32_e32 v13, v13, v26
	global_load_dwordx4 v[26:29], v[6:7], off offset:3072
	s_mov_b32 s0, 0xa000
	v_add_co_u32_e64 v50, s[0:1], s0, v66
	v_max_f32_e32 v6, v43, v43
	s_nop 0
	v_addc_co_u32_e64 v51, s[0:1], 0, v67, s[0:1]
	v_max_f32_e32 v15, v15, v6
	v_max_f32_e32 v6, v42, v42
	global_load_dwordx4 v[42:45], v[50:51], off offset:-4096
	v_max_f32_e32 v12, v12, v6
	v_max_f32_e32 v6, v48, v48
	s_mov_b32 s0, 0x9000
	v_max_f32_e32 v30, v30, v6
	v_add_co_u32_e64 v6, s[0:1], s0, v66
	v_max_f32_e32 v46, v46, v46
	s_nop 0
	v_addc_co_u32_e64 v7, s[0:1], 0, v67, s[0:1]
	global_load_dwordx4 v[52:55], v[6:7], off offset:1024
	global_load_dwordx4 v[56:59], v[6:7], off offset:2048
	global_load_dwordx4 v[60:63], v[6:7], off offset:3072
	v_max_f32_e32 v47, v47, v47
	v_max_f32_e32 v32, v32, v46
	v_max_f32_e32 v6, v36, v36
	v_max_f32_e32 v7, v35, v35
	v_max_f32_e32 v31, v31, v47
	v_max_f32_e32 v6, v9, v6
	v_max_f32_e32 v7, v34, v7
	v_max_f32_e32 v9, v49, v32
	v_min_f32_e32 v34, v49, v32
	ds_read_b128 v[46:49], v71 offset:8192
	v_max_f32_e32 v41, v41, v41
	v_max_f32_e32 v39, v39, v39
	v_max_f32_e32 v38, v38, v38
	v_max_f32_e32 v37, v37, v37
	v_max_f32_e32 v14, v14, v41
	v_max_f32_e32 v40, v40, v40
	v_max_f32_e32 v11, v11, v39
	v_max_f32_e32 v33, v33, v38
	v_max_f32_e32 v8, v8, v37
	v_max_f32_e32 v16, v16, v40
	v_max_f32_e32 v32, v10, v14
	v_min_f32_e32 v35, v10, v14
	v_max_f32_e32 v38, v13, v11
	v_min_f32_e32 v39, v13, v11
	v_max_f32_e32 v10, v15, v33
	v_max_f32_e32 v11, v12, v8
	v_max_f32_e32 v36, v17, v16
	v_min_f32_e32 v37, v17, v16
	v_min_f32_e32 v40, v15, v33
	v_min_f32_e32 v41, v12, v8
	v_max_f32_e32 v64, v30, v6
	v_min_f32_e32 v65, v30, v6
	v_max_f32_e32 v68, v31, v7
	v_min_f32_e32 v69, v31, v7
	v_max_f32_e32 v73, v9, v10
	v_min_f32_e32 v74, v9, v10
	v_max_f32_e32 v75, v32, v11
	v_min_f32_e32 v76, v32, v11
	ds_read_b128 v[30:33], v71 offset:9216
	s_waitcnt vmcnt(7) lgkmcnt(1)
	v_mfma_f32_32x32x16_bf16 v[2:17], v[2:5], v[46:49], 0
	v_max_f32_e32 v77, v36, v64
	v_min_f32_e32 v64, v36, v64
	v_max_f32_e32 v78, v38, v68
	v_min_f32_e32 v38, v38, v68
	v_max_f32_e32 v68, v34, v40
	v_min_f32_e32 v79, v34, v40
	v_max_f32_e32 v80, v35, v41
	s_waitcnt vmcnt(6) lgkmcnt(0)
	v_mfma_f32_32x32x16_bf16 v[2:17], v[18:21], v[30:33], v[2:17]
	v_min_f32_e32 v81, v35, v41
	v_max_f32_e32 v40, v37, v65
	v_min_f32_e32 v65, v37, v65
	ds_read_b128 v[34:37], v71 offset:10240
	ds_read_b128 v[18:21], v71 offset:11264
	v_max_f32_e32 v82, v39, v69
	v_min_f32_e32 v69, v39, v69
	s_waitcnt vmcnt(5) lgkmcnt(1)
	v_mfma_f32_32x32x16_bf16 v[2:17], v[22:25], v[34:37], v[2:17]
	v_max_f32_e32 v85, v76, v38
	v_min_f32_e32 v87, v76, v38
	v_max_f32_e32 v89, v68, v40
	v_min_f32_e32 v68, v68, v40
	ds_read_b128 v[38:41], v71 offset:12288
	ds_read_b128 v[22:25], v71 offset:13312
	v_max_f32_e32 v83, v73, v77
	s_waitcnt vmcnt(4) lgkmcnt(2)
	v_mfma_f32_32x32x16_bf16 v[2:17], v[26:29], v[18:21], v[2:17]
	ds_read_b128 v[26:29], v71 offset:15360
	v_max_f32_e32 v84, v75, v78
	v_max_f32_e32 v90, v80, v82
	v_min_f32_e32 v82, v80, v82
	v_max_f32_e32 v91, v79, v65
	v_max_f32_e32 v92, v81, v69
	v_min_f32_e32 v77, v73, v77
	s_waitcnt vmcnt(3) lgkmcnt(2)
	v_mfma_f32_32x32x16_bf16 v[2:17], v[42:45], v[38:41], v[2:17]
	ds_read_b128 v[42:45], v71 offset:14336
	v_min_f32_e32 v75, v75, v78
	v_max_f32_e32 v78, v74, v64
	v_min_f32_e32 v64, v74, v64
	v_min_f32_e32 v65, v79, v65
	v_min_f32_e32 v69, v81, v69
	v_max_f32_e32 v73, v83, v84
	s_waitcnt vmcnt(2) lgkmcnt(2)
	v_mfma_f32_32x32x16_bf16 v[2:17], v[52:55], v[22:25], v[2:17]
	v_min_f32_e32 v74, v83, v84
	v_max_f32_e32 v79, v68, v82
	v_min_f32_e32 v81, v68, v82
	v_max_f32_e32 v82, v91, v92
	v_min_f32_e32 v83, v91, v92
	global_load_dwordx4 v[92:95], v[50:51], off offset:1024
	global_load_dwordx4 v[96:99], v[50:51], off offset:2048
	global_load_dwordx4 v[100:103], v[50:51], off offset:3072
	s_waitcnt vmcnt(4) lgkmcnt(0)
	v_mfma_f32_32x32x16_bf16 v[2:17], v[56:59], v[42:45], v[2:17]
	s_mov_b32 s0, 0xc000
	v_add_co_u32_e64 v68, s[0:1], s0, v66
	v_max_f32_e32 v76, v77, v75
	v_min_f32_e32 v80, v77, v75
	v_max_f32_e32 v84, v78, v85
	v_min_f32_e32 v86, v78, v85
	s_waitcnt vmcnt(3)
; __device__ __forceinline__ int crow(int r, int hi) { return (r & 3) + 8 * (r >> 2) + 4 * hi; }
; #define PEER_CE(i, j) do { const unsigned mx_ = kmax(a[i], a[j]), mn_ = kmin(a[i], a[j]); a[i] = mx_; a[j] = mn_; } while (0)
; __device__ __forceinline__ void sort16_desc(unsigned (&a)[16]) {
;     ...
;     PEER_CE(0, 13); PEER_CE(1, 12); PEER_CE(2, 15); PEER_CE(3, 14); PEER_CE(4, 8); PEER_CE(5, 6); PEER_CE(7, 11); PEER_CE(9, 10);
;     PEER_CE(0, 5); PEER_CE(1, 7); PEER_CE(2, 9); PEER_CE(3, 4); PEER_CE(6, 13); PEER_CE(8, 14); PEER_CE(10, 15); PEER_CE(11, 12);
;     PEER_CE(0, 1); PEER_CE(2, 3); PEER_CE(4, 5); PEER_CE(6, 8); PEER_CE(7, 9); PEER_CE(10, 11); PEER_CE(12, 13); PEER_CE(14, 15);
;     PEER_CE(0, 2); PEER_CE(1, 3); PEER_CE(4, 10); PEER_CE(5, 11); PEER_CE(6, 7); PEER_CE(8, 9); PEER_CE(12, 14); PEER_CE(13, 15);
;     PEER_CE(1, 2); PEER_CE(3, 12); PEER_CE(4, 6); PEER_CE(5, 7); PEER_CE(8, 10); PEER_CE(9, 11); PEER_CE(13, 14);
;     PEER_CE(1, 4); PEER_CE(2, 6); PEER_CE(5, 8); PEER_CE(7, 10); PEER_CE(9, 13); PEER_CE(11, 14);
;     PEER_CE(2, 4); PEER_CE(3, 6); PEER_CE(9, 12); PEER_CE(11, 13);
;     PEER_CE(3, 5); PEER_CE(6, 8); PEER_CE(7, 9); PEER_CE(10, 12);
;     PEER_CE(3, 4); PEER_CE(5, 6); PEER_CE(7, 8); PEER_CE(9, 10); PEER_CE(11, 12);
;     PEER_CE(6, 7); PEER_CE(8, 9);
;     ...
; }
; __device__ __forceinline__ void topk_p_lds(const bf16* __restrict__ skf, const char* qlds, int r32, int hi, unsigned (&Lst)[16]) {
;     bf16x8 bq[8];
; #pragma unroll
;     for (int ks = 0; ks < 8; ++ks) bq[ks] = *reinterpret_cast<const bf16x8*>(qlds + ((2 * ks + hi) * 32 + r32) * 16);
; #pragma unroll
;     for (int kb = 0; kb < 4; ++kb) {
;         bf16x8 a[8];
; #pragma unroll
;         for (int ks = 0; ks < 8; ++ks) a[ks] = *reinterpret_cast<const bf16x8*>(skf + (size_t)((((kb * 8 + ks) * 2 + hi) * 32 + r32) * 8));
;         f32x16 acc = {};
; #pragma unroll
;         for (int ks = 0; ks < 8; ++ks) acc = __builtin_amdgcn_mfma_f32_32x32x16_bf16(a[ks], bq[ks], acc, 0, 0, 0);
;         unsigned S[16];
; #pragma unroll
;         for (int r = 0; r < 16; ++r) S[r] = (__float_as_uint(acc[r]) & ~127u) | (unsigned)(32 * kb + crow(r, hi));
;         sort16_desc(S);
;         if (kb == 0) {
; #pragma unroll
;             for (int r = 0; r < 16; ++r) Lst[r] = S[r];
;         } else merge_top16(Lst, S);
	v_mfma_f32_32x32x16_bf16 v[2:17], v[60:63], v[26:29], v[2:17]
	v_max_f32_e32 v88, v64, v87
	v_min_f32_e32 v75, v64, v87
	v_max_f32_e32 v85, v65, v69
	v_min_f32_e32 v87, v65, v69
	v_addc_co_u32_e64 v69, s[0:1], 0, v67, s[0:1]
	global_load_dwordx4 v[62:65], v[68:69], off offset:-4096
	s_nop 5
	v_and_b32_e32 v7, 0xffffff80, v7
	v_or3_b32 v7, v72, v7, 9
	v_and_b32_e32 v6, 0xffffff80, v6
	v_and_b32_e32 v9, 0xffffff80, v9
	v_max_f32_e32 v60, v7, v7
	v_and_b32_e32 v7, 0xffffff80, v15
	v_or3_b32 v6, v72, v6, 8
	v_or3_b32 v9, v72, v9, 11
	v_or3_b32 v7, v72, v7, 25
	v_max_f32_e32 v55, v6, v6
	v_and_b32_e32 v6, 0xffffff80, v16
	v_max_f32_e32 v52, v9, v9
	v_and_b32_e32 v9, 0xffffff80, v14
	v_and_b32_e32 v8, 0xffffff80, v8
	v_max_f32_e32 v61, v7, v7
	v_and_b32_e32 v7, 0xffffff80, v10
	v_or3_b32 v6, v72, v6, 26
	v_or3_b32 v9, v72, v9, 24
	v_or3_b32 v8, v72, v8, 10
	v_or3_b32 v7, v72, v7, 16
	v_max_f32_e32 v16, v6, v6
	v_and_b32_e32 v6, 0xffffff80, v11
	v_max_f32_e32 v14, v9, v9
	v_max_f32_e32 v59, v8, v8
	v_max_f32_e32 v10, v7, v7
	v_or3_b32 v11, v72, v6, 17
	global_load_dwordx4 v[6:9], v[50:51], off
	v_and_or_b32 v2, v2, s15, v72
	v_and_b32_e32 v3, 0xffffff80, v3
	v_max_f32_e32 v15, v2, v2
	v_and_b32_e32 v5, 0xffffff80, v5
	v_or3_b32 v3, v72, v3, 1
	v_min_f32_e32 v54, v60, v59
	v_min_f32_e32 v2, v15, v61
	v_or3_b32 v5, v72, v5, 3
	s_mov_b32 s0, 0xb000
	v_max_f32_e32 v3, v3, v3
	v_min_f32_e32 v91, v54, v2
	v_max_f32_e32 v5, v5, v5
	v_max_f32_e32 v110, v54, v2
	v_add_co_u32_e64 v2, s[0:1], s0, v66
	v_min_f32_e32 v58, v3, v14
	v_min_f32_e32 v56, v55, v10
	v_min_f32_e32 v57, v5, v16
	v_max_f32_e32 v14, v3, v14
	v_addc_co_u32_e64 v3, s[0:1], 0, v67, s[0:1]
	v_min_f32_e32 v105, v56, v57
	v_max_f32_e32 v111, v56, v57
	v_max_f32_e32 v10, v55, v10
	global_load_dwordx4 v[54:57], v[2:3], off offset:1024
	v_and_b32_e32 v13, 0xffffff80, v13
	v_and_b32_e32 v12, 0xffffff80, v12
	v_and_b32_e32 v4, 0xffffff80, v4
	v_and_b32_e32 v17, 0xffffff80, v17
	v_or3_b32 v13, v72, v13, 19
	v_or3_b32 v12, v72, v12, 18
	v_or3_b32 v4, v72, v4, 2
	v_or3_b32 v17, v72, v17, 27
	v_max_f32_e32 v13, v13, v13
	v_max_f32_e32 v12, v12, v12
	v_max_f32_e32 v11, v11, v11
	v_max_f32_e32 v17, v17, v17
	v_max_f32_e32 v4, v4, v4
	v_min_f32_e32 v53, v52, v13
	v_min_f32_e32 v106, v11, v12
	v_min_f32_e32 v107, v4, v17
	v_max_f32_e32 v77, v89, v90
	v_min_f32_e32 v78, v89, v90
	v_min_f32_e32 v90, v53, v58
	v_min_f32_e32 v108, v106, v107
	v_max_f32_e32 v15, v15, v61
	v_max_f32_e32 v115, v60, v59
	v_max_f32_e32 v106, v106, v107
	v_max_f32_e32 v107, v53, v58
	global_load_dwordx4 v[58:61], v[2:3], off offset:2048
	v_max_f32_e32 v13, v52, v13
	global_load_dwordx4 v[50:53], v[2:3], off offset:3072
	v_max_f32_e32 v4, v4, v17
	v_max_f32_e32 v11, v11, v12
	v_max_f32_e32 v5, v5, v16
	v_min_f32_e32 v104, v90, v91
	v_min_f32_e32 v109, v105, v108
	v_min_f32_e32 v113, v14, v13
	v_min_f32_e32 v12, v4, v11
	v_min_f32_e32 v16, v5, v10
	v_min_f32_e32 v116, v15, v115
	v_min_f32_e32 v89, v104, v109
	v_min_f32_e32 v112, v110, v111
	v_min_f32_e32 v17, v113, v12
	v_min_f32_e32 v117, v16, v116
	v_min_f32_e32 v118, v106, v107
	v_max_f32_e32 v104, v104, v109
	v_max_f32_e32 v109, v90, v91
	v_max_f32_e32 v105, v105, v108
	v_min_f32_e32 v114, v112, v17
	v_min_f32_e32 v119, v117, v118
	v_min_f32_e32 v91, v109, v105
	v_min_f32_e32 v120, v114, v119
	v_min_f32_e32 v2, v104, v91
	v_max_f32_e32 v3, v114, v119
	v_max_f32_e32 v104, v104, v91
	v_min_f32_e32 v90, v120, v2
	v_max_f32_e32 v2, v120, v2
	v_min_f32_e32 v108, v3, v104
	v_min_f32_e32 v91, v2, v108
	v_max_f32_e32 v114, v2, v108
	v_max_f32_e32 v110, v110, v111
	v_max_f32_e32 v111, v113, v12
	v_max_f32_e32 v112, v112, v17
	v_max_f32_e32 v116, v16, v116
	v_max_f32_e32 v104, v3, v104
	v_max_f32_e32 v115, v15, v115
	v_max_f32_e32 v120, v14, v13
	v_max_f32_e32 v122, v4, v11
	v_max_f32_e32 v123, v5, v10
	s_waitcnt vmcnt(3)
	v_mfma_f32_32x32x16_bf16 v[2:17], v[6:9], v[46:49], 0
	v_max_f32_e32 v106, v106, v107
	v_min_f32_e32 v121, v115, v120
	v_min_f32_e32 v124, v122, v123
	v_max_f32_e32 v108, v117, v118
	v_min_f32_e32 v113, v110, v111
	v_min_f32_e32 v107, v116, v106
	v_min_f32_e32 v125, v121, v124
	v_mfma_f32_32x32x16_bf16 v[2:17], v[92:95], v[30:33], v[2:17]
	v_max_f32_e32 v105, v109, v105
	v_min_f32_e32 v117, v108, v113
	v_min_f32_e32 v118, v112, v107
	v_min_f32_e32 v109, v125, v105
	v_min_f32_e32 v119, v117, v118
	v_min_f32_e32 v126, v104, v109
	v_max_f32_e32 v117, v117, v118
	v_mfma_f32_32x32x16_bf16 v[2:17], v[96:99], v[34:37], v[2:17]
	v_max_f32_e32 v104, v104, v109
	v_max_f32_e32 v115, v115, v120
	v_max_f32_e32 v120, v122, v123
	v_min_f32_e32 v109, v117, v104
	v_max_f32_e32 v104, v117, v104
	v_max_f32_e32 v117, v121, v124
	v_min_f32_e32 v96, v115, v120
	v_mfma_f32_32x32x16_bf16 v[2:17], v[100:103], v[18:21], v[2:17]
	v_max_f32_e32 v98, v116, v106
	v_max_f32_e32 v99, v110, v111
	v_min_f32_e32 v97, v117, v96
	v_min_f32_e32 v106, v98, v99
	v_max_f32_e32 v105, v125, v105
	v_min_f32_e32 v110, v97, v106
	v_max_f32_e32 v101, v108, v113
	v_mfma_f32_32x32x16_bf16 v[2:17], v[62:65], v[38:41], v[2:17]
	v_max_f32_e32 v102, v112, v107
	global_load_dwordx4 v[92:95], v[68:69], off
	v_max_f32_e32 v118, v119, v126
	v_max_f32_e32 v62, v105, v110
	v_max_f32_e32 v63, v101, v102
	v_min_f32_e32 v127, v119, v126
	v_min_f32_e32 v119, v109, v118
	s_waitcnt vmcnt(3)
	v_mfma_f32_32x32x16_bf16 v[2:17], v[54:57], v[22:25], v[2:17]
	v_max_f32_e32 v113, v109, v118
	v_min_f32_e32 v118, v62, v63
	v_max_f32_e32 v125, v62, v63
	v_max_f32_e32 v117, v117, v96
	v_max_f32_e32 v126, v97, v106
	s_mov_b32 s0, 0xd000
	v_min_f32_e32 v100, v105, v110
	s_waitcnt vmcnt(2)
; __device__ __forceinline__ void sort16_desc(unsigned (&a)[16]) {
;     ...
;     PEER_CE(0, 13); PEER_CE(1, 12); PEER_CE(2, 15); PEER_CE(3, 14); PEER_CE(4, 8); PEER_CE(5, 6); PEER_CE(7, 11); PEER_CE(9, 10);
;     PEER_CE(0, 5); PEER_CE(1, 7); PEER_CE(2, 9); PEER_CE(3, 4); PEER_CE(6, 13); PEER_CE(8, 14); PEER_CE(10, 15); PEER_CE(11, 12);
;     PEER_CE(0, 1); PEER_CE(2, 3); PEER_CE(4, 5); PEER_CE(6, 8); PEER_CE(7, 9); PEER_CE(10, 11); PEER_CE(12, 13); PEER_CE(14, 15);
;     PEER_CE(0, 2); PEER_CE(1, 3); PEER_CE(4, 10); PEER_CE(5, 11); PEER_CE(6, 7); PEER_CE(8, 9); PEER_CE(12, 14); PEER_CE(13, 15);
;     PEER_CE(1, 2); PEER_CE(3, 12); PEER_CE(4, 6); PEER_CE(5, 7); PEER_CE(8, 10); PEER_CE(9, 11); PEER_CE(13, 14);
;     PEER_CE(1, 4); PEER_CE(2, 6); PEER_CE(5, 8); PEER_CE(7, 10); PEER_CE(9, 13); PEER_CE(11, 14);
;     PEER_CE(2, 4); PEER_CE(3, 6); PEER_CE(9, 12); PEER_CE(11, 13);
;     PEER_CE(3, 5); PEER_CE(6, 8); PEER_CE(7, 9); PEER_CE(10, 12);
;     PEER_CE(3, 4); PEER_CE(5, 6); PEER_CE(7, 8); PEER_CE(9, 10); PEER_CE(11, 12);
;     PEER_CE(6, 7); PEER_CE(8, 9);
;     ...
; }
; __device__ __forceinline__ void merge_top16(unsigned (&Lst)[16], const unsigned (&S)[16]) {
; #pragma unroll
;     for (int i = 0; i < 16; ++i) Lst[i] = kmax(Lst[i], S[15 - i]);
;     bitonic_merge_desc<16>(Lst);
; }
; __device__ __forceinline__ void topk_p_lds(const bf16* __restrict__ skf, const char* qlds, int r32, int hi, unsigned (&Lst)[16]) {
;     bf16x8 bq[8];
; #pragma unroll
;     for (int ks = 0; ks < 8; ++ks) bq[ks] = *reinterpret_cast<const bf16x8*>(qlds + ((2 * ks + hi) * 32 + r32) * 16);
; #pragma unroll
;     for (int kb = 0; kb < 4; ++kb) {
;         bf16x8 a[8];
; #pragma unroll
;         for (int ks = 0; ks < 8; ++ks) a[ks] = *reinterpret_cast<const bf16x8*>(skf + (size_t)((((kb * 8 + ks) * 2 + hi) * 32 + r32) * 8));
;         f32x16 acc = {};
; #pragma unroll
;         for (int ks = 0; ks < 8; ++ks) acc = __builtin_amdgcn_mfma_f32_32x32x16_bf16(a[ks], bq[ks], acc, 0, 0, 0);
;         unsigned S[16];
; #pragma unroll
;         for (int r = 0; r < 16; ++r) S[r] = (__float_as_uint(acc[r]) & ~127u) | (unsigned)(32 * kb + crow(r, hi));
;         sort16_desc(S);
;         if (kb == 0) {
; #pragma unroll
;             for (int r = 0; r < 16; ++r) Lst[r] = S[r];
;         } else merge_top16(Lst, S);
	v_mfma_f32_32x32x16_bf16 v[2:17], v[58:61], v[42:45], v[2:17]
	v_min_f32_e32 v103, v101, v102
	v_add_co_u32_e64 v108, s[0:1], s0, v66
	v_min_f32_e32 v107, v100, v103
	s_nop 0
	v_addc_co_u32_e64 v109, s[0:1], 0, v67, s[0:1]
	v_min_f32_e32 v112, v104, v107
	s_waitcnt vmcnt(1)
	v_mfma_f32_32x32x16_bf16 v[2:17], v[50:53], v[26:29], v[2:17]
	v_max_f32_e32 v123, v104, v107
	v_max_f32_e32 v129, v98, v99
	global_load_dwordx4 v[54:57], v[108:109], off offset:1024
	s_mov_b32 s0, 0xe000
	v_max_f32_e32 v121, v100, v103
	v_min_f32_e32 v116, v112, v113
	v_min_f32_e32 v122, v118, v121
	s_nop 4
	v_and_b32_e32 v9, 0xffffff80, v9
	v_and_b32_e32 v13, 0xffffff80, v13
	v_and_b32_e32 v3, 0xffffff80, v3
	v_and_b32_e32 v14, 0xffffff80, v14
	v_and_b32_e32 v7, 0xffffff80, v7
	v_and_b32_e32 v8, 0xffffff80, v8
	v_and_b32_e32 v2, 0xffffff80, v2
	v_and_b32_e32 v15, 0xffffff80, v15
	v_and_b32_e32 v6, 0xffffff80, v6
	v_and_b32_e32 v10, 0xffffff80, v10
	v_and_b32_e32 v5, 0xffffff80, v5
	v_and_b32_e32 v16, 0xffffff80, v16
	v_and_b32_e32 v11, 0xffffff80, v11
	v_and_b32_e32 v12, 0xffffff80, v12
	v_and_b32_e32 v4, 0xffffff80, v4
	v_and_b32_e32 v17, 0xffffff80, v17
	v_or3_b32 v9, v72, v9, 43
	v_or3_b32 v13, v72, v13, 51
	v_or3_b32 v3, v72, v3, 33
	v_or3_b32 v14, v72, v14, 56
	v_or3_b32 v7, v72, v7, 41
	v_or3_b32 v8, v72, v8, 42
	v_or3_b32 v2, v72, v2, 32
	v_or3_b32 v15, v72, v15, 57
	v_or3_b32 v6, v72, v6, 40
	v_or3_b32 v10, v72, v10, 48
	v_or3_b32 v5, v72, v5, 35
	v_or3_b32 v16, v72, v16, 58
	v_or3_b32 v11, v72, v11, 49
	v_or3_b32 v12, v72, v12, 50
	v_or3_b32 v4, v72, v4, 34
	v_or3_b32 v17, v72, v17, 59
	v_max_f32_e32 v13, v13, v13
	v_max_f32_e32 v9, v9, v9
	v_max_f32_e32 v14, v14, v14
	v_max_f32_e32 v3, v3, v3
	v_max_f32_e32 v8, v8, v8
	v_max_f32_e32 v7, v7, v7
	v_max_f32_e32 v15, v15, v15
	v_max_f32_e32 v2, v2, v2
	v_max_f32_e32 v10, v10, v10
	v_max_f32_e32 v6, v6, v6
	v_max_f32_e32 v16, v16, v16
	v_max_f32_e32 v5, v5, v5
	v_max_f32_e32 v12, v12, v12
	v_max_f32_e32 v11, v11, v11
	v_max_f32_e32 v17, v17, v17
	v_max_f32_e32 v4, v4, v4
	v_min_f32_e32 v50, v9, v13
	v_min_f32_e32 v51, v3, v14
	v_min_f32_e32 v53, v7, v8
	v_min_f32_e32 v58, v2, v15
	v_min_f32_e32 v61, v6, v10
	v_min_f32_e32 v62, v5, v16
	v_min_f32_e32 v64, v11, v12
	v_min_f32_e32 v65, v4, v17
	v_max_f32_e32 v3, v3, v14
	v_max_f32_e32 v9, v9, v13
	v_max_f32_e32 v4, v4, v17
	v_max_f32_e32 v11, v11, v12
	v_max_f32_e32 v5, v5, v16
	v_max_f32_e32 v6, v6, v10
	v_max_f32_e32 v2, v2, v15
	v_max_f32_e32 v7, v7, v8
	v_min_f32_e32 v52, v50, v51
	v_min_f32_e32 v59, v53, v58
	v_min_f32_e32 v63, v61, v62
	v_min_f32_e32 v96, v64, v65
	v_max_f32_e32 v53, v53, v58
	v_max_f32_e32 v58, v61, v62
	v_min_f32_e32 v13, v3, v9
	v_min_f32_e32 v12, v4, v11
	v_min_f32_e32 v10, v5, v6
	v_min_f32_e32 v8, v2, v7
	v_max_f32_e32 v16, v64, v65
	v_max_f32_e32 v50, v50, v51
	v_min_f32_e32 v60, v52, v59
	v_min_f32_e32 v97, v63, v96
	v_min_f32_e32 v61, v53, v58
	v_min_f32_e32 v14, v13, v12
	v_min_f32_e32 v15, v10, v8
	v_min_f32_e32 v51, v16, v50
	v_max_f32_e32 v52, v52, v59
	v_max_f32_e32 v63, v63, v96
	v_min_f32_e32 v133, v60, v97
	v_min_f32_e32 v17, v61, v14
	v_min_f32_e32 v62, v15, v51
	v_max_f32_e32 v60, v60, v97
	v_min_f32_e32 v59, v52, v63
	v_min_f32_e32 v64, v17, v62
	v_min_f32_e32 v65, v60, v59
	v_max_f32_e32 v17, v17, v62
	v_max_f32_e32 v59, v60, v59
	v_min_f32_e32 v134, v64, v65
	v_max_f32_e32 v64, v64, v65
	v_min_f32_e32 v60, v17, v59
	v_min_f32_e32 v135, v64, v60
	v_max_f32_e32 v136, v64, v60
	v_max_f32_e32 v53, v53, v58
	v_max_f32_e32 v14, v61, v14
	v_max_f32_e32 v17, v17, v59
	global_load_dwordx4 v[58:61], v[68:69], off offset:1024
	v_max_f32_e32 v4, v4, v11
	v_max_f32_e32 v11, v52, v63
	global_load_dwordx4 v[62:65], v[68:69], off offset:2048
	v_max_f32_e32 v2, v2, v7
	v_max_f32_e32 v3, v3, v9
	v_max_f32_e32 v5, v5, v6
	v_max_f32_e32 v12, v13, v12
	v_max_f32_e32 v8, v10, v8
	v_max_f32_e32 v10, v16, v50
	v_min_f32_e32 v7, v2, v3
	v_min_f32_e32 v6, v4, v5
	v_max_f32_e32 v15, v15, v51
	v_min_f32_e32 v13, v53, v12
	v_min_f32_e32 v16, v8, v10
	v_min_f32_e32 v9, v7, v6
	v_min_f32_e32 v51, v15, v13
	v_min_f32_e32 v50, v14, v16
	v_min_f32_e32 v52, v9, v11
	v_min_f32_e32 v96, v51, v50
	v_min_f32_e32 v97, v17, v52
	v_min_f32_e32 v137, v96, v97
	v_max_f32_e32 v104, v96, v97
	global_load_dwordx4 v[96:99], v[68:69], off offset:3072
	v_max_f32_e32 v50, v51, v50
	v_max_f32_e32 v17, v17, v52
	v_min_f32_e32 v52, v50, v17
	v_max_f32_e32 v17, v50, v17
	v_add_co_u32_e64 v50, s[0:1], s0, v66
	v_min_f32_e32 v139, v52, v104
	s_nop 0
	v_addc_co_u32_e64 v51, s[0:1], 0, v67, s[0:1]
	global_load_dwordx4 v[100:103], v[50:51], off offset:-4096
	v_max_f32_e32 v52, v52, v104
	global_load_dwordx4 v[104:107], v[108:109], off offset:2048
	v_max_f32_e32 v2, v2, v3
	global_load_dwordx4 v[108:111], v[108:109], off offset:3072
	v_max_f32_e32 v3, v4, v5
	v_max_f32_e32 v6, v7, v6
	v_min_f32_e32 v4, v2, v3
	v_max_f32_e32 v7, v8, v10
	v_max_f32_e32 v8, v53, v12
	v_min_f32_e32 v5, v6, v4
	v_min_f32_e32 v10, v7, v8
	v_max_f32_e32 v9, v9, v11
	v_min_f32_e32 v11, v5, v10
	v_max_f32_e32 v13, v15, v13
	v_max_f32_e32 v14, v14, v16
	v_min_f32_e32 v12, v9, v11
	v_min_f32_e32 v15, v13, v14
	v_max_f32_e32 v9, v9, v11
	v_max_f32_e32 v11, v13, v14
	v_min_f32_e32 v16, v12, v15
	v_min_f32_e32 v13, v9, v11
	v_max_f32_e32 v12, v12, v15
	v_max_f32_e32 v4, v6, v4
	v_max_f32_e32 v6, v7, v8
	v_min_f32_e32 v14, v13, v12
	v_max_f32_e32 v15, v17, v16
	v_max_f32_e32 v5, v5, v10
	v_min_f32_e32 v7, v4, v6
	v_min_f32_e32 v130, v117, v129
	v_min_f32_e32 v53, v17, v16
	v_min_f32_e32 v16, v14, v15
	v_max_f32_e32 v9, v9, v11
	v_min_f32_e32 v8, v5, v7
	v_min_f32_e32 v128, v114, v127
	v_min_f32_e32 v124, v122, v123
	v_min_f32_e32 v10, v9, v8
	v_max3_f32 v11, v115, v120, v133
	v_max3_f32 v17, v117, v129, v134
	v_max3_f32 v69, v126, v130, v135
	v_max3_f32 v16, v112, v113, v16
	v_max3_f32 v14, v116, v14, v15
	v_max3_f32 v12, v119, v13, v12
	v_min_f32_e32 v68, v53, v52
	v_max3_f32 v52, v124, v53, v52
	v_max3_f32 v53, v114, v127, v10
	v_max3_f32 v112, v128, v9, v8
	v_max3_f32 v91, v91, v5, v7
	v_max3_f32 v90, v90, v4, v6
	v_max3_f32 v89, v89, v2, v3
	v_max_f32_e32 v113, v11, v16
	v_min_f32_e32 v114, v11, v16
	v_max_f32_e32 v116, v17, v14
	v_min_f32_e32 v119, v17, v14
	v_max_f32_e32 v120, v69, v12
	v_min_f32_e32 v69, v69, v12
	s_waitcnt vmcnt(7)
; __device__ __forceinline__ int crow(int r, int hi) { return (r & 3) + 8 * (r >> 2) + 4 * hi; }
; #define PEER_CE(i, j) do { const unsigned mx_ = kmax(a[i], a[j]), mn_ = kmin(a[i], a[j]); a[i] = mx_; a[j] = mn_; } while (0)
; __device__ __forceinline__ void sort16_desc(unsigned (&a)[16]) {
;     ...
;     PEER_CE(0, 13); PEER_CE(1, 12); PEER_CE(2, 15); PEER_CE(3, 14); PEER_CE(4, 8); PEER_CE(5, 6); PEER_CE(7, 11); PEER_CE(9, 10);
;     PEER_CE(0, 5); PEER_CE(1, 7); PEER_CE(2, 9); PEER_CE(3, 4); PEER_CE(6, 13); PEER_CE(8, 14); PEER_CE(10, 15); PEER_CE(11, 12);
;     PEER_CE(0, 1); PEER_CE(2, 3); PEER_CE(4, 5); PEER_CE(6, 8); PEER_CE(7, 9); PEER_CE(10, 11); PEER_CE(12, 13); PEER_CE(14, 15);
;     PEER_CE(0, 2); PEER_CE(1, 3); PEER_CE(4, 10); PEER_CE(5, 11); PEER_CE(6, 7); PEER_CE(8, 9); PEER_CE(12, 14); PEER_CE(13, 15);
;     PEER_CE(1, 2); PEER_CE(3, 12); PEER_CE(4, 6); PEER_CE(5, 7); PEER_CE(8, 10); PEER_CE(9, 11); PEER_CE(13, 14);
;     PEER_CE(1, 4); PEER_CE(2, 6); PEER_CE(5, 8); PEER_CE(7, 10); PEER_CE(9, 13); PEER_CE(11, 14);
;     PEER_CE(2, 4); PEER_CE(3, 6); PEER_CE(9, 12); PEER_CE(11, 13);
;     PEER_CE(3, 5); PEER_CE(6, 8); PEER_CE(7, 9); PEER_CE(10, 12);
;     PEER_CE(3, 4); PEER_CE(5, 6); PEER_CE(7, 8); PEER_CE(9, 10); PEER_CE(11, 12);
;     PEER_CE(6, 7); PEER_CE(8, 9);
;     ...
; }
; __device__ __forceinline__ void topk_p_lds(const bf16* __restrict__ skf, const char* qlds, int r32, int hi, unsigned (&Lst)[16]) {
;     bf16x8 bq[8];
; #pragma unroll
;     for (int ks = 0; ks < 8; ++ks) bq[ks] = *reinterpret_cast<const bf16x8*>(qlds + ((2 * ks + hi) * 32 + r32) * 16);
; #pragma unroll
;     for (int kb = 0; kb < 4; ++kb) {
;         bf16x8 a[8];
; #pragma unroll
;         for (int ks = 0; ks < 8; ++ks) a[ks] = *reinterpret_cast<const bf16x8*>(skf + (size_t)((((kb * 8 + ks) * 2 + hi) * 32 + r32) * 8));
;         f32x16 acc = {};
; #pragma unroll
;         for (int ks = 0; ks < 8; ++ks) acc = __builtin_amdgcn_mfma_f32_32x32x16_bf16(a[ks], bq[ks], acc, 0, 0, 0);
;         unsigned S[16];
; #pragma unroll
;         for (int r = 0; r < 16; ++r) S[r] = (__float_as_uint(acc[r]) & ~127u) | (unsigned)(32 * kb + crow(r, hi));
;         sort16_desc(S);
;         if (kb == 0) {
; #pragma unroll
;             for (int r = 0; r < 16; ++r) Lst[r] = S[r];
;         } else merge_top16(Lst, S);
	v_mfma_f32_32x32x16_bf16 v[2:17], v[92:95], v[46:49], 0
	v_min_f32_e32 v131, v126, v130
	v_min_f32_e32 v132, v125, v131
	v_min_f32_e32 v138, v136, v137
	v_max3_f32 v115, v125, v131, v138
	v_max3_f32 v117, v132, v136, v137
	v_max3_f32 v118, v118, v121, v139
	v_max3_f32 v68, v122, v123, v68
	s_waitcnt vmcnt(5)
	v_mfma_f32_32x32x16_bf16 v[2:17], v[58:61], v[30:33], v[2:17]
	v_max_f32_e32 v121, v115, v53
	v_min_f32_e32 v53, v115, v53
	v_max_f32_e32 v92, v117, v112
	v_min_f32_e32 v93, v117, v112
	v_max_f32_e32 v94, v118, v91
	v_min_f32_e32 v91, v118, v91
	v_max_f32_e32 v95, v68, v90
	s_waitcnt vmcnt(4)
	v_mfma_f32_32x32x16_bf16 v[2:17], v[62:65], v[34:37], v[2:17]
	v_min_f32_e32 v68, v68, v90
	v_max_f32_e32 v58, v52, v89
	v_min_f32_e32 v52, v52, v89
	v_max_f32_e32 v59, v113, v92
	v_min_f32_e32 v60, v113, v92
	v_max_f32_e32 v61, v116, v94
	v_max_f32_e32 v90, v120, v95
	s_waitcnt vmcnt(3)
	v_mfma_f32_32x32x16_bf16 v[2:17], v[96:99], v[18:21], v[2:17]
	v_min_f32_e32 v62, v120, v95
	v_max_f32_e32 v63, v121, v58
	v_max_f32_e32 v64, v114, v93
	v_min_f32_e32 v65, v114, v93
	v_max_f32_e32 v92, v119, v91
	v_min_f32_e32 v91, v119, v91
	v_max_f32_e32 v93, v69, v68
	s_waitcnt vmcnt(2)
	v_mfma_f32_32x32x16_bf16 v[2:17], v[100:103], v[38:41], v[2:17]
	v_min_f32_e32 v68, v69, v68
	v_max_f32_e32 v69, v53, v52
	v_min_f32_e32 v52, v53, v52
	v_min_f32_e32 v58, v121, v58
	v_max_f32_e32 v112, v59, v90
	v_min_f32_e32 v113, v59, v90
	v_max_f32_e32 v114, v61, v63
	v_mfma_f32_32x32x16_bf16 v[2:17], v[54:57], v[22:25], v[2:17]
	v_min_f32_e32 v102, v61, v63
	v_max_f32_e32 v103, v60, v62
	v_min_f32_e32 v115, v60, v62
	v_max_f32_e32 v121, v91, v52
	v_min_f32_e32 v122, v91, v52
	v_min_f32_e32 v89, v116, v94
	v_max_f32_e32 v117, v64, v93
	s_waitcnt vmcnt(1)
	v_mfma_f32_32x32x16_bf16 v[2:17], v[104:107], v[42:45], v[2:17]
	v_min_f32_e32 v118, v64, v93
	v_max_f32_e32 v116, v89, v58
	v_min_f32_e32 v89, v89, v58
	v_max_f32_e32 v120, v65, v68
	v_min_f32_e32 v68, v65, v68
	v_max_f32_e32 v119, v92, v69
	v_min_f32_e32 v69, v92, v69
	s_waitcnt vmcnt(0)
	v_mfma_f32_32x32x16_bf16 v[2:17], v[108:111], v[26:29], v[2:17]
	s_mov_b32 s0, 0xf000
	v_min_f32_e32 v123, v112, v114
	v_min_f32_e32 v107, v117, v119
	v_min_f32_e32 v104, v113, v102
	v_min_f32_e32 v105, v103, v116
	v_min_f32_e32 v106, v115, v89
	v_min_f32_e32 v124, v118, v69
	s_nop 4
	v_and_b32_e32 v9, 0xffffff80, v9
	v_and_b32_e32 v13, 0xffffff80, v13
	v_and_b32_e32 v3, 0xffffff80, v3
	v_and_b32_e32 v14, 0xffffff80, v14
	v_and_b32_e32 v7, 0xffffff80, v7
	v_and_b32_e32 v8, 0xffffff80, v8
	v_and_b32_e32 v2, 0xffffff80, v2
	v_and_b32_e32 v15, 0xffffff80, v15
	v_and_b32_e32 v6, 0xffffff80, v6
	v_and_b32_e32 v10, 0xffffff80, v10
	v_and_b32_e32 v5, 0xffffff80, v5
	v_and_b32_e32 v16, 0xffffff80, v16
	v_and_b32_e32 v11, 0xffffff80, v11
	v_and_b32_e32 v12, 0xffffff80, v12
	v_and_b32_e32 v4, 0xffffff80, v4
	v_and_b32_e32 v17, 0xffffff80, v17
	v_or3_b32 v9, v72, v9, s16
	v_or3_b32 v13, v72, v13, s17
	v_or3_b32 v3, v72, v3, s3
	v_or3_b32 v14, v72, v14, s23
	v_or3_b32 v7, v72, v7, s33
	v_or3_b32 v8, v72, v8, s68
	v_or3_b32 v2, v72, v2, 64
	v_or3_b32 v15, v72, v15, s69
	v_or3_b32 v6, v72, v6, s70
	v_or3_b32 v10, v72, v10, s71
	v_or3_b32 v5, v72, v5, s76
	v_or3_b32 v16, v72, v16, s77
	v_or3_b32 v11, v72, v11, s78
	v_or3_b32 v12, v72, v12, s79
	v_or3_b32 v4, v72, v4, s80
	v_or3_b32 v17, v72, v17, s81
	v_max_f32_e32 v13, v13, v13
	v_max_f32_e32 v9, v9, v9
	v_max_f32_e32 v14, v14, v14
	v_max_f32_e32 v3, v3, v3
	v_max_f32_e32 v8, v8, v8
	v_max_f32_e32 v7, v7, v7
	v_max_f32_e32 v15, v15, v15
	v_max_f32_e32 v2, v2, v2
	v_max_f32_e32 v10, v10, v10
	v_max_f32_e32 v6, v6, v6
	v_max_f32_e32 v16, v16, v16
	v_max_f32_e32 v5, v5, v5
	v_max_f32_e32 v12, v12, v12
	v_max_f32_e32 v11, v11, v11
	v_max_f32_e32 v17, v17, v17
	v_max_f32_e32 v4, v4, v4
	v_min_f32_e32 v52, v9, v13
	v_min_f32_e32 v53, v3, v14
	v_min_f32_e32 v55, v7, v8
	v_min_f32_e32 v56, v2, v15
	v_min_f32_e32 v59, v6, v10
	v_min_f32_e32 v60, v5, v16
	v_min_f32_e32 v62, v11, v12
	v_min_f32_e32 v63, v4, v17
	v_max_f32_e32 v3, v3, v14
	v_max_f32_e32 v9, v9, v13
	v_max_f32_e32 v4, v4, v17
	v_max_f32_e32 v11, v11, v12
	v_max_f32_e32 v5, v5, v16
	v_max_f32_e32 v6, v6, v10
	v_max_f32_e32 v2, v2, v15
	v_max_f32_e32 v7, v7, v8
	v_min_f32_e32 v13, v3, v9
	v_min_f32_e32 v12, v4, v11
	v_min_f32_e32 v10, v5, v6
	v_min_f32_e32 v8, v2, v7
	v_max_f32_e32 v7, v2, v7
	v_max_f32_e32 v9, v3, v9
	v_max_f32_e32 v11, v4, v11
	v_max_f32_e32 v6, v5, v6
	global_load_dwordx4 v[2:5], v[50:51], off
	v_min_f32_e32 v54, v52, v53
	v_min_f32_e32 v57, v55, v56
	v_min_f32_e32 v61, v59, v60
	v_min_f32_e32 v64, v62, v63
	v_max_f32_e32 v55, v55, v56
	v_max_f32_e32 v56, v59, v60
	v_max_f32_e32 v16, v62, v63
	v_max_f32_e32 v52, v52, v53
	v_min_f32_e32 v58, v54, v57
	v_min_f32_e32 v65, v61, v64
	v_min_f32_e32 v59, v55, v56
	v_min_f32_e32 v14, v13, v12
	v_min_f32_e32 v15, v10, v8
	v_min_f32_e32 v53, v16, v52
	v_max_f32_e32 v54, v54, v57
	v_max_f32_e32 v57, v61, v64
	v_min_f32_e32 v108, v58, v65
	v_min_f32_e32 v17, v59, v14
	v_min_f32_e32 v60, v15, v53
	v_max_f32_e32 v58, v58, v65
	v_min_f32_e32 v61, v54, v57
	v_max_f32_e32 v15, v15, v53
	v_max_f32_e32 v64, v55, v56
	v_max_f32_e32 v8, v10, v8
	v_max_f32_e32 v10, v16, v52
	v_max_f32_e32 v90, v54, v57
	global_load_dwordx4 v[52:55], v[50:51], off offset:1024
	v_min_f32_e32 v62, v17, v60
	v_min_f32_e32 v63, v58, v61
	v_max_f32_e32 v17, v17, v60
	v_max_f32_e32 v58, v58, v61
	v_min_f32_e32 v109, v62, v63
	v_max_f32_e32 v62, v62, v63
	v_min_f32_e32 v60, v17, v58
	v_min_f32_e32 v110, v62, v60
	v_max_f32_e32 v60, v62, v60
	v_max_f32_e32 v12, v13, v12
	v_min_f32_e32 v62, v7, v9
	v_min_f32_e32 v63, v11, v6
; __device__ __forceinline__ int crow(int r, int hi) { return (r & 3) + 8 * (r >> 2) + 4 * hi; }
; __device__ __forceinline__ unsigned kmax(unsigned a, unsigned b) { return __float_as_uint(__builtin_fmaxf(__uint_as_float(a), __uint_as_float(b))); }
; __device__ __forceinline__ void merge_top16(unsigned (&Lst)[16], const unsigned (&S)[16]) {
; #pragma unroll
;     for (int i = 0; i < 16; ++i) Lst[i] = kmax(Lst[i], S[15 - i]);
;     bitonic_merge_desc<16>(Lst);
; }
; __device__ __forceinline__ void topk_p_lds(const bf16* __restrict__ skf, const char* qlds, int r32, int hi, unsigned (&Lst)[16]) {
;     bf16x8 bq[8];
; #pragma unroll
;     for (int ks = 0; ks < 8; ++ks) bq[ks] = *reinterpret_cast<const bf16x8*>(qlds + ((2 * ks + hi) * 32 + r32) * 16);
; #pragma unroll
;     for (int kb = 0; kb < 4; ++kb) {
;         bf16x8 a[8];
; #pragma unroll
;         for (int ks = 0; ks < 8; ++ks) a[ks] = *reinterpret_cast<const bf16x8*>(skf + (size_t)((((kb * 8 + ks) * 2 + hi) * 32 + r32) * 8));
;         f32x16 acc = {};
; #pragma unroll
;         for (int ks = 0; ks < 8; ++ks) acc = __builtin_amdgcn_mfma_f32_32x32x16_bf16(a[ks], bq[ks], acc, 0, 0, 0);
;         unsigned S[16];
; #pragma unroll
;         for (int r = 0; r < 16; ++r) S[r] = (__float_as_uint(acc[r]) & ~127u) | (unsigned)(32 * kb + crow(r, hi));
;         sort16_desc(S);
;         if (kb == 0) {
; #pragma unroll
;             for (int r = 0; r < 16; ++r) Lst[r] = S[r];
;         } else merge_top16(Lst, S);
	v_min_f32_e32 v13, v64, v12
	v_max_f32_e32 v14, v59, v14
	v_min_f32_e32 v16, v8, v10
	v_min_f32_e32 v65, v62, v63
	v_min_f32_e32 v56, v15, v13
	v_min_f32_e32 v59, v14, v16
	v_max_f32_e32 v17, v17, v58
	v_min_f32_e32 v57, v65, v90
	v_min_f32_e32 v61, v56, v59
	v_min_f32_e32 v58, v17, v57
	v_min_f32_e32 v91, v61, v58
	v_max_f32_e32 v56, v56, v59
	v_max_f32_e32 v17, v17, v57
	v_min_f32_e32 v111, v60, v91
	v_max_f32_e32 v127, v60, v91
	v_min_f32_e32 v91, v56, v17
	v_max_f32_e32 v92, v61, v58
	v_max_f32_e32 v17, v56, v17
	global_load_dwordx4 v[56:59], v[50:51], off offset:2048
	v_max_f32_e32 v98, v62, v63
	global_load_dwordx4 v[60:63], v[50:51], off offset:3072
	v_max_f32_e32 v11, v11, v6
	v_add_co_u32_e64 v6, s[0:1], s0, v66
	v_max_f32_e32 v9, v7, v9
	s_nop 0
	v_addc_co_u32_e64 v7, s[0:1], 0, v67, s[0:1]
	v_max_f32_e32 v94, v65, v90
	v_max_f32_e32 v8, v8, v10
	v_max_f32_e32 v10, v64, v12
	global_load_dwordx4 v[64:67], v[6:7], off
	v_min_f32_e32 v128, v91, v92
	v_max_f32_e32 v130, v91, v92
	global_load_dwordx4 v[90:93], v[6:7], off offset:1024
	v_min_f32_e32 v99, v9, v11
	v_min_f32_e32 v100, v98, v99
	v_min_f32_e32 v12, v8, v10
	v_min_f32_e32 v50, v100, v12
	v_min_f32_e32 v51, v94, v50
	v_max_f32_e32 v50, v94, v50
	global_load_dwordx4 v[94:97], v[6:7], off offset:2048
	v_max_f32_e32 v13, v15, v13
	v_max_f32_e32 v14, v14, v16
	v_min_f32_e32 v15, v13, v14
	v_max_f32_e32 v13, v13, v14
	v_min_f32_e32 v16, v51, v15
	v_min_f32_e32 v14, v50, v13
	v_max_f32_e32 v15, v51, v15
	v_min_f32_e32 v51, v14, v15
	v_max_f32_e32 v14, v14, v15
	v_max_f32_e32 v12, v100, v12
	v_max_f32_e32 v15, v98, v99
	global_load_dwordx4 v[98:101], v[6:7], off offset:3072
	v_max_f32_e32 v8, v8, v10
	v_min_f32_e32 v129, v17, v16
	v_max_f32_e32 v16, v17, v16
	v_min_f32_e32 v10, v15, v8
	v_min_f32_e32 v17, v51, v16
	v_max_f32_e32 v13, v50, v13
	v_min_f32_e32 v6, v12, v10
	v_min_f32_e32 v125, v120, v121
	v_min_f32_e32 v126, v68, v122
	v_min_f32_e32 v7, v13, v6
	v_max_f32_e32 v6, v13, v6
	v_max_f32_e32 v8, v15, v8
	v_max3_f32 v13, v112, v114, v108
	v_max_f32_e32 v15, v123, v109
	v_max3_f32 v50, v113, v102, v110
	v_max3_f32 v17, v117, v119, v17
	v_max3_f32 v16, v107, v51, v16
	v_max3_f32 v14, v118, v69, v14
	v_max_f32_e32 v102, v104, v111
	v_max_f32_e32 v104, v105, v128
	v_max3_f32 v105, v106, v129, v130
	v_max_f32_e32 v51, v124, v7
	v_max3_f32 v69, v120, v121, v6
	v_max3_f32 v106, v125, v12, v10
	v_max3_f32 v68, v68, v122, v8
	v_max3_f32 v107, v126, v9, v11
	v_max_f32_e32 v108, v13, v17
	v_min_f32_e32 v109, v13, v17
	v_max_f32_e32 v110, v15, v16
	v_min_f32_e32 v111, v15, v16
	v_max_f32_e32 v112, v50, v14
	v_min_f32_e32 v50, v50, v14
	s_waitcnt vmcnt(7)
	v_mfma_f32_32x32x16_bf16 v[2:17], v[2:5], v[46:49], 0
	v_min_f32_e32 v131, v129, v130
	v_max3_f32 v103, v103, v116, v127
	v_max3_f32 v89, v115, v89, v131
	v_max_f32_e32 v113, v102, v51
	v_max_f32_e32 v47, v103, v69
	v_min_f32_e32 v48, v103, v69
	v_max_f32_e32 v49, v104, v106
	s_waitcnt vmcnt(6)
	v_mfma_f32_32x32x16_bf16 v[2:17], v[52:55], v[30:33], v[2:17]
	v_max_f32_e32 v69, v89, v68
	v_max_f32_e32 v30, v105, v107
	v_min_f32_e32 v46, v102, v51
	v_min_f32_e32 v51, v104, v106
	v_min_f32_e32 v68, v89, v68
	v_min_f32_e32 v31, v105, v107
	v_max_f32_e32 v32, v108, v47
	s_waitcnt vmcnt(5)
	v_mfma_f32_32x32x16_bf16 v[2:17], v[56:59], v[34:37], v[2:17]
	v_min_f32_e32 v33, v108, v47
	v_max_f32_e32 v47, v110, v49
	v_min_f32_e32 v49, v110, v49
	v_max_f32_e32 v52, v112, v69
	v_min_f32_e32 v34, v112, v69
	v_max_f32_e32 v35, v113, v30
	v_min_f32_e32 v30, v113, v30
	s_waitcnt vmcnt(4)
	v_mfma_f32_32x32x16_bf16 v[2:17], v[60:63], v[18:21], v[2:17]
	v_max_f32_e32 v36, v109, v48
	v_min_f32_e32 v37, v109, v48
	v_max_f32_e32 v48, v111, v51
	v_min_f32_e32 v51, v111, v51
	v_max_f32_e32 v18, v50, v68
	v_min_f32_e32 v19, v50, v68
	v_max_f32_e32 v20, v46, v31
	s_waitcnt vmcnt(3)
	v_mfma_f32_32x32x16_bf16 v[2:17], v[64:67], v[38:41], v[2:17]
	v_min_f32_e32 v21, v46, v31
	v_max_f32_e32 v31, v32, v52
	v_min_f32_e32 v32, v32, v52
	v_max_f32_e32 v38, v33, v34
	v_min_f32_e32 v33, v33, v34
	v_max_f32_e32 v34, v49, v30
	v_min_f32_e32 v30, v49, v30
	s_waitcnt vmcnt(2)
	v_mfma_f32_32x32x16_bf16 v[2:17], v[90:93], v[22:25], v[2:17]
	v_max_f32_e32 v46, v47, v35
	v_min_f32_e32 v35, v47, v35
	v_max_f32_e32 v24, v51, v21
	v_min_f32_e32 v21, v51, v21
	v_max_f32_e32 v22, v48, v20
	v_min_f32_e32 v20, v48, v20
	v_max_f32_e32 v39, v36, v18
	s_waitcnt vmcnt(1)
	v_mfma_f32_32x32x16_bf16 v[2:17], v[94:97], v[42:45], v[2:17]
	v_min_f32_e32 v18, v36, v18
	v_max_f32_e32 v23, v37, v19
	v_min_f32_e32 v19, v37, v19
	v_min_f32_e32 v25, v31, v46
	v_min_f32_e32 v36, v32, v35
	v_min_f32_e32 v37, v38, v34
	v_min_f32_e32 v40, v33, v30
	s_waitcnt vmcnt(0)
	v_mfma_f32_32x32x16_bf16 v[2:17], v[98:101], v[26:29], v[2:17]
	v_min_f32_e32 v41, v39, v22
	v_min_f32_e32 v42, v18, v20
	v_min_f32_e32 v43, v23, v24
	v_min_f32_e32 v44, v19, v21
	s_waitcnt lgkmcnt(0)
; __device__ __forceinline__ int crow(int r, int hi) { return (r & 3) + 8 * (r >> 2) + 4 * hi; }
; __device__ __forceinline__ unsigned kmax(unsigned a, unsigned b) { return __float_as_uint(__builtin_fmaxf(__uint_as_float(a), __uint_as_float(b))); }
; #define PEER_CE(i, j) do { const unsigned mx_ = kmax(a[i], a[j]), mn_ = kmin(a[i], a[j]); a[i] = mx_; a[j] = mn_; } while (0)
; __device__ __forceinline__ void sort16_desc(unsigned (&a)[16]) {
;     ...
;     PEER_CE(0, 13); PEER_CE(1, 12); PEER_CE(2, 15); PEER_CE(3, 14); PEER_CE(4, 8); PEER_CE(5, 6); PEER_CE(7, 11); PEER_CE(9, 10);
;     PEER_CE(0, 5); PEER_CE(1, 7); PEER_CE(2, 9); PEER_CE(3, 4); PEER_CE(6, 13); PEER_CE(8, 14); PEER_CE(10, 15); PEER_CE(11, 12);
;     PEER_CE(0, 1); PEER_CE(2, 3); PEER_CE(4, 5); PEER_CE(6, 8); PEER_CE(7, 9); PEER_CE(10, 11); PEER_CE(12, 13); PEER_CE(14, 15);
;     PEER_CE(0, 2); PEER_CE(1, 3); PEER_CE(4, 10); PEER_CE(5, 11); PEER_CE(6, 7); PEER_CE(8, 9); PEER_CE(12, 14); PEER_CE(13, 15);
;     PEER_CE(1, 2); PEER_CE(3, 12); PEER_CE(4, 6); PEER_CE(5, 7); PEER_CE(8, 10); PEER_CE(9, 11); PEER_CE(13, 14);
;     PEER_CE(1, 4); PEER_CE(2, 6); PEER_CE(5, 8); PEER_CE(7, 10); PEER_CE(9, 13); PEER_CE(11, 14);
;     PEER_CE(2, 4); PEER_CE(3, 6); PEER_CE(9, 12); PEER_CE(11, 13);
;     PEER_CE(3, 5); PEER_CE(6, 8); PEER_CE(7, 9); PEER_CE(10, 12);
;     PEER_CE(3, 4); PEER_CE(5, 6); PEER_CE(7, 8); PEER_CE(9, 10); PEER_CE(11, 12);
;     PEER_CE(6, 7); PEER_CE(8, 9);
;     ...
; }
; __device__ __forceinline__ void merge_top16(unsigned (&Lst)[16], const unsigned (&S)[16]) {
; #pragma unroll
;     for (int i = 0; i < 16; ++i) Lst[i] = kmax(Lst[i], S[15 - i]);
;     bitonic_merge_desc<16>(Lst);
; }
; __device__ __forceinline__ void topk_p_lds(const bf16* __restrict__ skf, const char* qlds, int r32, int hi, unsigned (&Lst)[16]) {
;     ...
;         for (int r = 0; r < 16; ++r) S[r] = (__float_as_uint(acc[r]) & ~127u) | (unsigned)(32 * kb + crow(r, hi));
;         sort16_desc(S);
;         if (kb == 0) {
; #pragma unroll
;             for (int r = 0; r < 16; ++r) Lst[r] = S[r];
;         } else merge_top16(Lst, S);
	s_nop 7
	v_and_b32_e32 v5, 0xffffff80, v5
	v_and_b32_e32 v16, 0xffffff80, v16
	v_and_b32_e32 v6, 0xffffff80, v6
	v_and_b32_e32 v10, 0xffffff80, v10
	v_and_b32_e32 v2, 0xffffff80, v2
	v_and_b32_e32 v15, 0xffffff80, v15
	v_and_b32_e32 v7, 0xffffff80, v7
	v_and_b32_e32 v8, 0xffffff80, v8
	v_and_b32_e32 v11, 0xffffff80, v11
	v_and_b32_e32 v12, 0xffffff80, v12
	v_and_b32_e32 v4, 0xffffff80, v4
	v_and_b32_e32 v17, 0xffffff80, v17
	v_and_b32_e32 v9, 0xffffff80, v9
	v_and_b32_e32 v13, 0xffffff80, v13
	v_and_b32_e32 v3, 0xffffff80, v3
	v_and_b32_e32 v14, 0xffffff80, v14
	v_or3_b32 v5, v72, v5, s82
	v_or3_b32 v16, v72, v16, s83
	v_or3_b32 v6, v72, v6, s84
	v_or3_b32 v10, v72, v10, s85
	v_or3_b32 v2, v72, v2, s86
	v_or3_b32 v15, v72, v15, s87
	v_or3_b32 v7, v72, v7, s88
	v_or3_b32 v8, v72, v8, s89
	v_or3_b32 v11, v72, v11, s90
	v_or3_b32 v12, v72, v12, s91
	v_or3_b32 v4, v72, v4, s92
	v_or3_b32 v17, v72, v17, s93
	v_or3_b32 v9, v72, v9, s94
	v_or3_b32 v13, v72, v13, s95
	v_or3_b32 v3, v72, v3, s96
	v_or3_b32 v14, v72, v14, s97
	v_max_f32_e32 v16, v16, v16
	v_max_f32_e32 v5, v5, v5
	v_max_f32_e32 v10, v10, v10
	v_max_f32_e32 v6, v6, v6
	v_max_f32_e32 v15, v15, v15
	v_max_f32_e32 v2, v2, v2
	v_max_f32_e32 v8, v8, v8
	v_max_f32_e32 v7, v7, v7
	v_max_f32_e32 v12, v12, v12
	v_max_f32_e32 v11, v11, v11
	v_max_f32_e32 v17, v17, v17
	v_max_f32_e32 v4, v4, v4
	v_max_f32_e32 v13, v13, v13
	v_max_f32_e32 v9, v9, v9
	v_max_f32_e32 v14, v14, v14
	v_max_f32_e32 v3, v3, v3
	v_max_f32_e32 v26, v5, v16
	v_max_f32_e32 v27, v6, v10
	v_max_f32_e32 v29, v2, v15
	v_max_f32_e32 v45, v7, v8
	v_min_f32_e32 v49, v11, v12
	v_min_f32_e32 v50, v4, v17
	v_min_f32_e32 v52, v9, v13
	v_min_f32_e32 v53, v3, v14
	v_min_f32_e32 v7, v7, v8
	v_min_f32_e32 v2, v2, v15
	v_min_f32_e32 v6, v6, v10
	v_min_f32_e32 v5, v5, v16
	v_max_f32_e32 v3, v3, v14
	v_max_f32_e32 v9, v9, v13
	v_max_f32_e32 v4, v4, v17
	v_max_f32_e32 v11, v11, v12
	v_min_f32_e32 v28, v26, v27
	v_min_f32_e32 v47, v29, v45
	v_max_f32_e32 v51, v49, v50
	v_max_f32_e32 v54, v52, v53
	v_max_f32_e32 v8, v7, v2
	v_max_f32_e32 v10, v6, v5
	v_min_f32_e32 v13, v3, v9
	v_min_f32_e32 v12, v4, v11
	v_min_f32_e32 v52, v52, v53
	v_min_f32_e32 v2, v7, v2
	v_min_f32_e32 v5, v6, v5
	v_min_f32_e32 v6, v49, v50
	v_max_f32_e32 v29, v29, v45
	v_max_f32_e32 v3, v3, v9
	v_max_f32_e32 v4, v4, v11
	v_max_f32_e32 v11, v26, v27
	v_min_f32_e32 v48, v28, v47
	v_min_f32_e32 v55, v51, v54
	v_max_f32_e32 v15, v8, v10
	v_max_f32_e32 v14, v13, v12
	v_min_f32_e32 v8, v8, v10
	v_min_f32_e32 v10, v13, v12
	v_max_f32_e32 v13, v28, v47
	v_max_f32_e32 v28, v51, v54
	v_min_f32_e32 v7, v52, v2
	v_min_f32_e32 v49, v5, v6
	v_max_f32_e32 v2, v52, v2
	v_max_f32_e32 v5, v5, v6
	v_min_f32_e32 v9, v29, v3
	v_min_f32_e32 v26, v4, v11
	v_max_f32_e32 v3, v29, v3
	v_max_f32_e32 v4, v4, v11
	v_min_f32_e32 v16, v15, v14
	v_max_f32_e32 v12, v8, v10
	v_min_f32_e32 v47, v13, v28
	v_min_f32_e32 v8, v8, v10
	v_min_f32_e32 v10, v48, v55
	v_max_f32_e32 v50, v7, v49
	v_min_f32_e32 v6, v2, v5
	v_min_f32_e32 v27, v9, v26
	v_max_f32_e32 v9, v9, v26
	v_min_f32_e32 v11, v3, v4
	v_max_f32_e32 v13, v13, v28
	v_max_f32_e32 v14, v15, v14
	v_max_f32_e32 v56, v48, v55
	v_max_f32_e32 v48, v8, v10
	v_max_f32_e32 v52, v50, v6
	v_max_f32_e32 v2, v2, v5
	v_min_f32_e32 v26, v9, v11
	v_min_f32_e32 v15, v13, v14
	v_min_f32_e32 v17, v56, v16
	v_min_f32_e32 v51, v12, v47
	v_max_f32_e32 v53, v48, v52
	v_min_f32_e32 v5, v27, v2
	v_max_f32_e32 v2, v27, v2
	v_min_f32_e32 v27, v26, v15
	v_max_f32_e32 v16, v56, v16
	v_max_f32_e32 v12, v12, v47
	v_max_f32_e32 v54, v17, v51
	v_max_f32_e32 v45, v53, v5
	v_min_f32_e32 v28, v2, v27
	v_min_f32_e32 v29, v16, v12
	v_min_f32_e32 v17, v17, v51
	v_min_f32_e32 v5, v53, v5
	v_max_f32_e32 v2, v2, v27
	v_max_f32_e32 v12, v16, v12
	v_min_f32_e32 v8, v8, v10
	v_min_f32_e32 v6, v50, v6
	v_max_f32_e32 v9, v9, v11
	v_max_f32_e32 v11, v13, v14
	v_max_f32_e32 v55, v54, v45
	v_min_f32_e32 v47, v28, v29
	v_min_f32_e32 v45, v54, v45
	v_max_f32_e32 v51, v17, v5
	v_min_f32_e32 v16, v2, v12
	v_max_f32_e32 v27, v28, v29
	v_max_f32_e32 v10, v8, v6
	v_min_f32_e32 v48, v48, v52
	v_max_f32_e32 v2, v2, v12
	v_max_f32_e32 v12, v26, v15
	v_min_f32_e32 v13, v9, v11
	v_min_f32_e32 v56, v55, v47
	v_max_f32_e32 v53, v45, v51
	v_min_f32_e32 v28, v16, v27
	v_max_f32_e32 v29, v55, v47
	v_max_f32_e32 v50, v10, v48
	v_min_f32_e32 v5, v17, v5
	v_min_f32_e32 v14, v12, v13
	v_min_f32_e32 v54, v56, v53
	v_min_f32_e32 v47, v28, v29
	v_min_f32_e32 v17, v50, v5
	v_max_f32_e32 v5, v50, v5
	v_min_f32_e32 v45, v45, v51
	v_max_f32_e32 v16, v16, v27
	v_min_f32_e32 v15, v2, v14
	v_max_f32_e32 v2, v2, v14
	v_min_f32_e32 v10, v10, v48
	v_min_f32_e32 v6, v8, v6
	v_max_f32_e32 v8, v9, v11
	v_min_f32_e32 v7, v7, v49
	v_max3_f32 v7, v31, v46, v7
	v_max_f32_e32 v6, v25, v6
	v_max3_f32 v9, v32, v35, v10
	v_max_f32_e32 v10, v36, v17
	v_max3_f32 v5, v38, v34, v5
	v_max_f32_e32 v11, v37, v45
	v_max3_f32 v14, v33, v30, v54
	v_max3_f32 v17, v40, v56, v53
	v_max3_f32 v22, v39, v22, v47
	v_max3_f32 v25, v41, v28, v29
	v_max3_f32 v16, v18, v20, v16
	v_max_f32_e32 v15, v42, v15
	v_max3_f32 v2, v23, v24, v2
	v_max3_f32 v12, v43, v12, v13
	v_max3_f32 v8, v19, v21, v8
	v_max3_f32 v3, v44, v3, v4
	v_max_f32_e32 v4, v7, v22
	v_max_f32_e32 v13, v6, v25
	v_max_f32_e32 v18, v9, v16
	v_min_f32_e32 v9, v9, v16
	v_max_f32_e32 v16, v10, v15
	v_min_f32_e32 v10, v10, v15
	v_max_f32_e32 v15, v5, v2
	v_min_f32_e32 v2, v5, v2
	v_max_f32_e32 v5, v11, v12
	v_min_f32_e32 v11, v11, v12
	v_max_f32_e32 v12, v14, v8
	v_min_f32_e32 v8, v14, v8
	v_max_f32_e32 v14, v17, v3
	v_min_f32_e32 v7, v7, v22
	v_min_f32_e32 v6, v6, v25
	v_min_f32_e32 v3, v17, v3
; __device__ __forceinline__ unsigned kmax(unsigned a, unsigned b) { return __float_as_uint(__builtin_fmaxf(__uint_as_float(a), __uint_as_float(b))); }
; __device__ __forceinline__ void merge_top16(unsigned (&Lst)[16], const unsigned (&S)[16]) {
; #pragma unroll
;     for (int i = 0; i < 16; ++i) Lst[i] = kmax(Lst[i], S[15 - i]);
;     bitonic_merge_desc<16>(Lst);
; }
; __device__ __forceinline__ void topk_p_lds(const bf16* __restrict__ skf, const char* qlds, int r32, int hi, unsigned (&Lst)[16]) {
;     ...
;     unsigned Y[16];
; #pragma unroll
;     for (int s = 0; s < 16; ++s) { auto rr = __builtin_amdgcn_permlane32_swap(Lst[s], Lst[s], false, false); Y[s] = hi ? rr[0] : rr[1]; }
;     merge_top16(Lst, Y);
	v_max_f32_e32 v17, v4, v15
	v_min_f32_e32 v4, v4, v15
	v_max_f32_e32 v15, v13, v5
	v_min_f32_e32 v5, v13, v5
	v_max_f32_e32 v13, v18, v12
	v_min_f32_e32 v12, v18, v12
	v_max_f32_e32 v18, v16, v14
	v_min_f32_e32 v14, v16, v14
	v_max_f32_e32 v16, v7, v2
	v_min_f32_e32 v2, v7, v2
	v_max_f32_e32 v7, v6, v11
	v_min_f32_e32 v6, v6, v11
	v_max_f32_e32 v11, v9, v8
	v_min_f32_e32 v8, v9, v8
	v_max_f32_e32 v9, v10, v3
	v_min_f32_e32 v3, v10, v3
	v_max_f32_e32 v10, v17, v13
	v_min_f32_e32 v13, v17, v13
	v_max_f32_e32 v17, v15, v18
	v_min_f32_e32 v15, v15, v18
	v_max_f32_e32 v18, v4, v12
	v_min_f32_e32 v4, v4, v12
	v_max_f32_e32 v12, v5, v14
	v_min_f32_e32 v5, v5, v14
	v_max_f32_e32 v14, v16, v11
	v_min_f32_e32 v11, v16, v11
	v_max_f32_e32 v16, v7, v9
	v_min_f32_e32 v7, v7, v9
	v_max_f32_e32 v9, v2, v8
	v_min_f32_e32 v2, v2, v8
	v_max_f32_e32 v8, v6, v3
	v_min_f32_e32 v3, v6, v3
	v_max_f32_e32 v6, v10, v17
	v_min_f32_e32 v10, v10, v17
	v_max_f32_e32 v17, v13, v15
	v_min_f32_e32 v13, v13, v15
	v_max_f32_e32 v15, v18, v12
	v_min_f32_e32 v12, v18, v12
	v_max_f32_e32 v18, v4, v5
	v_min_f32_e32 v4, v4, v5
	v_max_f32_e32 v5, v14, v16
	v_min_f32_e32 v14, v14, v16
	v_max_f32_e32 v16, v11, v7
	v_min_f32_e32 v7, v11, v7
	v_max_f32_e32 v11, v9, v8
	v_min_f32_e32 v8, v9, v8
	v_max_f32_e32 v9, v2, v3
	v_min_f32_e32 v2, v2, v3
	v_mov_b32_e32 v3, v6
	v_mov_b32_e32 v19, v6
	s_nop 1
	v_permlane32_swap_b32_e32 v3, v19
	v_cndmask_b32_e32 v3, v3, v19, vcc
	v_mov_b32_e32 v19, v10
	v_mov_b32_e32 v20, v10
	s_nop 1
	v_permlane32_swap_b32_e32 v19, v20
	v_cndmask_b32_e32 v19, v19, v20, vcc
	v_mov_b32_e32 v20, v17
	v_mov_b32_e32 v21, v17
	s_nop 1
	v_permlane32_swap_b32_e32 v20, v21
	v_cndmask_b32_e32 v20, v20, v21, vcc
	v_mov_b32_e32 v21, v13
	v_mov_b32_e32 v22, v13
	s_nop 1
	v_permlane32_swap_b32_e32 v21, v22
	v_cndmask_b32_e32 v21, v21, v22, vcc
	v_mov_b32_e32 v22, v15
	v_mov_b32_e32 v23, v15
	s_nop 1
	v_permlane32_swap_b32_e32 v22, v23
	v_cndmask_b32_e32 v22, v22, v23, vcc
	v_mov_b32_e32 v23, v12
	v_mov_b32_e32 v24, v12
	s_nop 1
	v_permlane32_swap_b32_e32 v23, v24
	v_cndmask_b32_e32 v23, v23, v24, vcc
	v_mov_b32_e32 v24, v18
	v_mov_b32_e32 v25, v18
	s_nop 1
	v_permlane32_swap_b32_e32 v24, v25
	v_cndmask_b32_e32 v24, v24, v25, vcc
	v_mov_b32_e32 v25, v4
	v_mov_b32_e32 v26, v4
	s_nop 1
	v_permlane32_swap_b32_e32 v25, v26
	v_cndmask_b32_e32 v25, v25, v26, vcc
	v_mov_b32_e32 v26, v5
	v_mov_b32_e32 v27, v5
	s_nop 1
	v_permlane32_swap_b32_e32 v26, v27
	v_cndmask_b32_e32 v26, v26, v27, vcc
	v_mov_b32_e32 v27, v14
	v_mov_b32_e32 v28, v14
	s_nop 1
	v_permlane32_swap_b32_e32 v27, v28
	v_cndmask_b32_e32 v27, v27, v28, vcc
	v_mov_b32_e32 v28, v16
	v_mov_b32_e32 v29, v16
	s_nop 1
	v_permlane32_swap_b32_e32 v28, v29
	v_cndmask_b32_e32 v28, v28, v29, vcc
	v_mov_b32_e32 v29, v7
	v_mov_b32_e32 v30, v7
	s_nop 1
	v_permlane32_swap_b32_e32 v29, v30
	v_cndmask_b32_e32 v29, v29, v30, vcc
	v_mov_b32_e32 v30, v11
	v_mov_b32_e32 v31, v11
	s_nop 1
	v_permlane32_swap_b32_e32 v30, v31
	v_cndmask_b32_e32 v30, v30, v31, vcc
	v_mov_b32_e32 v31, v8
	v_mov_b32_e32 v32, v8
	s_nop 1
	v_permlane32_swap_b32_e32 v31, v32
	v_cndmask_b32_e32 v31, v31, v32, vcc
	v_mov_b32_e32 v32, v9
	v_mov_b32_e32 v33, v9
	s_nop 1
	v_permlane32_swap_b32_e32 v32, v33
	v_cndmask_b32_e32 v32, v32, v33, vcc
	v_mov_b32_e32 v33, v2
	v_mov_b32_e32 v34, v2
	s_nop 1
	v_permlane32_swap_b32_e32 v33, v34
	v_cndmask_b32_e32 v33, v33, v34, vcc
	v_max_f32_e32 v33, v33, v33
	v_max_f32_e32 v32, v32, v32
	v_max_f32_e32 v31, v31, v31
	v_max_f32_e32 v30, v30, v30
	v_max_f32_e32 v29, v29, v29
	v_max_f32_e32 v28, v28, v28
	v_max_f32_e32 v27, v27, v27
	v_max_f32_e32 v26, v26, v26
	v_max_f32_e32 v25, v25, v25
	v_max_f32_e32 v24, v24, v24
	v_max_f32_e32 v23, v23, v23
	v_max_f32_e32 v22, v22, v22
	v_max_f32_e32 v21, v21, v21
	v_max_f32_e32 v20, v20, v20
	v_max_f32_e32 v19, v19, v19
	v_max_f32_e32 v3, v3, v3
	v_max_f32_e32 v6, v6, v33
	v_max_f32_e32 v10, v10, v32
	v_max_f32_e32 v17, v17, v31
	v_max_f32_e32 v13, v13, v30
	v_max_f32_e32 v15, v15, v29
	v_max_f32_e32 v12, v12, v28
	v_max_f32_e32 v18, v18, v27
	v_max_f32_e32 v4, v4, v26
	v_max_f32_e32 v5, v5, v25
	v_max_f32_e32 v14, v14, v24
	v_max_f32_e32 v16, v16, v23
	v_max_f32_e32 v7, v7, v22
	v_max_f32_e32 v11, v11, v21
	v_max_f32_e32 v8, v8, v20
	v_max_f32_e32 v9, v9, v19
	v_max_f32_e32 v2, v2, v3
	v_max_f32_e32 v3, v6, v5
	v_min_f32_e32 v5, v6, v5
	v_max_f32_e32 v6, v10, v14
	v_min_f32_e32 v10, v10, v14
	v_max_f32_e32 v14, v17, v16
	v_min_f32_e32 v16, v17, v16
	v_max_f32_e32 v17, v13, v7
	v_min_f32_e32 v7, v13, v7
	v_max_f32_e32 v13, v15, v11
	v_min_f32_e32 v11, v15, v11
	v_max_f32_e32 v15, v12, v8
	v_min_f32_e32 v8, v12, v8
	v_max_f32_e32 v12, v18, v9
	v_min_f32_e32 v9, v18, v9
	v_max_f32_e32 v18, v4, v2
	v_min_f32_e32 v2, v4, v2
	v_max_f32_e32 v4, v3, v13
	v_min_f32_e32 v3, v3, v13
	v_max_f32_e32 v13, v6, v15
	v_min_f32_e32 v6, v6, v15
	v_max_f32_e32 v15, v14, v12
	v_min_f32_e32 v12, v14, v12
	v_max_f32_e32 v14, v17, v18
	v_min_f32_e32 v17, v17, v18
	v_max_f32_e32 v18, v5, v11
	v_min_f32_e32 v5, v5, v11
	v_max_f32_e32 v11, v10, v8
	v_min_f32_e32 v8, v10, v8
	v_max_f32_e32 v10, v16, v9
	v_min_f32_e32 v9, v16, v9
	v_max_f32_e32 v16, v7, v2
	v_min_f32_e32 v2, v7, v2
	v_max_f32_e32 v7, v4, v15
	v_min_f32_e32 v4, v4, v15
	v_max_f32_e32 v15, v13, v14
	v_max_f32_e32 v19, v3, v12
	v_min_f32_e32 v3, v3, v12
	v_max_f32_e32 v12, v6, v17
	v_min_f32_e32 v13, v13, v14
	v_min_f32_e32 v6, v6, v17
	v_max_f32_e32 v20, v18, v10
	v_max_f32_e32 v21, v11, v16
	v_min_f32_e32 v22, v11, v16
	v_max_f32_e32 v17, v7, v15
	v_max_f32_e32 v14, v19, v12
	v_min_f32_e32 v11, v19, v12
	v_lshlrev_b32_e32 v19, 7, v73
	v_min_f32_e32 v10, v18, v10
; #define PEER_CAND(a, b, cid, dst) do { const float sum_ = __uint_as_float(T0[a] & ~127u) + __uint_as_float(T1[b] & ~127u); dst = (__float_as_uint(sum_) & ~63u) | (unsigned)(cid); \
;         tab[(cid) * 64] = (unsigned short)((T0[a] & 127u) * 128u + (T1[b] & 127u)); } while (0)
; __device__ __forceinline__ void select_wave_lds(const bf16* __restrict__ skf_h, char* qtile, int h, int* __restrict__ pidx, float* __restrict__ pgate, int wid, int lane) {
;     ...
;     unsigned short* tab = (unsigned short*)(qtile + wid * 16384) + lane;
;     unsigned C[16], R1[16], X[32];
;     ...
; #pragma unroll
;     for (int b = 0; b < 16; ++b) PEER_CAND(0, b, 15 - b, C[b]);
; #pragma unroll
;     for (int b = 0; b < 16; ++b) { if (b < 8) PEER_CAND(1, b, 23 - b, R1[b]); else R1[b] = KEY_NEG_INF; }
;     {   int xi = 0;
; #pragma unroll
;         for (int a = 2; a < 16; ++a)
; #pragma unroll
;             for (int b = 0; b < 16; ++b) if ((a + 1) * (b + 1) <= 16) { PEER_CAND(a, b, 24 + xi, X[xi]); ++xi; }
; #pragma unroll
;         for (int q = 26; q < 32; ++q) X[q] = KEY_NEG_INF;
;     }
;     ...
;     if (hi == 0) {
	v_max_f32_e32 v23, v5, v9
	v_min_f32_e32 v24, v5, v9
	v_max_f32_e32 v9, v8, v2
	v_min_f32_e32 v2, v8, v2
	v_min_f32_e32 v18, v7, v15
	v_max_f32_e32 v16, v4, v13
	v_min_f32_e32 v15, v4, v13
	v_max_f32_e32 v12, v3, v6
	v_min_f32_e32 v13, v3, v6
	v_max_f32_e32 v3, v20, v21
	v_min_f32_e32 v4, v20, v21
	v_and_b32_e32 v19, 0x3f80, v19
	v_and_b32_e32 v20, 0x7f, v17
	v_max_f32_e32 v5, v10, v22
	v_min_f32_e32 v6, v10, v22
	v_max_f32_e32 v7, v23, v9
	v_min_f32_e32 v8, v23, v9
	v_max_f32_e32 v9, v24, v2
	v_min_f32_e32 v10, v24, v2
	v_mad_i32_i24 v2, v70, -14, v71
	v_or_b32_e32 v21, v20, v19
	ds_write_b16 v2, v21 offset:1920
	v_and_b32_e32 v21, 0x7f, v18
	v_or_b32_e32 v22, v21, v19
	ds_write_b16 v2, v22 offset:1792
	v_and_b32_e32 v22, 0x7f, v16
	v_or_b32_e32 v23, v22, v19
	ds_write_b16 v2, v23 offset:1664
	v_and_b32_e32 v23, 0x7f, v15
	v_or_b32_e32 v24, v23, v19
	ds_write_b16 v2, v24 offset:1536
	v_and_b32_e32 v24, 0x7f, v14
	v_or_b32_e32 v25, v24, v19
	ds_write_b16 v2, v25 offset:1408
	v_and_b32_e32 v25, 0x7f, v11
	v_or_b32_e32 v26, v25, v19
	ds_write_b16 v2, v26 offset:1280
	v_and_b32_e32 v26, 0x7f, v12
	v_or_b32_e32 v27, v26, v19
	ds_write_b16 v2, v27 offset:1152
	v_and_b32_e32 v27, 0x7f, v13
	v_or_b32_e32 v28, v27, v19
	ds_write_b16 v2, v28 offset:1024
	v_and_or_b32 v28, v3, s7, v19
	ds_write_b16 v2, v28 offset:896
	v_and_or_b32 v28, v4, s7, v19
	ds_write_b16 v2, v28 offset:768
	v_and_or_b32 v28, v5, s7, v19
	ds_write_b16 v2, v28 offset:640
	v_and_or_b32 v28, v6, s7, v19
	ds_write_b16 v2, v28 offset:512
	v_and_or_b32 v28, v7, s7, v19
	ds_write_b16 v2, v28 offset:384
	v_and_or_b32 v28, v8, s7, v19
	ds_write_b16 v2, v28 offset:256
	v_and_or_b32 v28, v9, s7, v19
	v_and_or_b32 v19, v10, s7, v19
	ds_write_b16 v2, v19
	v_lshlrev_b32_e32 v19, 7, v74
	v_and_b32_e32 v19, 0x3f80, v19
	ds_write_b16 v2, v28 offset:128
	v_or_b32_e32 v28, v20, v19
	ds_write_b16 v2, v28 offset:2944
	v_or_b32_e32 v28, v21, v19
	ds_write_b16 v2, v28 offset:2816
	v_or_b32_e32 v28, v22, v19
	ds_write_b16 v2, v28 offset:2688
	v_or_b32_e32 v28, v23, v19
	v_or_b32_e32 v25, v25, v19
	ds_write_b16 v2, v28 offset:2560
	v_or_b32_e32 v28, v24, v19
	ds_write_b16 v2, v25 offset:2304
	v_or_b32_e32 v25, v26, v19
	v_or_b32_e32 v19, v27, v19
	ds_write_b16 v2, v19 offset:2048
	v_lshlrev_b32_e32 v19, 7, v76
	v_and_b32_e32 v19, 0x3f80, v19
	ds_write_b16 v2, v25 offset:2176
	v_or_b32_e32 v25, v20, v19
	ds_write_b16 v2, v25 offset:3072
	v_or_b32_e32 v25, v21, v19
	ds_write_b16 v2, v25 offset:3200
	v_or_b32_e32 v25, v22, v19
	ds_write_b16 v2, v25 offset:3328
	v_or_b32_e32 v25, v23, v19
	v_or_b32_e32 v19, v24, v19
	ds_write_b16 v2, v19 offset:3584
	v_lshlrev_b32_e32 v19, 7, v80
	v_and_b32_e32 v19, 0x3f80, v19
	v_or_b32_e32 v24, v20, v19
	ds_write_b16 v2, v24 offset:3712
	v_or_b32_e32 v24, v21, v19
	ds_write_b16 v2, v24 offset:3840
	v_or_b32_e32 v24, v22, v19
	v_or_b32_e32 v19, v23, v19
	ds_write_b16 v2, v19 offset:4096
	v_lshlrev_b32_e32 v19, 7, v84
	v_and_b32_e32 v19, 0x3f80, v19
	v_or_b32_e32 v23, v20, v19
	ds_write_b16 v2, v23 offset:4224
	v_or_b32_e32 v23, v21, v19
	v_or_b32_e32 v19, v22, v19
	ds_write_b16 v2, v19 offset:4480
	v_lshlrev_b32_e32 v19, 7, v86
	v_and_b32_e32 v19, 0x3f80, v19
	v_or_b32_e32 v22, v20, v19
	v_or_b32_e32 v19, v21, v19
	ds_write_b16 v2, v19 offset:4736
	v_lshlrev_b32_e32 v19, 7, v88
	v_and_b32_e32 v19, 0x3f80, v19
	ds_write_b16 v2, v22 offset:4608
	v_or_b32_e32 v22, v20, v19
	v_or_b32_e32 v19, v21, v19
	ds_write_b16 v2, v19 offset:4992
	v_lshlrev_b32_e32 v19, 7, v75
	v_and_b32_e32 v19, 0x3f80, v19
	ds_write_b16 v2, v22 offset:4864
	v_or_b32_e32 v22, v20, v19
	v_or_b32_e32 v19, v21, v19
	ds_write_b16 v2, v19 offset:5248
	v_lshlrev_b32_e32 v19, 7, v77
	v_and_or_b32 v19, v19, s6, v20
	ds_write_b16 v2, v19 offset:5376
	v_lshlrev_b32_e32 v19, 7, v78
	v_and_or_b32 v19, v19, s6, v20
	ds_write_b16 v2, v19 offset:5504
	v_lshlrev_b32_e32 v19, 7, v79
	v_and_or_b32 v19, v19, s6, v20
	ds_write_b16 v2, v19 offset:5632
	v_lshlrev_b32_e32 v19, 7, v81
	v_and_or_b32 v19, v19, s6, v20
	ds_write_b16 v2, v19 offset:5760
	v_lshlrev_b32_e32 v19, 7, v82
	v_and_or_b32 v19, v19, s6, v20
	ds_write_b16 v2, v19 offset:5888
	v_lshlrev_b32_e32 v19, 7, v83
	v_and_or_b32 v19, v19, s6, v20
	ds_write_b16 v2, v19 offset:6016
	v_lshlrev_b32_e32 v19, 7, v85
	v_and_or_b32 v19, v19, s6, v20
	ds_write_b16 v2, v19 offset:6144
	v_lshlrev_b32_e32 v19, 7, v87
	v_and_or_b32 v19, v19, s6, v20
	ds_write_b16 v2, v28 offset:2432
	ds_write_b16 v2, v25 offset:3456
	ds_write_b16 v2, v24 offset:3968
	ds_write_b16 v2, v23 offset:4352
	ds_write_b16 v2, v22 offset:5120
	ds_write_b16 v2, v19 offset:6272
	s_waitcnt lgkmcnt(0)
	s_and_saveexec_b64 s[0:1], vcc
	s_cbranch_execz .LBB0_809
; __device__ __forceinline__ unsigned kmax(unsigned a, unsigned b) { return __float_as_uint(__builtin_fmaxf(__uint_as_float(a), __uint_as_float(b))); }
; #define PEER_CAND(a, b, cid, dst) do { const float sum_ = __uint_as_float(T0[a] & ~127u) + __uint_as_float(T1[b] & ~127u); dst = (__float_as_uint(sum_) & ~63u) | (unsigned)(cid); \
;         tab[(cid) * 64] = (unsigned short)((T0[a] & 127u) * 128u + (T1[b] & 127u)); } while (0)
; __device__ __forceinline__ void merge_top16(unsigned (&Lst)[16], const unsigned (&S)[16]) {
; #pragma unroll
;     for (int i = 0; i < 16; ++i) Lst[i] = kmax(Lst[i], S[15 - i]);
;     bitonic_merge_desc<16>(Lst);
; }
; __device__ __forceinline__ void select_wave_lds(const bf16* __restrict__ skf_h, char* qtile, int h, int* __restrict__ pidx, float* __restrict__ pgate, int wid, int lane) {
;     ...
; #pragma unroll
;     for (int b = 0; b < 16; ++b) PEER_CAND(0, b, 15 - b, C[b]);
; #pragma unroll
;     for (int b = 0; b < 16; ++b) { if (b < 8) PEER_CAND(1, b, 23 - b, R1[b]); else R1[b] = KEY_NEG_INF; }
;     {   int xi = 0;
; #pragma unroll
;         for (int a = 2; a < 16; ++a)
; #pragma unroll
;             for (int b = 0; b < 16; ++b) if ((a + 1) * (b + 1) <= 16) { PEER_CAND(a, b, 24 + xi, X[xi]); ++xi; }
; #pragma unroll
;         for (int q = 26; q < 32; ++q) X[q] = KEY_NEG_INF;
;     }
;     ...
;     merge_top16(C, R1);
;     {   unsigned X16[16], Xb[16];
; #pragma unroll
;         for (int q = 0; q < 16; ++q) { X16[q] = X[q]; Xb[q] = X[16 + q]; }
;         sort16_desc(X16); sort16_desc(Xb);
;         merge_top16(X16, Xb);
;         merge_top16(C, X16); }
	v_and_b32_e32 v19, 0xffffff80, v88
	v_and_b32_e32 v18, 0xffffff80, v18
	v_and_b32_e32 v17, 0xffffff80, v17
	v_and_b32_e32 v21, 0xffffff80, v86
	v_and_b32_e32 v23, 0xffffff80, v84
	v_and_b32_e32 v16, 0xffffff80, v16
	v_and_b32_e32 v28, 0xffffff80, v80
	v_and_b32_e32 v15, 0xffffff80, v15
	v_and_b32_e32 v36, 0xffffff80, v76
	v_and_b32_e32 v14, 0xffffff80, v14
	v_add_f32_e32 v20, v19, v18
	v_add_f32_e32 v19, v19, v17
	v_add_f32_e32 v22, v21, v18
	v_add_f32_e32 v21, v21, v17
	v_add_f32_e32 v24, v23, v16
	v_add_f32_e32 v25, v23, v18
	v_add_f32_e32 v23, v23, v17
	v_add_f32_e32 v29, v28, v15
	v_add_f32_e32 v31, v28, v16
	v_add_f32_e32 v33, v28, v18
	v_add_f32_e32 v28, v28, v17
	v_add_f32_e32 v37, v36, v14
	v_add_f32_e32 v39, v36, v15
	v_add_f32_e32 v41, v36, v16
	v_add_f32_e32 v44, v36, v18
	v_add_f32_e32 v36, v36, v17
	v_and_or_b32 v20, v20, s57, 39
	v_and_or_b32 v19, v19, s57, 38
	v_and_or_b32 v22, v22, s57, 37
	v_and_or_b32 v21, v21, s57, 36
	v_and_or_b32 v24, v24, s57, 35
	v_and_or_b32 v25, v25, s57, 34
	v_and_or_b32 v23, v23, s57, 33
	v_and_or_b32 v29, v29, s57, 32
	v_and_or_b32 v31, v31, s57, 31
	v_and_or_b32 v33, v33, s57, 30
	v_and_or_b32 v28, v28, s57, 29
	v_and_or_b32 v37, v37, s57, 28
	v_and_or_b32 v39, v39, s57, 27
	v_and_or_b32 v41, v41, s57, 26
	v_and_or_b32 v44, v44, s57, 25
	v_and_or_b32 v36, v36, s57, 24
	v_max_f32_e32 v22, v22, v22
	v_max_f32_e32 v36, v36, v36
	v_max_f32_e32 v33, v33, v33
	v_max_f32_e32 v28, v28, v28
	v_max_f32_e32 v21, v21, v21
	v_max_f32_e32 v44, v44, v44
	v_max_f32_e32 v24, v24, v24
	v_max_f32_e32 v31, v31, v31
	v_max_f32_e32 v20, v20, v20
	v_max_f32_e32 v41, v41, v41
	v_max_f32_e32 v25, v25, v25
	v_max_f32_e32 v23, v23, v23
	v_max_f32_e32 v19, v19, v19
	v_max_f32_e32 v39, v39, v39
	v_max_f32_e32 v29, v29, v29
	v_max_f32_e32 v37, v37, v37
	v_max_f32_e32 v59, v36, v22
	v_max_f32_e32 v60, v28, v33
	v_max_f32_e32 v62, v44, v21
	v_max_f32_e32 v63, v31, v24
	v_max_f32_e32 v66, v41, v20
	v_max_f32_e32 v67, v23, v25
	v_max_f32_e32 v69, v39, v19
	v_max_f32_e32 v71, v37, v29
	v_min_f32_e32 v23, v23, v25
	v_min_f32_e32 v20, v41, v20
	v_min_f32_e32 v24, v31, v24
	v_min_f32_e32 v21, v44, v21
	v_min_f32_e32 v28, v28, v33
	v_min_f32_e32 v22, v36, v22
	v_min_f32_e32 v29, v37, v29
	v_min_f32_e32 v19, v39, v19
	v_max_f32_e32 v61, v59, v60
	v_max_f32_e32 v64, v62, v63
	v_max_f32_e32 v72, v69, v71
	v_min_f32_e32 v69, v69, v71
	v_min_f32_e32 v59, v59, v60
	v_max_f32_e32 v25, v23, v20
	v_max_f32_e32 v31, v24, v21
	v_max_f32_e32 v33, v28, v22
	v_max_f32_e32 v36, v29, v19
	v_min_f32_e32 v39, v62, v63
	v_min_f32_e32 v62, v66, v67
	v_min_f32_e32 v21, v24, v21
	v_min_f32_e32 v22, v28, v22
	v_min_f32_e32 v19, v29, v19
	v_min_f32_e32 v20, v23, v20
	v_and_b32_e32 v26, 0xffffff80, v87
	v_and_b32_e32 v27, 0xffffff80, v85
	v_and_b32_e32 v30, 0xffffff80, v83
	v_and_b32_e32 v32, 0xffffff80, v82
	v_and_b32_e32 v34, 0xffffff80, v81
	v_and_b32_e32 v35, 0xffffff80, v79
	v_and_b32_e32 v38, 0xffffff80, v78
	v_and_b32_e32 v40, 0xffffff80, v77
	v_and_b32_e32 v42, 0xffffff80, v75
	v_max_f32_e32 v68, v66, v67
	v_min_f32_e32 v60, v69, v59
	v_min_f32_e32 v41, v25, v31
	v_max_f32_e32 v37, v33, v36
	v_min_f32_e32 v33, v33, v36
	v_min_f32_e32 v36, v39, v62
	v_min_f32_e32 v24, v21, v22
	v_min_f32_e32 v23, v19, v20
	v_max_f32_e32 v21, v21, v22
	v_max_f32_e32 v19, v19, v20
	v_add_f32_e32 v26, v26, v17
	v_add_f32_e32 v27, v27, v17
	v_add_f32_e32 v30, v30, v17
	v_add_f32_e32 v32, v32, v17
	v_add_f32_e32 v34, v34, v17
	v_add_f32_e32 v35, v35, v17
	v_add_f32_e32 v38, v38, v17
	v_add_f32_e32 v40, v40, v17
	v_add_f32_e32 v43, v42, v18
	v_add_f32_e32 v42, v42, v17
	v_max_f32_e32 v65, v61, v64
	v_max_f32_e32 v44, v60, v41
	v_max_f32_e32 v63, v39, v62
	v_max_f32_e32 v39, v33, v36
	v_max_f32_e32 v59, v69, v59
	v_max_f32_e32 v25, v25, v31
	v_min_f32_e32 v33, v33, v36
	v_min_f32_e32 v36, v60, v41
	v_max_f32_e32 v28, v24, v23
	v_min_f32_e32 v20, v21, v19
	v_min_f32_e32 v60, v61, v64
	v_min_f32_e32 v61, v68, v72
	v_and_or_b32 v26, v26, s57, 49
	v_and_or_b32 v27, v27, s57, 48
	v_and_or_b32 v30, v30, s57, 47
	v_and_or_b32 v32, v32, s57, 46
	v_and_or_b32 v34, v34, s57, 45
	v_and_or_b32 v35, v35, s57, 44
	v_and_or_b32 v38, v38, s57, 43
	v_and_or_b32 v40, v40, s57, 42
	v_and_or_b32 v43, v43, s57, 41
	v_and_or_b32 v42, v42, s57, 40
	v_min_f32_e32 v66, v37, v63
	v_min_f32_e32 v31, v59, v25
	v_max_f32_e32 v41, v33, v36
	v_max_f32_e32 v22, v28, v20
	v_min_f32_e32 v64, v60, v61
	v_max_f32_e32 v19, v21, v19
	v_max_f32_e32 v32, v32, v32
	v_max_f32_e32 v34, v34, v34
	v_max_f32_e32 v27, v27, v27
	v_max_f32_e32 v35, v35, v35
	v_min_f32_e32 v67, v44, v66
	v_min_f32_e32 v62, v39, v31
	v_max_f32_e32 v29, v41, v22
	v_min_f32_e32 v21, v64, v19
	v_max_f32_e32 v42, v42, v42
	v_max_f32_e32 v43, v43, v43
	v_max_f32_e32 v30, v30, v30
	v_max_f32_e32 v40, v40, v40
	v_max_f32_e32 v26, v26, v26
	v_max_f32_e32 v38, v38, v38
	v_and_b32_e32 v45, 0xffffff80, v74
	v_and_b32_e32 v53, 0xffffff80, v73
	v_max_f32_e32 v73, v68, v72
	v_min_f32_e32 v74, v34, v32
	v_min_f32_e32 v75, v35, v27
	v_max_f32_e32 v69, v67, v62
	v_max_f32_e32 v68, v29, v21
	v_max_f32_e32 v42, 0xff800000, v42
	v_max_f32_e32 v32, v34, v32
	v_max_f32_e32 v43, 0xff800000, v43
	v_max_f32_e32 v30, 0xff800000, v30
	v_max_f32_e32 v40, 0xff800000, v40
	v_max_f32_e32 v26, 0xff800000, v26
	v_max_f32_e32 v38, 0xff800000, v38
	v_max_f32_e32 v27, v35, v27
	v_max_f32_e32 v71, v69, v68
	v_min_f32_e32 v68, v69, v68
	v_max_f32_e32 v34, v42, v32
	v_max_f32_e32 v69, v43, v30
	v_max_f32_e32 v77, v40, v26
	v_max_f32_e32 v35, v38, v27
	v_min_f32_e32 v32, v42, v32
	v_max_f32_e32 v42, 0xff800000, v74
	v_max_f32_e32 v74, 0xff800000, v75
	v_min_f32_e32 v30, v43, v30
; #define PEER_CAND(a, b, cid, dst) do { const float sum_ = __uint_as_float(T0[a] & ~127u) + __uint_as_float(T1[b] & ~127u); dst = (__float_as_uint(sum_) & ~63u) | (unsigned)(cid); \
;         tab[(cid) * 64] = (unsigned short)((T0[a] & 127u) * 128u + (T1[b] & 127u)); } while (0)
; __device__ __forceinline__ void select_wave_lds(const bf16* __restrict__ skf_h, char* qtile, int h, int* __restrict__ pidx, float* __restrict__ pgate, int wid, int lane) {
;     ...
; #pragma unroll
;     for (int b = 0; b < 16; ++b) PEER_CAND(0, b, 15 - b, C[b]);
; #pragma unroll
;     for (int b = 0; b < 16; ++b) { if (b < 8) PEER_CAND(1, b, 23 - b, R1[b]); else R1[b] = KEY_NEG_INF; }
;     {   int xi = 0;
; #pragma unroll
;         for (int a = 2; a < 16; ++a)
; #pragma unroll
;             for (int b = 0; b < 16; ++b) if ((a + 1) * (b + 1) <= 16) { PEER_CAND(a, b, 24 + xi, X[xi]); ++xi; }
; #pragma unroll
;         for (int q = 26; q < 32; ++q) X[q] = KEY_NEG_INF;
;     }
;     ...
;     merge_top16(C, R1);
;     {   unsigned X16[16], Xb[16];
; #pragma unroll
;         for (int q = 0; q < 16; ++q) { X16[q] = X[q]; Xb[q] = X[16 + q]; }
;         sort16_desc(X16); sort16_desc(Xb);
;         merge_top16(X16, Xb);
;         merge_top16(C, X16); }
	v_min_f32_e32 v26, v40, v26
	v_max3_f32 v76, v65, v73, s34
	v_max_f32_e32 v60, v60, v61
	v_min_f32_e32 v61, v65, v73
	v_min_f32_e32 v73, v34, v69
	v_min_f32_e32 v78, v77, v35
	v_max_f32_e32 v34, v34, v69
	v_max_f32_e32 v35, v77, v35
	v_min_f32_e32 v27, v38, v27
	v_max_f32_e32 v75, v42, v74
	v_max_f32_e32 v40, v30, v26
	v_min_f32_e32 v79, v73, v78
	v_max_f32_e32 v73, v73, v78
	v_min_f32_e32 v69, v34, v35
	v_max3_f32 v38, v27, v32, s34
	v_max_f32_e32 v43, v75, v40
	v_min_f32_e32 v27, v27, v32
	v_max_f32_e32 v25, v59, v25
	v_max_f32_e32 v37, v37, v63
	v_min_f32_e32 v77, v73, v69
	v_min_f32_e32 v78, v38, v43
	v_max_f32_e32 v27, 0xff800000, v27
	v_min_f32_e32 v32, v75, v40
	v_min_f32_e32 v42, v42, v74
	v_min_f32_e32 v26, v30, v26
	v_max_f32_e32 v19, v64, v19
	v_min_f32_e32 v64, v60, v61
	v_min_f32_e32 v59, v25, v37
	v_max_f32_e32 v79, 0xff800000, v79
	v_min_f32_e32 v80, v77, v78
	v_max_f32_e32 v40, v27, v32
	v_max3_f32 v30, v42, v26, s34
	v_min_f32_e32 v27, v27, v32
	v_min_f32_e32 v26, v42, v26
	v_min_f32_e32 v63, v64, v59
	v_max_f32_e32 v44, v44, v66
	v_max_f32_e32 v31, v39, v31
	v_max_f32_e32 v81, v79, v80
	v_max_f32_e32 v74, v40, v30
	v_min_f32_e32 v79, v79, v80
	v_min_f32_e32 v30, v40, v30
	v_max_f32_e32 v27, 0xff800000, v27
	v_max_f32_e32 v26, 0xff800000, v26
	v_and_b32_e32 v13, 0xffffff80, v13
	v_and_b32_e32 v12, 0xffffff80, v12
	v_and_b32_e32 v11, 0xffffff80, v11
	v_and_b32_e32 v10, 0xffffff80, v10
	v_and_b32_e32 v9, 0xffffff80, v9
	v_and_b32_e32 v8, 0xffffff80, v8
	v_and_b32_e32 v7, 0xffffff80, v7
	v_and_b32_e32 v6, 0xffffff80, v6
	v_and_b32_e32 v5, 0xffffff80, v5
	v_and_b32_e32 v4, 0xffffff80, v4
	v_and_b32_e32 v3, 0xffffff80, v3
	v_min_f32_e32 v65, v19, v63
	v_min_f32_e32 v39, v44, v31
	v_min_f32_e32 v62, v67, v62
	v_min_f32_e32 v21, v29, v21
	v_max_f32_e32 v40, v79, v30
	v_max_f32_e32 v32, v27, v26
	v_min_f32_e32 v30, v79, v30
	v_max_f32_e32 v19, v19, v63
	v_max_f32_e32 v31, v44, v31
	v_max_f32_e32 v60, v60, v61
	v_max_f32_e32 v25, v25, v37
	v_min_f32_e32 v33, v33, v36
	v_min_f32_e32 v20, v28, v20
	v_max_f32_e32 v69, v73, v69
	v_max_f32_e32 v38, v38, v43
	v_min_f32_e32 v26, v27, v26
	v_add_f32_e32 v46, v45, v13
	v_add_f32_e32 v47, v45, v12
	v_add_f32_e32 v48, v45, v11
	v_add_f32_e32 v49, v45, v14
	v_add_f32_e32 v50, v45, v15
	v_add_f32_e32 v51, v45, v16
	v_add_f32_e32 v52, v45, v18
	v_add_f32_e32 v45, v45, v17
	v_add_f32_e32 v10, v53, v10
	v_add_f32_e32 v9, v53, v9
	v_add_f32_e32 v8, v53, v8
	v_add_f32_e32 v7, v53, v7
	v_add_f32_e32 v6, v53, v6
	v_add_f32_e32 v5, v53, v5
	v_add_f32_e32 v4, v53, v4
	v_add_f32_e32 v3, v53, v3
	v_add_f32_e32 v13, v53, v13
	v_add_f32_e32 v12, v53, v12
	v_add_f32_e32 v11, v53, v11
	v_add_f32_e32 v14, v53, v14
	v_add_f32_e32 v15, v53, v15
	v_add_f32_e32 v16, v53, v16
	v_add_f32_e32 v18, v53, v18
	v_add_f32_e32 v17, v53, v17
	v_min_f32_e32 v66, v65, v39
	v_max_f32_e32 v29, v62, v21
	v_min_f32_e32 v75, v81, v74
	v_max_f32_e32 v42, v32, v30
	v_max_f32_e32 v44, v19, v31
	v_max_f32_e32 v59, v64, v59
	v_min_f32_e32 v37, v60, v25
	v_max_f32_e32 v28, v33, v20
	v_min_f32_e32 v22, v41, v22
	v_max_f32_e32 v64, v77, v78
	v_min_f32_e32 v43, v69, v38
	v_min_f32_e32 v19, v19, v31
	v_max_f32_e32 v31, v65, v39
	v_min_f32_e32 v30, v32, v30
	v_max_f32_e32 v26, 0xff800000, v26
	v_and_or_b32 v46, v46, s57, 16
	v_and_or_b32 v47, v47, s57, 17
	v_and_or_b32 v48, v48, s57, 18
	v_and_or_b32 v49, v49, s57, 19
	v_and_or_b32 v50, v50, s57, 20
	v_and_or_b32 v51, v51, s57, 21
	v_and_or_b32 v52, v52, s57, 22
	v_and_or_b32 v45, v45, s57, 23
	v_and_b32_e32 v10, 0xffffffc0, v10
	v_and_or_b32 v9, v9, s57, 1
	v_and_or_b32 v8, v8, s57, 2
	v_and_or_b32 v7, v7, s57, 3
	v_and_or_b32 v6, v6, s57, 4
	v_and_or_b32 v5, v5, s57, 5
	v_and_or_b32 v4, v4, s57, 6
	v_and_or_b32 v3, v3, s57, 7
	v_and_or_b32 v13, v13, s57, 8
	v_and_or_b32 v12, v12, s57, 9
	v_and_or_b32 v11, v11, s57, 10
	v_and_or_b32 v14, v14, s57, 11
	v_and_or_b32 v15, v15, s57, 12
	v_and_or_b32 v16, v16, s57, 13
	v_and_or_b32 v18, v18, s57, 14
	v_and_or_b32 v17, v17, s57, 15
	v_min_f32_e32 v72, v71, v66
	v_max_f32_e32 v67, v68, v29
	v_min_f32_e32 v80, v75, v40
	v_min_f32_e32 v61, v59, v37
	v_max_f32_e32 v36, v28, v22
	v_min_f32_e32 v21, v62, v21
	v_max_f32_e32 v62, v81, v74
	v_min_f32_e32 v73, v64, v43
	v_max3_f32 v37, v59, v37, s34
	v_min_f32_e32 v39, v19, v31
	v_max_f32_e32 v59, v71, v66
	v_min_f32_e32 v27, v30, v26
	v_min_f32_e32 v22, v28, v22
	v_max_f32_e32 v17, v17, v17
	v_max_f32_e32 v46, v46, v46
	v_max_f32_e32 v3, v3, v3
	v_max_f32_e32 v14, v14, v14
	v_max_f32_e32 v50, v50, v50
	v_max_f32_e32 v7, v7, v7
	v_max_f32_e32 v16, v16, v16
	v_max_f32_e32 v48, v48, v48
	v_max_f32_e32 v5, v5, v5
	v_max_f32_e32 v12, v12, v12
	v_max_f32_e32 v52, v52, v52
	v_max_f32_e32 v9, v9, v9
	v_max_f32_e32 v18, v18, v18
	v_max_f32_e32 v47, v47, v47
	v_max_f32_e32 v4, v4, v4
	v_max_f32_e32 v11, v11, v11
	v_max_f32_e32 v51, v51, v51
	v_max_f32_e32 v8, v8, v8
	v_max_f32_e32 v15, v15, v15
	v_max_f32_e32 v49, v49, v49
	v_max_f32_e32 v6, v6, v6
	v_max_f32_e32 v13, v13, v13
	v_max_f32_e32 v45, v45, v45
	v_max_f32_e32 v10, v10, v10
	v_min_f32_e32 v79, v80, v42
	v_min_f32_e32 v63, v44, v61
	v_min_f32_e32 v41, v36, v21
	v_min_f32_e32 v29, v68, v29
	v_max3_f32 v27, v39, v59, v27
	v_min_f32_e32 v20, v33, v20
	v_max3_f32 v25, v60, v25, s34
	v_min_f32_e32 v60, v72, v67
	v_max3_f32 v22, v22, v64, v43
	v_max3_f32 v43, v44, v61, s34
	v_min_f32_e32 v44, v62, v73
	v_min_f32_e32 v39, v39, v59
	v_min_f32_e32 v23, v24, v23
	v_max_f32_e32 v17, 0xff800000, v17
	v_max_f32_e32 v3, v3, v46
	v_max_f32_e32 v14, 0xff800000, v14
	v_max_f32_e32 v7, v7, v50
	v_max_f32_e32 v16, 0xff800000, v16
	v_max_f32_e32 v5, v5, v48
; __device__ __forceinline__ unsigned kmax(unsigned a, unsigned b) { return __float_as_uint(__builtin_fmaxf(__uint_as_float(a), __uint_as_float(b))); }
; __device__ __forceinline__ unsigned kmin(unsigned a, unsigned b) { return __float_as_uint(__builtin_fminf(__uint_as_float(a), __uint_as_float(b))); }
; template <int N> __device__ __forceinline__ void bitonic_merge_desc(unsigned (&a)[N]) {
; #pragma unroll
;     for (int j = N >> 1; j > 0; j >>= 1)
; #pragma unroll
;         for (int i = 0; i < N; ++i) { const int l = i ^ j;
;             if (l > i) { const unsigned mx = kmax(a[i], a[l]), mn = kmin(a[i], a[l]); a[i] = mx; a[l] = mn; } }
; }
; __device__ __forceinline__ void sort16_desc(unsigned (&a)[16]) {
;     ...
;     PEER_CE(0, 13); PEER_CE(1, 12); PEER_CE(2, 15); PEER_CE(3, 14); PEER_CE(4, 8); PEER_CE(5, 6); PEER_CE(7, 11); PEER_CE(9, 10);
;     PEER_CE(0, 5); PEER_CE(1, 7); PEER_CE(2, 9); PEER_CE(3, 4); PEER_CE(6, 13); PEER_CE(8, 14); PEER_CE(10, 15); PEER_CE(11, 12);
;     PEER_CE(0, 1); PEER_CE(2, 3); PEER_CE(4, 5); PEER_CE(6, 8); PEER_CE(7, 9); PEER_CE(10, 11); PEER_CE(12, 13); PEER_CE(14, 15);
;     PEER_CE(0, 2); PEER_CE(1, 3); PEER_CE(4, 10); PEER_CE(5, 11); PEER_CE(6, 7); PEER_CE(8, 9); PEER_CE(12, 14); PEER_CE(13, 15);
;     PEER_CE(1, 2); PEER_CE(3, 12); PEER_CE(4, 6); PEER_CE(5, 7); PEER_CE(8, 10); PEER_CE(9, 11); PEER_CE(13, 14);
;     PEER_CE(1, 4); PEER_CE(2, 6); PEER_CE(5, 8); PEER_CE(7, 10); PEER_CE(9, 13); PEER_CE(11, 14);
;     PEER_CE(2, 4); PEER_CE(3, 6); PEER_CE(9, 12); PEER_CE(11, 13);
;     PEER_CE(3, 5); PEER_CE(6, 8); PEER_CE(7, 9); PEER_CE(10, 12);
;     PEER_CE(3, 4); PEER_CE(5, 6); PEER_CE(7, 8); PEER_CE(9, 10); PEER_CE(11, 12);
;     PEER_CE(6, 7); PEER_CE(8, 9);
;     ...
; }
; __device__ __forceinline__ void merge_top16(unsigned (&Lst)[16], const unsigned (&S)[16]) {
; #pragma unroll
;     for (int i = 0; i < 16; ++i) Lst[i] = kmax(Lst[i], S[15 - i]);
;     bitonic_merge_desc<16>(Lst);
; }
; __device__ __forceinline__ void select_wave_lds(const bf16* __restrict__ skf_h, char* qtile, int h, int* __restrict__ pidx, float* __restrict__ pgate, int wid, int lane) {
;     ...
;     merge_top16(C, R1);
;     {   unsigned X16[16], Xb[16];
; #pragma unroll
;         for (int q = 0; q < 16; ++q) { X16[q] = X[q]; Xb[q] = X[16 + q]; }
;         sort16_desc(X16); sort16_desc(Xb);
;         merge_top16(X16, Xb);
;         merge_top16(C, X16); }
	v_max_f32_e32 v12, 0xff800000, v12
	v_max_f32_e32 v9, v9, v52
	v_max_f32_e32 v18, 0xff800000, v18
	v_max_f32_e32 v4, v4, v47
	v_max_f32_e32 v11, 0xff800000, v11
	v_max_f32_e32 v8, v8, v51
	v_max_f32_e32 v15, 0xff800000, v15
	v_max_f32_e32 v6, v6, v49
	v_max_f32_e32 v13, 0xff800000, v13
	v_max_f32_e32 v10, v10, v45
	v_max3_f32 v79, v72, v67, v79
	v_max_f32_e32 v63, 0xff800000, v63
	v_max3_f32 v41, v41, v62, v73
	v_max3_f32 v29, v29, v75, v40
	v_max3_f32 v20, v20, v69, v38
	v_max3_f32 v42, v60, v80, v42
	v_max3_f32 v19, v19, v31, s34
	v_max3_f32 v21, v36, v21, v44
	v_max3_f32 v26, v39, v30, v26
	v_max3_f32 v23, v23, v34, v35
	v_max_f32_e32 v46, v17, v3
	v_max_f32_e32 v50, v14, v7
	v_max_f32_e32 v48, v16, v5
	v_max_f32_e32 v52, v12, v9
	v_max_f32_e32 v47, v18, v4
	v_max_f32_e32 v51, v11, v8
	v_max_f32_e32 v49, v15, v6
	v_max_f32_e32 v45, v13, v10
	v_min_f32_e32 v40, v37, v29
	v_min_f32_e32 v32, v27, v20
	v_min_f32_e32 v60, v25, v42
	v_min_f32_e32 v28, v19, v22
	v_min_f32_e32 v36, v43, v21
	v_min_f32_e32 v24, v26, v23
	v_min_f32_e32 v3, v17, v3
	v_min_f32_e32 v7, v14, v7
	v_min_f32_e32 v5, v16, v5
	v_min_f32_e32 v9, v12, v9
	v_min_f32_e32 v4, v18, v4
	v_min_f32_e32 v8, v11, v8
	v_min_f32_e32 v6, v15, v6
	v_min_f32_e32 v10, v13, v10
	v_max_f32_e32 v17, v76, v79
	v_max_f32_e32 v18, v63, v41
	v_max_f32_e32 v29, v37, v29
	v_max_f32_e32 v20, v27, v20
	v_max_f32_e32 v25, v25, v42
	v_max_f32_e32 v19, v19, v22
	v_max_f32_e32 v21, v43, v21
	v_max_f32_e32 v23, v26, v23
	v_max_f32_e32 v14, v3, v7
	v_max_f32_e32 v12, v5, v9
	v_max_f32_e32 v11, v4, v8
	v_max_f32_e32 v13, v6, v10
	v_min_f32_e32 v39, v17, v18
	v_min_f32_e32 v27, v29, v20
	v_min_f32_e32 v22, v25, v19
	v_min_f32_e32 v26, v21, v23
	v_min_f32_e32 v5, v5, v9
	v_min_f32_e32 v6, v6, v10
	v_max_f32_e32 v9, v17, v18
	v_max_f32_e32 v10, v29, v20
	v_max_f32_e32 v18, v25, v19
	v_max_f32_e32 v19, v21, v23
	v_min_f32_e32 v82, v76, v79
	v_min_f32_e32 v74, v63, v41
	v_max_f32_e32 v16, v14, v12
	v_max_f32_e32 v15, v11, v13
	v_min_f32_e32 v37, v39, v27
	v_min_f32_e32 v41, v22, v26
	v_min_f32_e32 v3, v3, v7
	v_min_f32_e32 v4, v4, v8
	v_min_f32_e32 v17, v9, v10
	v_min_f32_e32 v20, v18, v19
	v_min_f32_e32 v12, v14, v12
	v_min_f32_e32 v11, v11, v13
	v_max_f32_e32 v13, v39, v27
	v_max_f32_e32 v14, v22, v26
	v_max_f32_e32 v53, v46, v50
	v_max_f32_e32 v54, v48, v52
	v_max_f32_e32 v56, v47, v51
	v_max_f32_e32 v57, v49, v45
	v_min_f32_e32 v77, v82, v74
	v_min_f32_e32 v33, v40, v32
	v_min_f32_e32 v31, v60, v28
	v_min_f32_e32 v30, v36, v24
	v_min_f32_e32 v42, v37, v41
	v_min_f32_e32 v44, v46, v50
	v_min_f32_e32 v46, v48, v52
	v_min_f32_e32 v47, v47, v51
	v_min_f32_e32 v45, v49, v45
	v_max_f32_e32 v50, v82, v74
	v_max_f32_e32 v32, v40, v32
	v_max_f32_e32 v28, v60, v28
	v_max_f32_e32 v24, v36, v24
	v_max_f32_e32 v7, v3, v5
	v_max_f32_e32 v8, v4, v6
	v_min_f32_e32 v21, v17, v20
	v_min_f32_e32 v22, v13, v14
	v_min_f32_e32 v3, v3, v5
	v_min_f32_e32 v4, v4, v6
	v_max_f32_e32 v5, v9, v10
	v_max_f32_e32 v6, v18, v19
	v_max_f32_e32 v55, v53, v54
	v_max_f32_e32 v58, v56, v57
	v_min_f32_e32 v38, v77, v33
	v_min_f32_e32 v34, v31, v30
	v_max3_f32 v42, v16, v15, v42
	v_max_f32_e32 v48, v44, v46
	v_max_f32_e32 v49, v47, v45
	v_min_f32_e32 v40, v50, v32
	v_min_f32_e32 v36, v28, v24
	v_max3_f32 v21, v7, v8, v21
	v_min_f32_e32 v29, v53, v54
	v_min_f32_e32 v52, v56, v57
	v_max_f32_e32 v33, v77, v33
	v_max_f32_e32 v30, v31, v30
	v_max3_f32 v22, v12, v11, v22
	v_min_f32_e32 v27, v44, v46
	v_min_f32_e32 v39, v47, v45
	v_max_f32_e32 v32, v50, v32
	v_max_f32_e32 v24, v28, v24
	v_min_f32_e32 v9, v5, v6
	v_min_f32_e32 v15, v16, v15
	v_min_f32_e32 v7, v7, v8
	v_min_f32_e32 v11, v12, v11
	v_min_f32_e32 v35, v38, v34
	v_min_f32_e32 v51, v40, v36
	v_min_f32_e32 v31, v33, v30
	v_min_f32_e32 v28, v32, v24
	v_max3_f32 v9, v3, v4, v9
	v_min_f32_e32 v44, v55, v58
	v_max3_f32 v15, v15, v37, v41
	v_min_f32_e32 v37, v48, v49
	v_max3_f32 v7, v7, v17, v20
	v_min_f32_e32 v20, v29, v52
	v_max3_f32 v11, v11, v13, v14
	v_min_f32_e32 v13, v27, v39
	v_min_f32_e32 v3, v3, v4
	v_max3_f32 v35, v55, v58, v35
	v_max3_f32 v51, v48, v49, v51
	v_max3_f32 v31, v29, v52, v31
	v_max3_f32 v28, v27, v39, v28
	v_max3_f32 v34, v44, v38, v34
	v_max3_f32 v36, v37, v40, v36
	v_max3_f32 v20, v20, v33, v30
	v_max3_f32 v13, v13, v32, v24
	v_max3_f32 v3, v3, v5, v6
	v_max_f32_e32 v43, v35, v42
	v_max_f32_e32 v23, v51, v21
	v_max_f32_e32 v26, v31, v22
	v_max_f32_e32 v10, v28, v9
	v_max_f32_e32 v16, v34, v15
	v_max_f32_e32 v8, v36, v7
	v_max_f32_e32 v12, v20, v11
	v_max_f32_e32 v4, v13, v3
	v_max_f32_e32 v25, v43, v23
	v_max_f32_e32 v18, v26, v10
	v_max_f32_e32 v17, v16, v8
	v_max_f32_e32 v5, v12, v4
	v_max_f32_e32 v19, v25, v18
	v_max_f32_e32 v6, v17, v5
	v_min_f32_e32 v18, v25, v18
	v_min_f32_e32 v5, v17, v5
	v_max_f32_e32 v17, v18, v5
	v_min_f32_e32 v18, v18, v5
	v_min_f32_e32 v5, v43, v23
	v_min_f32_e32 v10, v26, v10
	v_min_f32_e32 v8, v16, v8
	v_min_f32_e32 v4, v12, v4
	v_max_f32_e32 v23, v5, v10
	v_max_f32_e32 v12, v8, v4
	v_min_f32_e32 v5, v5, v10
	v_min_f32_e32 v4, v8, v4
	v_max_f32_e32 v32, v5, v4
	v_min_f32_e32 v33, v5, v4
	v_min_f32_e32 v4, v35, v42
	v_min_f32_e32 v5, v51, v21
	v_min_f32_e32 v10, v31, v22
	v_min_f32_e32 v9, v28, v9
	v_min_f32_e32 v15, v34, v15
	v_min_f32_e32 v7, v36, v7
	v_min_f32_e32 v11, v20, v11
	v_min_f32_e32 v3, v13, v3
	v_max_f32_e32 v16, v23, v12
	v_min_f32_e32 v12, v23, v12
	v_max_f32_e32 v8, v4, v5
	v_max_f32_e32 v21, v10, v9
	v_max_f32_e32 v23, v15, v7
	v_max_f32_e32 v13, v11, v3
	v_max_f32_e32 v14, v19, v6
	v_max_f32_e32 v22, v8, v21
	v_max_f32_e32 v20, v23, v13
	v_min_f32_e32 v8, v8, v21
	v_min_f32_e32 v13, v23, v13
	v_min_f32_e32 v4, v4, v5
; __device__ __forceinline__ void select_wave_lds(const bf16* __restrict__ skf_h, char* qtile, int h, int* __restrict__ pidx, float* __restrict__ pgate, int wid, int lane) {
;     ...
;     asm volatile("s_waitcnt lgkmcnt(0)" ::: "memory");
;     float v[16]; float sum = 0.f; const float mx = __uint_as_float(C[0] & ~63u);
; #pragma unroll
;     for (int s = 0; s < 16; ++s) { v[s] = __expf(__uint_as_float(C[s] & ~63u) - mx); sum += v[s]; }
;     const float inv = 1.f / sum;
;     int ex[16];
; #pragma unroll
;     for (int s = 0; s < 16; ++s) ex[s] = (int)tab[(C[s] & 63u) * 64];
;     if (hi == 0) {
;         int* pi = pidx + (size_t)(wid * 32 + r32) * 128 + h * 16; float* pg = pgate + (size_t)(wid * 32 + r32) * 128 + h * 16;
; #pragma unroll
;         for (int s = 0; s < 16; s += 4) { *(int4*)(pi + s) = make_int4(ex[s], ex[s + 1], ex[s + 2], ex[s + 3]); *(f32x4*)(pg + s) = (f32x4){v[s] * inv, v[s + 1] * inv, v[s + 2] * inv, v[s + 3] * inv}; }
;     }
	v_min_f32_e32 v5, v10, v9
	v_min_f32_e32 v7, v15, v7
	v_min_f32_e32 v3, v11, v3
	v_min_f32_e32 v19, v19, v6
	v_max_f32_e32 v28, v8, v13
	v_min_f32_e32 v8, v8, v13
	v_max_f32_e32 v9, v4, v5
	v_max_f32_e32 v10, v7, v3
	v_and_b32_e32 v13, 0xffffffc0, v14
	v_and_b32_e32 v6, 0xffffffc0, v19
	v_max_f32_e32 v11, v9, v10
	v_min_f32_e32 v9, v9, v10
	v_sub_f32_e32 v10, v13, v13
	v_mul_f32_e32 v10, 0x3fb8aa3b, v10
	v_sub_f32_e32 v6, v6, v13
	v_max_f32_e32 v30, v22, v20
	v_min_f32_e32 v31, v22, v20
	v_min_f32_e32 v4, v4, v5
	v_min_f32_e32 v3, v7, v3
	v_exp_f32_e32 v20, v10
	v_mul_f32_e32 v6, 0x3fb8aa3b, v6
	v_max_f32_e32 v5, v4, v3
	v_exp_f32_e32 v21, v6
	v_min_f32_e32 v3, v4, v3
	v_and_b32_e32 v4, 0xffffffc0, v3
	v_sub_f32_e32 v4, v4, v13
	v_and_b32_e32 v7, 0xffffffc0, v5
	v_add_f32_e32 v6, 0, v20
	v_mul_f32_e32 v4, 0x3fb8aa3b, v4
	v_add_f32_e32 v15, v21, v6
	v_sub_f32_e32 v6, v7, v13
	v_exp_f32_e32 v23, v4
	v_lshlrev_b32_e32 v4, 7, v5
	v_and_b32_e32 v5, 0xffffffc0, v11
	v_mul_f32_e32 v6, 0x3fb8aa3b, v6
	v_sub_f32_e32 v5, v5, v13
	v_exp_f32_e32 v22, v6
	v_and_b32_e32 v6, 0xffffffc0, v9
	v_mul_f32_e32 v5, 0x3fb8aa3b, v5
	v_exp_f32_e32 v24, v5
	v_sub_f32_e32 v5, v6, v13
	v_mul_f32_e32 v5, 0x3fb8aa3b, v5
	v_exp_f32_e32 v25, v5
	v_lshlrev_b32_e32 v5, 6, v11
	v_and_b32_e32 v5, 0xfc0, v5
	v_lshlrev_b32_e32 v6, 6, v9
	v_lshl_add_u32 v10, v5, 1, v2
	v_and_b32_e32 v5, 0xffffffc0, v28
	v_and_b32_e32 v6, 0xfc0, v6
	v_sub_f32_e32 v5, v5, v13
	v_lshl_add_u32 v9, v6, 1, v2
	v_and_b32_e32 v6, 0xffffffc0, v8
	v_mul_f32_e32 v5, 0x3fb8aa3b, v5
	v_exp_f32_e32 v26, v5
	v_sub_f32_e32 v5, v6, v13
	v_mul_f32_e32 v5, 0x3fb8aa3b, v5
	v_exp_f32_e32 v27, v5
	v_lshlrev_b32_e32 v5, 6, v28
	v_and_b32_e32 v5, 0xfc0, v5
	v_lshlrev_b32_e32 v6, 6, v8
	v_lshl_add_u32 v34, v5, 1, v2
	v_and_b32_e32 v5, 0xffffffc0, v30
	v_and_b32_e32 v6, 0xfc0, v6
	v_sub_f32_e32 v5, v5, v13
	v_lshl_add_u32 v8, v6, 1, v2
	v_and_b32_e32 v6, 0xffffffc0, v31
	v_mul_f32_e32 v5, 0x3fb8aa3b, v5
	v_exp_f32_e32 v28, v5
	v_sub_f32_e32 v5, v6, v13
	v_lshlrev_b32_e32 v3, 7, v3
	v_mul_f32_e32 v5, 0x3fb8aa3b, v5
	v_and_b32_e32 v3, 0x1f80, v3
	v_and_b32_e32 v4, 0x1f80, v4
	v_exp_f32_e32 v29, v5
	v_lshlrev_b32_e32 v5, 6, v30
	v_lshlrev_b32_e32 v6, 6, v31
	v_add_u32_e32 v3, v2, v3
	v_add_u32_e32 v4, v2, v4
	v_and_b32_e32 v5, 0xfc0, v5
	v_and_b32_e32 v6, 0xfc0, v6
	v_lshl_add_u32 v30, v6, 1, v2
	v_lshl_add_u32 v31, v5, 1, v2
	ds_read_u16 v7, v3
	ds_read_u16 v6, v4
	ds_read_u16 v5, v9
	ds_read_u16 v4, v10
	ds_read_u16 v11, v8
	ds_read_u16 v10, v34
	ds_read_u16 v9, v30
	ds_read_u16 v8, v31
	v_and_b32_e32 v3, 0xffffffc0, v32
	v_sub_f32_e32 v3, v3, v13
	v_and_b32_e32 v31, 0xffffffc0, v33
	v_mul_f32_e32 v3, 0x3fb8aa3b, v3
	v_exp_f32_e32 v30, v3
	v_sub_f32_e32 v3, v31, v13
	v_mul_f32_e32 v3, 0x3fb8aa3b, v3
	v_exp_f32_e32 v31, v3
	v_lshlrev_b32_e32 v3, 6, v32
	v_lshlrev_b32_e32 v32, 6, v33
	v_and_b32_e32 v32, 0xfc0, v32
	v_and_b32_e32 v34, 0xffffffc0, v17
	v_lshl_add_u32 v37, v32, 1, v2
	v_and_b32_e32 v32, 0xffffffc0, v16
	v_and_b32_e32 v33, 0xffffffc0, v12
	v_and_b32_e32 v35, 0xffffffc0, v18
	v_sub_f32_e32 v34, v34, v13
	v_sub_f32_e32 v32, v32, v13
	v_sub_f32_e32 v33, v33, v13
	v_mul_f32_e32 v34, 0x3fb8aa3b, v34
	v_sub_f32_e32 v13, v35, v13
	v_exp_f32_e32 v34, v34
	v_mul_f32_e32 v13, 0x3fb8aa3b, v13
	v_mul_f32_e32 v32, 0x3fb8aa3b, v32
	v_exp_f32_e32 v35, v13
	v_exp_f32_e32 v32, v32
	v_mul_f32_e32 v33, 0x3fb8aa3b, v33
	v_exp_f32_e32 v33, v33
	v_add_f32_e32 v15, v34, v15
	v_add_f32_e32 v15, v35, v15
	v_add_f32_e32 v15, v32, v15
	v_add_f32_e32 v15, v33, v15
	v_add_f32_e32 v15, v30, v15
	v_add_f32_e32 v15, v31, v15
	v_add_f32_e32 v15, v28, v15
	v_add_f32_e32 v15, v29, v15
	v_add_f32_e32 v15, v26, v15
	v_add_f32_e32 v15, v27, v15
	v_add_f32_e32 v15, v24, v15
	v_add_f32_e32 v15, v25, v15
	v_add_f32_e32 v15, v22, v15
	v_lshlrev_b32_e32 v16, 6, v16
	v_add_f32_e32 v15, v23, v15
	v_and_b32_e32 v13, 0xfc0, v16
	v_div_scale_f32 v16, s[40:41], v15, v15, 1.0
	v_rcp_f32_e32 v36, v16
	v_lshl_add_u32 v38, v13, 1, v2
	v_lshlrev_b32_e32 v12, 6, v12
	s_lshl_b64 s[36:37], s[24:25], 17
	v_fma_f32 v13, -v16, v36, 1.0
	v_fmac_f32_e32 v36, v13, v36
	v_div_scale_f32 v13, vcc, 1.0, v15, 1.0
	v_mul_f32_e32 v39, v13, v36
	v_fma_f32 v40, -v16, v39, v13
	v_fmac_f32_e32 v39, v40, v36
	v_fma_f32 v13, -v16, v39, v13
	v_div_fmas_f32 v13, v13, v36, v39
	v_div_fixup_f32 v36, v13, v15, 1.0
	v_lshlrev_b32_e32 v13, 6, v17
	v_and_b32_e32 v13, 0xfc0, v13
	v_lshl_add_u32 v17, v13, 1, v2
	v_lshlrev_b32_e32 v13, 7, v19
	v_and_b32_e32 v13, 0x1f80, v13
	v_lshlrev_b32_e32 v15, 6, v18
	v_add_u32_e32 v39, v2, v13
	v_lshlrev_b32_e32 v13, 7, v14
	v_readlane_b32 s3, v240, 26
	v_and_b32_e32 v3, 0xfc0, v3
	v_and_b32_e32 v12, 0xfc0, v12
	v_and_b32_e32 v15, 0xfc0, v15
	v_and_b32_e32 v13, 0x1f80, v13
	s_add_u32 s16, s3, s36
	v_readlane_b32 s3, v240, 27
	v_lshl_add_u32 v3, v3, 1, v2
	v_lshl_add_u32 v12, v12, 1, v2
	v_lshl_add_u32 v16, v15, 1, v2
	v_add_u32_e32 v2, v2, v13
	s_addc_u32 s17, s3, s37
	v_readlane_b32 s3, v240, 10
	ds_read_u16 v15, v37
	ds_read_u16 v14, v3
	ds_read_u16 v13, v12
	ds_read_u16 v12, v38
	ds_read_u16 v19, v16
	ds_read_u16 v18, v17
	ds_read_u16 v17, v39
	ds_read_u16 v16, v2
	v_lshl_or_b32 v2, s72, 5, v70
	s_add_u32 s36, s3, s36
	v_readlane_b32 s3, v240, 6
	v_ashrrev_i32_e32 v3, 31, v2
	s_addc_u32 s37, s3, s37
	v_lshlrev_b64 v[2:3], 9, v[2:3]
	v_lshl_add_u64 v[38:39], s[36:37], 0, v[2:3]
	s_lshl_b32 s36, s22, 4
	s_ashr_i32 s37, s36, 31
	s_lshl_b64 s[36:37], s[36:37], 2
	v_lshl_add_u64 v[38:39], v[38:39], 0, s[36:37]
	v_lshl_add_u64 v[2:3], s[16:17], 0, v[2:3]
	v_lshl_add_u64 v[40:41], v[2:3], 0, s[36:37]
	s_waitcnt lgkmcnt(0)
	global_store_dwordx4 v[38:39], v[16:19], off
	v_mul_f32_e32 v2, v24, v36
	v_mul_f32_e32 v3, v25, v36
	s_nop 0
	v_mul_f32_e32 v18, v34, v36
	v_mul_f32_e32 v19, v35, v36
	v_mul_f32_e32 v16, v20, v36
	v_mul_f32_e32 v17, v21, v36
	global_store_dwordx4 v[40:41], v[16:19], off
	global_store_dwordx4 v[38:39], v[12:15], off offset:16
	s_nop 1
	v_mul_f32_e32 v14, v30, v36
	v_mul_f32_e32 v15, v31, v36
	v_mul_f32_e32 v12, v32, v36
	v_mul_f32_e32 v13, v33, v36
	global_store_dwordx4 v[40:41], v[12:15], off offset:16
	global_store_dwordx4 v[38:39], v[8:11], off offset:32
	s_nop 1
	v_mul_f32_e32 v10, v26, v36
	v_mul_f32_e32 v11, v27, v36
	v_mul_f32_e32 v8, v28, v36
	v_mul_f32_e32 v9, v29, v36
	global_store_dwordx4 v[40:41], v[8:11], off offset:32
	global_store_dwordx4 v[38:39], v[4:7], off offset:48
	s_nop 1
	v_mul_f32_e32 v4, v22, v36
	v_mul_f32_e32 v5, v23, v36
	global_store_dwordx4 v[40:41], v[2:5], off offset:48
; __device__ __forceinline__ void quant_h2_wave(int t0w, int c, const bf16* __restrict__ x1a, const float* __restrict__ ssq, const float* __restrict__ mod,
;                                               unsigned char* __restrict__ HQ, float* __restrict__ HS, int lane) {
;     ...
;         const int t = t0w + pass * 8 + (lane >> 3), b = t >> 11;
;         const f32x4 s0 = *(const f32x4*)(ssq + (size_t)t * 16), s1 = *(const f32x4*)(ssq + (size_t)t * 16 + 4), s2 = *(const f32x4*)(ssq + (size_t)t * 16 + 8), s3 = *(const f32x4*)(ssq + (size_t)t * 16 + 12);
;         const float tot = ((s0.x + s0.y) + (s0.z + s0.w)) + ((s1.x + s1.y) + (s1.z + s1.w)) + ((s2.x + s2.y) + (s2.z + s2.w)) + ((s3.x + s3.y) + (s3.z + s3.w));
;         const float rstd = rsqrtf(tot * (1.f / 1024.f) + 1e-6f);
;         const float* be = mod + (size_t)b * 6144 + 3 * 1024 + k0;
;         f32x4 hv[8]; float am = 0.f;
; #pragma unroll
;         for (int u = 0; u < 4; ++u) { const v4u xa = *(const v4u*)(x1a + (size_t)t * 1024 + k0 + 8 * u);
; #pragma unroll
;             for (int hh = 0; hh < 2; ++hh) { const unsigned w0 = xa[2 * hh], w1 = xa[2 * hh + 1];
;                 const f32x4 xv = {__builtin_bit_cast(float, w0 << 16), __builtin_bit_cast(float, w0 & 0xffff0000u), __builtin_bit_cast(float, w1 << 16), __builtin_bit_cast(float, w1 & 0xffff0000u)};
;                 const f32x4 h = xv * rstd + *(const f32x4*)(be + 8 * u + 4 * hh); hv[2 * u + hh] = h;
;                 am = fmaxf(am, fmaxf(fmaxf(fabsf(h.x), fabsf(h.y)), fmaxf(fabsf(h.z), fabsf(h.w)))); } }
.LBB0_809:
	s_or_b64 exec, exec, s[0:1]
	s_lshl_b32 s0, s24, 8
	s_lshl_b32 s1, s22, 7
	s_and_b32 s1, s1, 0x80
	s_add_i32 s0, s0, s50
	s_add_i32 s3, s0, s1
	v_or_b32_e32 v30, s3, v1
	v_ashrrev_i32_e32 v31, 31, v30
	v_lshlrev_b64 v[2:3], 6, v[30:31]
	v_lshl_add_u64 v[14:15], s[8:9], 0, v[2:3]
	global_load_dwordx4 v[64:67], v[14:15], off offset:48
	global_load_dwordx4 v[60:63], v[14:15], off offset:32
	global_load_dwordx4 v[56:59], v[14:15], off offset:16
	global_load_dwordx4 v[52:55], v[14:15], off
	global_load_dwordx4 v[80:83], v[14:15], off offset:560
	global_load_dwordx4 v[76:79], v[14:15], off offset:544
	global_load_dwordx4 v[72:75], v[14:15], off offset:528
	global_load_dwordx4 v[68:71], v[14:15], off offset:512
	s_ashr_i32 s0, s22, 1
	v_lshl_or_b32 v18, s0, 8, v146
	s_ashr_i32 s1, s0, 31
	v_ashrrev_i32_e32 v19, 31, v18
	s_lshl_b64 s[16:17], s[0:1], 14
	s_ashr_i32 s0, s3, 11
	v_lshl_add_u64 v[28:29], v[18:19], 1, s[44:45]
	s_mul_hi_i32 s1, s0, 0x6000
	s_mulk_i32 s0, 0x6000
	s_add_u32 s0, s28, s0
	s_addc_u32 s1, s29, s1
	v_lshl_add_u64 v[18:19], v[18:19], 2, s[0:1]
	s_mov_b64 s[0:1], 0x3000
	v_lshl_add_u64 v[26:27], v[18:19], 0, s[0:1]
	v_lshlrev_b64 v[200:201], 11, v[30:31]
	v_lshl_add_u64 v[200:201], v[28:29], 0, v[200:201]
	s_mov_b64 s[40:41], 0x4000
	v_lshl_add_u64 v[202:203], v[200:201], 0, s[40:41]
	global_load_dwordx4 v[96:99], v[200:201], off offset:48
	global_load_dwordx4 v[92:95], v[200:201], off offset:32
	global_load_dwordx4 v[88:91], v[200:201], off offset:16
	global_load_dwordx4 v[84:87], v[200:201], off
	global_load_dwordx4 v[112:115], v[202:203], off offset:48
	global_load_dwordx4 v[108:111], v[202:203], off offset:32
	global_load_dwordx4 v[104:107], v[202:203], off offset:16
	global_load_dwordx4 v[100:103], v[202:203], off
	global_load_dwordx4 v[168:171], v[26:27], off
	global_load_dwordx4 v[172:175], v[26:27], off offset:16
	global_load_dwordx4 v[176:179], v[26:27], off offset:32
	global_load_dwordx4 v[180:183], v[26:27], off offset:48
	global_load_dwordx4 v[184:187], v[26:27], off offset:64
	global_load_dwordx4 v[188:191], v[26:27], off offset:80
	global_load_dwordx4 v[192:195], v[26:27], off offset:96
	global_load_dwordx4 v[196:199], v[26:27], off offset:112
	s_waitcnt vmcnt(0)
	v_mov_b32_e32 v2, v64
	v_mov_b32_e32 v3, v65
	v_mov_b32_e32 v4, v66
	v_mov_b32_e32 v5, v67
	v_mov_b32_e32 v6, v60
	v_mov_b32_e32 v7, v61
	v_mov_b32_e32 v8, v62
	v_mov_b32_e32 v9, v63
	v_mov_b32_e32 v10, v56
	v_mov_b32_e32 v11, v57
	v_mov_b32_e32 v12, v58
	v_mov_b32_e32 v13, v59
	v_mov_b32_e32 v14, v52
	v_mov_b32_e32 v15, v53
	v_mov_b32_e32 v16, v54
	v_mov_b32_e32 v17, v55
	s_waitcnt vmcnt(2)
	v_add_f32_e32 v6, v6, v7
	v_add_f32_e32 v8, v8, v9
	s_waitcnt vmcnt(0)
	v_mov_b32_e32 v20, v15
	v_mov_b32_e32 v21, v16
	v_mov_b32_e32 v15, v17
	v_mov_b32_e32 v16, v11
	v_mov_b32_e32 v17, v12
	v_mov_b32_e32 v11, v13
	v_add_f32_e32 v14, v20, v14
	v_add_f32_e32 v15, v21, v15
	v_add_f32_e32 v10, v16, v10
	v_add_f32_e32 v11, v17, v11
	v_pk_add_f32 v[14:15], v[14:15], v[14:15] op_sel:[0,1] op_sel_hi:[1,0]
	v_pk_add_f32 v[10:11], v[10:11], v[10:11] op_sel:[0,1] op_sel_hi:[1,0]
	v_mov_b32_e32 v15, v2
	v_mov_b32_e32 v11, v3
	v_mov_b32_e32 v7, v4
	v_mov_b32_e32 v9, v5
	v_add_f32_e32 v2, v14, v10
	v_add_f32_e32 v3, v15, v11
	v_add_f32_e32 v4, v6, v8
	v_add_f32_e32 v5, v7, v9
	s_nop 0
	v_add_f32_e32 v2, v2, v4
	v_add_f32_e32 v3, v3, v5
	s_nop 0
	v_add_f32_e32 v2, v2, v3
	v_fmamk_f32 v2, v2, 0x3a800000, v147
	v_cmp_gt_f32_e32 vcc, s59, v2
	v_mul_f32_e32 v3, 0x4b800000, v2
	s_nop 0
	v_cndmask_b32_e32 v2, v2, v3, vcc
	v_rsq_f32_e32 v2, v2
	s_nop 0
	v_mul_f32_e32 v3, 0x45800000, v2
	v_cndmask_b32_e32 v38, v2, v3, vcc
	v_lshlrev_b64 v[2:3], 11, v[30:31]
	v_lshl_add_u64 v[14:15], v[28:29], 0, v[2:3]
	v_mov_b32_e32 v2, v96
	v_mov_b32_e32 v3, v97
	v_mov_b32_e32 v4, v98
	v_mov_b32_e32 v5, v99
	v_mov_b32_e32 v6, v92
	v_mov_b32_e32 v7, v93
	v_mov_b32_e32 v8, v94
	v_mov_b32_e32 v9, v95
	v_mov_b32_e32 v10, v88
	v_mov_b32_e32 v11, v89
	v_mov_b32_e32 v12, v90
	v_mov_b32_e32 v13, v91
	s_nop 0
	v_mov_b32_e32 v14, v84
	v_mov_b32_e32 v15, v85
	v_mov_b32_e32 v16, v86
	v_mov_b32_e32 v17, v87
	v_add_co_u32_e32 v18, vcc, s19, v18
	s_waitcnt vmcnt(2)
	v_lshlrev_b32_e32 v50, 16, v6
	v_addc_co_u32_e32 v19, vcc, 0, v19, vcc
	v_mov_b32_e32 v18, v168
	v_mov_b32_e32 v19, v169
	v_mov_b32_e32 v20, v170
	v_mov_b32_e32 v21, v171
	s_nop 0
	v_mov_b32_e32 v22, v180
	v_mov_b32_e32 v23, v181
	v_mov_b32_e32 v24, v182
	v_mov_b32_e32 v25, v183
	v_mov_b32_e32 v32, v176
	v_mov_b32_e32 v33, v177
	v_mov_b32_e32 v34, v178
	v_mov_b32_e32 v35, v179
	v_mov_b32_e32 v40, v172
	v_mov_b32_e32 v41, v173
	v_mov_b32_e32 v42, v174
	v_mov_b32_e32 v43, v175
	s_waitcnt vmcnt(4)
	v_lshlrev_b32_e32 v36, 16, v14
	v_and_b32_e32 v37, 0xffff0000, v14
	v_lshlrev_b32_e32 v14, 16, v15
	v_and_b32_e32 v15, 0xffff0000, v15
	v_and_b32_e32 v51, 0xffff0000, v6
	v_lshlrev_b32_e32 v6, 16, v7
	v_and_b32_e32 v7, 0xffff0000, v7
	s_waitcnt vmcnt(3)
	v_fma_f32 v46, v38, v14, v20
	v_fma_f32 v47, v38, v15, v21
	v_fma_f32 v48, v38, v36, v18
	v_fma_f32 v49, v38, v37, v19
	v_max_f32_e64 v14, |v46|, |v47|
	v_max3_f32 v18, |v48|, |v49|, v14
	v_lshlrev_b32_e32 v14, 16, v16
	v_and_b32_e32 v15, 0xffff0000, v16
	v_lshlrev_b32_e32 v16, 16, v17
	v_and_b32_e32 v17, 0xffff0000, v17
	s_waitcnt vmcnt(0)
; __device__ __forceinline__ void quant_h2_wave(int t0w, int c, const bf16* __restrict__ x1a, const float* __restrict__ ssq, const float* __restrict__ mod,
;                                               unsigned char* __restrict__ HQ, float* __restrict__ HS, int lane) {
;     ...
;         f32x4 hv[8]; float am = 0.f;
; #pragma unroll
;         for (int u = 0; u < 4; ++u) { const v4u xa = *(const v4u*)(x1a + (size_t)t * 1024 + k0 + 8 * u);
; #pragma unroll
;             for (int hh = 0; hh < 2; ++hh) { const unsigned w0 = xa[2 * hh], w1 = xa[2 * hh + 1];
;                 const f32x4 xv = {__builtin_bit_cast(float, w0 << 16), __builtin_bit_cast(float, w0 & 0xffff0000u), __builtin_bit_cast(float, w1 << 16), __builtin_bit_cast(float, w1 & 0xffff0000u)};
;                 const f32x4 h = xv * rstd + *(const f32x4*)(be + 8 * u + 4 * hh); hv[2 * u + hh] = h;
;                 am = fmaxf(am, fmaxf(fmaxf(fabsf(h.x), fabsf(h.y)), fmaxf(fabsf(h.z), fabsf(h.w)))); } }
;         am = max8_dpp(am);
;         const float sc = am > 0.f ? 119.f / am : 0.f;
;         v4u oa, ob;
; #pragma unroll
;         for (int k = 0; k < 4; ++k) { unsigned wa = 0u, wb = 0u;
; #pragma unroll
;             for (int i = 0; i < 8; ++i) { const float f = (i < 4) ? hv[2 * k][i] : hv[2 * k + 1][i - 4]; const int q = (int)rintf(f * sc); const int ahi = (q + 8) >> 4, blo = q - 16 * ahi;
;                 wa |= ((unsigned)ahi & 15u) << (4 * i); wb |= ((unsigned)blo & 15u) << (4 * i); }
	v_fma_f32 v42, v38, v16, v42
	v_fma_f32 v43, v38, v17, v43
	v_fma_f32 v44, v38, v14, v40
	v_fma_f32 v45, v38, v15, v41
	v_max_f32_e64 v14, |v42|, |v43|
	v_max3_f32 v14, |v44|, |v45|, v14
	v_max3_f32 v16, v18, 0, v14
	v_lshlrev_b32_e32 v14, 16, v10
	v_and_b32_e32 v15, 0xffff0000, v10
	v_lshlrev_b32_e32 v10, 16, v11
	v_and_b32_e32 v11, 0xffff0000, v11
	v_fma_f32 v36, v38, v10, v34
	v_fma_f32 v37, v38, v11, v35
	v_fma_f32 v40, v38, v14, v32
	v_fma_f32 v41, v38, v15, v33
	v_max_f32_e64 v10, |v36|, |v37|
	v_max3_f32 v14, |v40|, |v41|, v10
	v_lshlrev_b32_e32 v10, 16, v12
	v_and_b32_e32 v11, 0xffff0000, v12
	v_lshlrev_b32_e32 v12, 16, v13
	v_and_b32_e32 v13, 0xffff0000, v13
	v_fma_f32 v32, v38, v12, v24
	v_fma_f32 v33, v38, v13, v25
	v_fma_f32 v34, v38, v10, v22
	v_fma_f32 v35, v38, v11, v23
	v_max_f32_e64 v10, |v32|, |v33|
	v_max3_f32 v10, |v34|, |v35|, v10
	v_max3_f32 v39, v16, v14, v10
	v_mov_b32_e32 v10, v196
	v_mov_b32_e32 v11, v197
	v_mov_b32_e32 v12, v198
	v_mov_b32_e32 v13, v199
	v_mov_b32_e32 v14, v192
	v_mov_b32_e32 v15, v193
	v_mov_b32_e32 v16, v194
	v_mov_b32_e32 v17, v195
	v_mov_b32_e32 v18, v188
	v_mov_b32_e32 v19, v189
	v_mov_b32_e32 v20, v190
	v_mov_b32_e32 v21, v191
	v_mov_b32_e32 v22, v184
	v_mov_b32_e32 v23, v185
	v_mov_b32_e32 v24, v186
	v_mov_b32_e32 v25, v187
	s_waitcnt vmcnt(0)
	v_fma_f32 v24, v38, v6, v24
	v_fma_f32 v25, v38, v7, v25
	v_fma_f32 v22, v38, v50, v22
	v_fma_f32 v23, v38, v51, v23
	v_max_f32_e64 v6, |v24|, |v25|
	v_max3_f32 v50, |v22|, |v23|, v6
	v_lshlrev_b32_e32 v6, 16, v8
	v_and_b32_e32 v7, 0xffff0000, v8
	v_lshlrev_b32_e32 v8, 16, v9
	v_and_b32_e32 v9, 0xffff0000, v9
	v_fma_f32 v8, v38, v8, v20
	v_fma_f32 v9, v38, v9, v21
	v_fma_f32 v18, v38, v6, v18
	v_fma_f32 v19, v38, v7, v19
	v_max_f32_e64 v6, |v8|, |v9|
	v_max3_f32 v6, |v18|, |v19|, v6
	v_max3_f32 v20, v39, v50, v6
	v_lshlrev_b32_e32 v6, 16, v2
	v_and_b32_e32 v7, 0xffff0000, v2
	v_lshlrev_b32_e32 v2, 16, v3
	v_and_b32_e32 v3, 0xffff0000, v3
	v_fma_f32 v16, v38, v2, v16
	v_fma_f32 v17, v38, v3, v17
	v_fma_f32 v14, v38, v6, v14
	v_fma_f32 v15, v38, v7, v15
	v_max_f32_e64 v2, |v16|, |v17|
	v_max3_f32 v6, |v14|, |v15|, v2
	v_lshlrev_b32_e32 v2, 16, v4
	v_and_b32_e32 v3, 0xffff0000, v4
	v_lshlrev_b32_e32 v4, 16, v5
	v_and_b32_e32 v5, 0xffff0000, v5
	v_fma_f32 v12, v38, v4, v12
	v_fma_f32 v13, v38, v5, v13
	v_fma_f32 v10, v38, v2, v10
	v_fma_f32 v11, v38, v3, v11
	v_max_f32_e64 v2, |v12|, |v13|
	v_max3_f32 v2, |v10|, |v11|, v2
	v_max3_f32 v2, v20, v6, v2
	s_nop 1
	v_mov_b32_dpp v3, v2 quad_perm:[1,0,3,2] row_mask:0xf bank_mask:0xf bound_ctrl:1
	v_max_f32_e32 v3, v3, v3
	v_max_f32_e32 v2, v2, v3
	s_nop 1
	v_mov_b32_dpp v3, v2 quad_perm:[2,3,0,1] row_mask:0xf bank_mask:0xf bound_ctrl:1
	v_max_f32_e32 v3, v3, v3
	v_max_f32_e32 v2, v2, v3
	s_nop 1
	v_mov_b32_dpp v3, v2 row_half_mirror row_mask:0xf bank_mask:0xf bound_ctrl:1
	v_max_f32_e32 v3, v3, v3
	v_max_f32_e32 v20, v2, v3
	v_div_scale_f32 v2, s[36:37], v20, v20, s35
	v_rcp_f32_e32 v3, v2
	v_cmp_lt_f32_e64 s[0:1], 0, v20
	v_fma_f32 v4, -v2, v3, 1.0
	v_fmac_f32_e32 v3, v4, v3
	v_div_scale_f32 v4, vcc, s35, v20, s35
	v_mul_f32_e32 v5, v4, v3
	v_fma_f32 v6, -v2, v5, v4
	v_fmac_f32_e32 v5, v6, v3
	v_fma_f32 v2, -v2, v5, v4
	v_div_fmas_f32 v2, v2, v3, v5
	v_div_fixup_f32 v2, v2, v20, s35
	v_cndmask_b32_e64 v5, 0, v2, s[0:1]
	v_mul_f32_e32 v2, v48, v5
	v_rndne_f32_e32 v2, v2
	v_cvt_i32_f32_e32 v2, v2
	v_mul_f32_e32 v15, v15, v5
	v_rndne_f32_e32 v15, v15
	v_cvt_i32_f32_e32 v15, v15
	v_add_u32_e32 v3, 8, v2
	v_and_b32_e32 v4, 15, v2
	v_mul_f32_e32 v2, v49, v5
	v_rndne_f32_e32 v2, v2
	v_cvt_i32_f32_e32 v2, v2
	v_lshrrev_b32_e32 v3, 4, v3
	v_mul_f32_e32 v16, v16, v5
	v_mul_f32_e32 v17, v17, v5
	v_add_u32_e32 v6, 8, v2
	v_and_b32_e32 v6, 0xf0, v6
	v_lshlrev_b32_e32 v2, 4, v2
	v_and_or_b32 v3, v3, 15, v6
	v_and_b32_e32 v6, 0xf0, v2
	v_mul_f32_e32 v2, v46, v5
	v_rndne_f32_e32 v2, v2
	v_cvt_i32_f32_e32 v2, v2
	v_rndne_f32_e32 v16, v16
	v_rndne_f32_e32 v17, v17
	v_cvt_i32_f32_e32 v16, v16
	v_lshl_add_u32 v7, v2, 4, v161
	v_lshlrev_b32_e32 v2, 8, v2
	v_and_b32_e32 v21, 0xf00, v2
	v_mul_f32_e32 v2, v47, v5
	v_rndne_f32_e32 v2, v2
	v_cvt_i32_f32_e32 v2, v2
	v_and_b32_e32 v7, 0xf00, v7
	v_cvt_i32_f32_e32 v17, v17
	v_mul_f32_e32 v10, v10, v5
	v_lshl_add_u32 v38, v2, 8, v162
	v_and_b32_e32 v38, 0xf000, v38
	v_lshlrev_b32_e32 v2, 12, v2
	v_or3_b32 v3, v3, v7, v38
	v_and_b32_e32 v7, 0xf000, v2
	v_mul_f32_e32 v2, v44, v5
	v_rndne_f32_e32 v2, v2
	v_cvt_i32_f32_e32 v2, v2
	v_mul_f32_e32 v11, v11, v5
	v_rndne_f32_e32 v10, v10
	v_rndne_f32_e32 v11, v11
	v_lshl_add_u32 v38, v2, 12, v163
	v_lshlrev_b32_e32 v2, 16, v2
	v_and_b32_e32 v39, 0xf0000, v2
	v_mul_f32_e32 v2, v45, v5
	v_rndne_f32_e32 v2, v2
	v_cvt_i32_f32_e32 v2, v2
	v_and_b32_e32 v38, 0xf0000, v38
	v_mul_f32_e32 v12, v12, v5
	v_cvt_i32_f32_e32 v10, v10
	v_lshl_add_u32 v44, v2, 16, v164
	v_and_b32_e32 v44, 0xf00000, v44
	v_lshlrev_b32_e32 v2, 20, v2
	v_or3_b32 v3, v3, v38, v44
	v_and_b32_e32 v38, 0xf00000, v2
	v_mul_f32_e32 v2, v42, v5
	v_rndne_f32_e32 v2, v2
	v_cvt_i32_f32_e32 v2, v2
	v_cvt_i32_f32_e32 v11, v11
	v_rndne_f32_e32 v12, v12
	v_cvt_i32_f32_e32 v12, v12
	v_lshl_add_u32 v42, v2, 20, v165
	v_lshlrev_b32_e32 v2, 24, v2
	v_and_b32_e32 v44, 0xf000000, v2
	v_mul_f32_e32 v2, v43, v5
	v_rndne_f32_e32 v2, v2
	v_cvt_i32_f32_e32 v43, v2
	v_and_b32_e32 v42, 0xf000000, v42
	v_lshl_add_u32 v2, v43, 24, v166
	v_and_b32_e32 v2, 0xf0000000, v2
	v_or3_b32 v2, v3, v42, v2
	v_lshl_or_b32 v3, v43, 28, v4
	v_or3_b32 v3, v3, v6, v21
	v_or3_b32 v3, v3, v7, v39
	v_or3_b32 v6, v3, v38, v44
	v_mul_f32_e32 v3, v40, v5
	v_rndne_f32_e32 v3, v3
	v_cvt_i32_f32_e32 v3, v3
	v_add_u32_e32 v4, 8, v3
; __device__ __forceinline__ void quant_h2_wave(int t0w, int c, const bf16* __restrict__ x1a, const float* __restrict__ ssq, const float* __restrict__ mod,
;                                               unsigned char* __restrict__ HQ, float* __restrict__ HS, int lane) {
;     ...
;         for (int k = 0; k < 4; ++k) { unsigned wa = 0u, wb = 0u;
; #pragma unroll
;             for (int i = 0; i < 8; ++i) { const float f = (i < 4) ? hv[2 * k][i] : hv[2 * k + 1][i - 4]; const int q = (int)rintf(f * sc); const int ahi = (q + 8) >> 4, blo = q - 16 * ahi;
;                 wa |= ((unsigned)ahi & 15u) << (4 * i); wb |= ((unsigned)blo & 15u) << (4 * i); }
;             oa[k] = wa; ob[k] = wb; }
;         unsigned char* dst = HQ + ((size_t)c * 16384 + t) * 256 + 32 * s;
;         *(v4u*)dst = oa; *(v4u*)(dst + 16) = ob;
;         if (s == 0) HS[(size_t)c * 16384 + t] = am * (1.f / 119.f);
	v_and_b32_e32 v7, 15, v3
	v_mul_f32_e32 v3, v41, v5
	v_rndne_f32_e32 v3, v3
	v_cvt_i32_f32_e32 v3, v3
	v_lshrrev_b32_e32 v4, 4, v4
	v_add_u32_e32 v21, 8, v3
	v_and_b32_e32 v21, 0xf0, v21
	v_lshlrev_b32_e32 v3, 4, v3
	v_and_or_b32 v4, v4, 15, v21
	v_and_b32_e32 v21, 0xf0, v3
	v_mul_f32_e32 v3, v36, v5
	v_rndne_f32_e32 v3, v3
	v_cvt_i32_f32_e32 v3, v3
	v_lshl_add_u32 v36, v3, 4, v161
	v_lshlrev_b32_e32 v3, 8, v3
	v_and_b32_e32 v38, 0xf00, v3
	v_mul_f32_e32 v3, v37, v5
	v_rndne_f32_e32 v3, v3
	v_cvt_i32_f32_e32 v3, v3
	v_and_b32_e32 v36, 0xf00, v36
	v_lshl_add_u32 v37, v3, 8, v162
	v_and_b32_e32 v37, 0xf000, v37
	v_lshlrev_b32_e32 v3, 12, v3
	v_or3_b32 v4, v4, v36, v37
	v_and_b32_e32 v36, 0xf000, v3
	v_mul_f32_e32 v3, v34, v5
	v_rndne_f32_e32 v3, v3
	v_cvt_i32_f32_e32 v3, v3
	v_lshl_add_u32 v34, v3, 12, v163
	v_lshlrev_b32_e32 v3, 16, v3
	v_and_b32_e32 v37, 0xf0000, v3
	v_mul_f32_e32 v3, v35, v5
	v_rndne_f32_e32 v3, v3
	v_cvt_i32_f32_e32 v3, v3
	v_and_b32_e32 v34, 0xf0000, v34
	v_lshl_add_u32 v35, v3, 16, v164
	v_and_b32_e32 v35, 0xf00000, v35
	v_lshlrev_b32_e32 v3, 20, v3
	v_or3_b32 v4, v4, v34, v35
	v_and_b32_e32 v34, 0xf00000, v3
	v_mul_f32_e32 v3, v32, v5
	v_rndne_f32_e32 v3, v3
	v_cvt_i32_f32_e32 v3, v3
	v_lshl_add_u32 v32, v3, 20, v165
	v_lshlrev_b32_e32 v3, 24, v3
	v_and_b32_e32 v35, 0xf000000, v3
	v_mul_f32_e32 v3, v33, v5
	v_rndne_f32_e32 v3, v3
	v_cvt_i32_f32_e32 v33, v3
	v_and_b32_e32 v32, 0xf000000, v32
	v_lshl_add_u32 v3, v33, 24, v166
	v_and_b32_e32 v3, 0xf0000000, v3
	v_or3_b32 v3, v4, v32, v3
	v_lshl_or_b32 v4, v33, 28, v7
	v_or3_b32 v4, v4, v21, v38
	v_or3_b32 v4, v4, v36, v37
	v_or3_b32 v7, v4, v34, v35
	v_mul_f32_e32 v4, v22, v5
	v_rndne_f32_e32 v4, v4
	v_cvt_i32_f32_e32 v4, v4
	v_add_u32_e32 v21, 8, v4
	v_and_b32_e32 v22, 15, v4
	v_mul_f32_e32 v4, v23, v5
	v_rndne_f32_e32 v4, v4
	v_cvt_i32_f32_e32 v4, v4
	v_lshrrev_b32_e32 v21, 4, v21
	v_add_u32_e32 v23, 8, v4
	v_and_b32_e32 v23, 0xf0, v23
	v_lshlrev_b32_e32 v4, 4, v4
	v_and_or_b32 v21, v21, 15, v23
	v_and_b32_e32 v23, 0xf0, v4
	v_mul_f32_e32 v4, v24, v5
	v_rndne_f32_e32 v4, v4
	v_cvt_i32_f32_e32 v4, v4
	v_lshl_add_u32 v24, v4, 4, v161
	v_lshlrev_b32_e32 v4, 8, v4
	v_and_b32_e32 v32, 0xf00, v4
	v_mul_f32_e32 v4, v25, v5
	v_rndne_f32_e32 v4, v4
	v_cvt_i32_f32_e32 v4, v4
	v_and_b32_e32 v24, 0xf00, v24
	v_lshl_add_u32 v25, v4, 8, v162
	v_and_b32_e32 v25, 0xf000, v25
	v_lshlrev_b32_e32 v4, 12, v4
	v_or3_b32 v21, v21, v24, v25
	v_and_b32_e32 v24, 0xf000, v4
	v_mul_f32_e32 v4, v18, v5
	v_rndne_f32_e32 v4, v4
	v_cvt_i32_f32_e32 v4, v4
	v_lshl_add_u32 v18, v4, 12, v163
	v_lshlrev_b32_e32 v4, 16, v4
	v_and_b32_e32 v25, 0xf0000, v4
	v_mul_f32_e32 v4, v19, v5
	v_rndne_f32_e32 v4, v4
	v_cvt_i32_f32_e32 v4, v4
	v_and_b32_e32 v18, 0xf0000, v18
	v_lshl_add_u32 v19, v4, 16, v164
	v_and_b32_e32 v19, 0xf00000, v19
	v_lshlrev_b32_e32 v4, 20, v4
	v_or3_b32 v18, v21, v18, v19
	v_and_b32_e32 v19, 0xf00000, v4
	v_mul_f32_e32 v4, v8, v5
	v_rndne_f32_e32 v4, v4
	v_cvt_i32_f32_e32 v4, v4
	v_lshl_add_u32 v8, v4, 20, v165
	v_lshlrev_b32_e32 v4, 24, v4
	v_and_b32_e32 v21, 0xf000000, v4
	v_mul_f32_e32 v4, v9, v5
	v_rndne_f32_e32 v4, v4
	v_cvt_i32_f32_e32 v9, v4
	v_and_b32_e32 v8, 0xf000000, v8
	v_lshl_add_u32 v4, v9, 24, v166
	v_and_b32_e32 v4, 0xf0000000, v4
	v_or3_b32 v4, v18, v8, v4
	v_lshl_or_b32 v8, v9, 28, v22
	v_mul_f32_e32 v9, v14, v5
	v_rndne_f32_e32 v9, v9
	v_cvt_i32_f32_e32 v9, v9
	v_mul_f32_e32 v5, v13, v5
	v_or3_b32 v8, v8, v23, v32
	v_add_u32_e32 v18, 8, v15
	v_add_u32_e32 v14, 8, v9
	v_rndne_f32_e32 v5, v5
	v_or3_b32 v8, v8, v24, v25
	v_lshrrev_b32_e32 v14, 4, v14
	v_and_b32_e32 v18, 0xf0, v18
	v_cvt_i32_f32_e32 v13, v5
	v_or3_b32 v8, v8, v19, v21
	v_and_or_b32 v14, v14, 15, v18
	v_lshl_add_u32 v18, v16, 4, v161
	v_lshl_add_u32 v19, v17, 8, v162
	v_and_b32_e32 v18, 0xf00, v18
	v_and_b32_e32 v19, 0xf000, v19
	v_and_b32_e32 v9, 15, v9
	v_lshlrev_b32_e32 v15, 4, v15
	v_lshlrev_b32_e32 v16, 8, v16
	v_or3_b32 v14, v14, v18, v19
	v_lshl_add_u32 v18, v10, 12, v163
	v_lshl_add_u32 v19, v11, 16, v164
	v_and_b32_e32 v15, 0xf0, v15
	v_and_b32_e32 v16, 0xf00, v16
	v_lshlrev_b32_e32 v17, 12, v17
	v_and_b32_e32 v18, 0xf0000, v18
	v_lshlrev_b32_e32 v10, 16, v10
	v_and_b32_e32 v19, 0xf00000, v19
	v_lshl_or_b32 v9, v13, 28, v9
	v_and_b32_e32 v17, 0xf000, v17
	v_and_b32_e32 v10, 0xf0000, v10
	v_or3_b32 v14, v14, v18, v19
	v_lshlrev_b32_e32 v11, 20, v11
	v_lshl_add_u32 v18, v12, 20, v165
	v_lshlrev_b32_e32 v12, 24, v12
	v_or3_b32 v9, v9, v15, v16
	v_and_b32_e32 v11, 0xf00000, v11
	v_and_b32_e32 v12, 0xf000000, v12
	v_or3_b32 v9, v9, v17, v10
	v_lshl_add_u32 v5, v13, 24, v166
	v_or3_b32 v9, v9, v11, v12
	v_lshl_add_u64 v[10:11], s[16:17], 0, v[30:31]
	v_and_b32_e32 v18, 0xf000000, v18
	v_and_b32_e32 v5, 0xf0000000, v5
	v_lshlrev_b64 v[12:13], 8, v[10:11]
	v_or3_b32 v5, v14, v18, v5
	v_lshl_add_u64 v[12:13], v[150:151], 0, v[12:13]
	global_store_dwordx4 v[12:13], v[2:5], off
	global_store_dwordx4 v[12:13], v[6:9], off offset:16
	s_and_saveexec_b64 s[0:1], s[4:5]
	s_cbranch_execz .LBB0_811
	v_mul_f32_e32 v4, 0x3c09ae41, v20
	v_lshl_add_u64 v[2:3], v[10:11], 2, s[10:11]
	global_store_dword v[2:3], v4, off
; __device__ __forceinline__ void quant_h2_wave(int t0w, int c, const bf16* __restrict__ x1a, const float* __restrict__ ssq, const float* __restrict__ mod,
;                                               unsigned char* __restrict__ HQ, float* __restrict__ HS, int lane) {
;     ...
;         const int t = t0w + pass * 8 + (lane >> 3), b = t >> 11;
;         const f32x4 s0 = *(const f32x4*)(ssq + (size_t)t * 16), s1 = *(const f32x4*)(ssq + (size_t)t * 16 + 4), s2 = *(const f32x4*)(ssq + (size_t)t * 16 + 8), s3 = *(const f32x4*)(ssq + (size_t)t * 16 + 12);
;         const float tot = ((s0.x + s0.y) + (s0.z + s0.w)) + ((s1.x + s1.y) + (s1.z + s1.w)) + ((s2.x + s2.y) + (s2.z + s2.w)) + ((s3.x + s3.y) + (s3.z + s3.w));
;         const float rstd = rsqrtf(tot * (1.f / 1024.f) + 1e-6f);
;         const float* be = mod + (size_t)b * 6144 + 3 * 1024 + k0;
;         f32x4 hv[8]; float am = 0.f;
; #pragma unroll
;         for (int u = 0; u < 4; ++u) { const v4u xa = *(const v4u*)(x1a + (size_t)t * 1024 + k0 + 8 * u);
; #pragma unroll
;             for (int hh = 0; hh < 2; ++hh) { const unsigned w0 = xa[2 * hh], w1 = xa[2 * hh + 1];
;                 const f32x4 xv = {__builtin_bit_cast(float, w0 << 16), __builtin_bit_cast(float, w0 & 0xffff0000u), __builtin_bit_cast(float, w1 << 16), __builtin_bit_cast(float, w1 & 0xffff0000u)};
;                 const f32x4 h = xv * rstd + *(const f32x4*)(be + 8 * u + 4 * hh); hv[2 * u + hh] = h;
;                 am = fmaxf(am, fmaxf(fmaxf(fabsf(h.x), fabsf(h.y)), fmaxf(fabsf(h.z), fabsf(h.w)))); } }
.LBB0_811:
	s_or_b64 exec, exec, s[0:1]
	v_or_b32_e32 v20, 8, v30
	v_ashrrev_i32_e32 v21, 31, v20
	v_lshlrev_b64 v[2:3], 6, v[20:21]
	v_lshl_add_u64 v[14:15], s[8:9], 0, v[2:3]
	v_mov_b32_e32 v2, v80
	v_mov_b32_e32 v3, v81
	v_mov_b32_e32 v4, v82
	v_mov_b32_e32 v5, v83
	v_mov_b32_e32 v6, v76
	v_mov_b32_e32 v7, v77
	v_mov_b32_e32 v8, v78
	v_mov_b32_e32 v9, v79
	v_mov_b32_e32 v10, v72
	v_mov_b32_e32 v11, v73
	v_mov_b32_e32 v12, v74
	v_mov_b32_e32 v13, v75
	s_nop 0
	v_mov_b32_e32 v14, v68
	v_mov_b32_e32 v15, v69
	v_mov_b32_e32 v16, v70
	v_mov_b32_e32 v17, v71
	s_waitcnt vmcnt(2)
	v_add_f32_e32 v6, v6, v7
	v_add_f32_e32 v8, v8, v9
	s_waitcnt vmcnt(0)
	v_mov_b32_e32 v18, v15
	v_mov_b32_e32 v19, v16
	v_mov_b32_e32 v15, v17
	v_mov_b32_e32 v16, v11
	v_mov_b32_e32 v17, v12
	v_mov_b32_e32 v11, v13
	v_add_f32_e32 v14, v18, v14
	v_add_f32_e32 v15, v19, v15
	v_add_f32_e32 v10, v16, v10
	v_add_f32_e32 v11, v17, v11
	v_pk_add_f32 v[14:15], v[14:15], v[14:15] op_sel:[0,1] op_sel_hi:[1,0]
	v_pk_add_f32 v[10:11], v[10:11], v[10:11] op_sel:[0,1] op_sel_hi:[1,0]
	v_mov_b32_e32 v15, v2
	v_mov_b32_e32 v11, v3
	v_mov_b32_e32 v7, v4
	v_mov_b32_e32 v9, v5
	v_add_f32_e32 v2, v14, v10
	v_add_f32_e32 v3, v15, v11
	v_add_f32_e32 v4, v6, v8
	v_add_f32_e32 v5, v7, v9
	s_nop 0
	v_add_f32_e32 v2, v2, v4
	v_add_f32_e32 v3, v3, v5
	s_nop 0
	v_add_f32_e32 v2, v2, v3
	v_fmamk_f32 v2, v2, 0x3a800000, v147
	v_cmp_gt_f32_e32 vcc, s59, v2
	v_mul_f32_e32 v3, 0x4b800000, v2
	s_nop 0
	v_cndmask_b32_e32 v2, v2, v3, vcc
	v_rsq_f32_e32 v2, v2
	s_nop 0
	v_mul_f32_e32 v3, 0x45800000, v2
	v_cndmask_b32_e32 v38, v2, v3, vcc
	v_lshlrev_b64 v[2:3], 11, v[20:21]
	v_lshl_add_u64 v[10:11], v[28:29], 0, v[2:3]
	v_mov_b32_e32 v2, v112
	v_mov_b32_e32 v3, v113
	v_mov_b32_e32 v4, v114
	v_mov_b32_e32 v5, v115
	v_mov_b32_e32 v12, v108
	v_mov_b32_e32 v13, v109
	v_mov_b32_e32 v14, v110
	v_mov_b32_e32 v15, v111
	v_mov_b32_e32 v6, v104
	v_mov_b32_e32 v7, v105
	v_mov_b32_e32 v8, v106
	v_mov_b32_e32 v9, v107
	v_mov_b32_e32 v16, v100
	v_mov_b32_e32 v17, v101
	v_mov_b32_e32 v18, v102
	v_mov_b32_e32 v19, v103
	v_mov_b32_e32 v46, v180
	v_mov_b32_e32 v47, v181
	v_mov_b32_e32 v48, v182
	v_mov_b32_e32 v49, v183
	v_mov_b32_e32 v22, v176
	v_mov_b32_e32 v23, v177
	v_mov_b32_e32 v24, v178
	v_mov_b32_e32 v25, v179
	v_mov_b32_e32 v28, v172
	v_mov_b32_e32 v29, v173
	v_mov_b32_e32 v30, v174
	v_mov_b32_e32 v31, v175
	v_mov_b32_e32 v32, v168
	v_mov_b32_e32 v33, v169
	v_mov_b32_e32 v34, v170
	v_mov_b32_e32 v35, v171
	s_waitcnt vmcnt(6)
	v_lshlrev_b32_e32 v36, 16, v13
	v_and_b32_e32 v37, 0xffff0000, v13
	s_waitcnt vmcnt(4)
	v_lshlrev_b32_e32 v10, 16, v16
	v_and_b32_e32 v11, 0xffff0000, v16
	v_lshlrev_b32_e32 v16, 16, v17
	v_and_b32_e32 v17, 0xffff0000, v17
	s_waitcnt vmcnt(0)
	v_fma_f32 v42, v38, v16, v34
	v_fma_f32 v43, v38, v17, v35
	v_fma_f32 v44, v38, v10, v32
	v_fma_f32 v45, v38, v11, v33
	v_max_f32_e64 v10, |v42|, |v43|
	v_lshlrev_b32_e32 v16, 16, v19
	v_and_b32_e32 v17, 0xffff0000, v19
	v_max3_f32 v32, |v44|, |v45|, v10
	v_lshlrev_b32_e32 v10, 16, v18
	v_and_b32_e32 v11, 0xffff0000, v18
	v_fma_f32 v34, v38, v16, v30
	v_fma_f32 v35, v38, v17, v31
	v_fma_f32 v40, v38, v10, v28
	v_fma_f32 v41, v38, v11, v29
	v_max_f32_e64 v10, |v34|, |v35|
	v_max3_f32 v10, |v40|, |v41|, v10
	v_max3_f32 v16, v32, 0, v10
	v_lshlrev_b32_e32 v10, 16, v6
	v_and_b32_e32 v11, 0xffff0000, v6
	v_lshlrev_b32_e32 v6, 16, v7
	v_and_b32_e32 v7, 0xffff0000, v7
	v_fma_f32 v28, v38, v6, v24
	v_fma_f32 v29, v38, v7, v25
	v_fma_f32 v32, v38, v10, v22
	v_fma_f32 v33, v38, v11, v23
	v_max_f32_e64 v6, |v28|, |v29|
	v_max3_f32 v10, |v32|, |v33|, v6
	v_lshlrev_b32_e32 v6, 16, v8
	v_and_b32_e32 v7, 0xffff0000, v8
	v_lshlrev_b32_e32 v8, 16, v9
	v_and_b32_e32 v9, 0xffff0000, v9
	v_fma_f32 v22, v38, v8, v48
	v_fma_f32 v23, v38, v9, v49
	v_fma_f32 v24, v38, v6, v46
	v_fma_f32 v25, v38, v7, v47
	v_max_f32_e64 v6, |v22|, |v23|
	v_max3_f32 v6, |v24|, |v25|, v6
	v_max3_f32 v39, v16, v10, v6
	v_lshlrev_b32_e32 v30, 16, v12
	v_and_b32_e32 v31, 0xffff0000, v12
	v_mov_b32_e32 v6, v196
	v_mov_b32_e32 v7, v197
	v_mov_b32_e32 v8, v198
	v_mov_b32_e32 v9, v199
	v_mov_b32_e32 v10, v192
	v_mov_b32_e32 v11, v193
	v_mov_b32_e32 v12, v194
	v_mov_b32_e32 v13, v195
	v_mov_b32_e32 v16, v188
	v_mov_b32_e32 v17, v189
	v_mov_b32_e32 v18, v190
	v_mov_b32_e32 v19, v191
	v_mov_b32_e32 v46, v184
	v_mov_b32_e32 v47, v185
	v_mov_b32_e32 v48, v186
	v_mov_b32_e32 v49, v187
	s_waitcnt vmcnt(0)
; __device__ __forceinline__ void quant_h2_wave(int t0w, int c, const bf16* __restrict__ x1a, const float* __restrict__ ssq, const float* __restrict__ mod,
;                                               unsigned char* __restrict__ HQ, float* __restrict__ HS, int lane) {
;     ...
;         for (int u = 0; u < 4; ++u) { const v4u xa = *(const v4u*)(x1a + (size_t)t * 1024 + k0 + 8 * u);
; #pragma unroll
;             for (int hh = 0; hh < 2; ++hh) { const unsigned w0 = xa[2 * hh], w1 = xa[2 * hh + 1];
;                 const f32x4 xv = {__builtin_bit_cast(float, w0 << 16), __builtin_bit_cast(float, w0 & 0xffff0000u), __builtin_bit_cast(float, w1 << 16), __builtin_bit_cast(float, w1 & 0xffff0000u)};
;                 const f32x4 h = xv * rstd + *(const f32x4*)(be + 8 * u + 4 * hh); hv[2 * u + hh] = h;
;                 am = fmaxf(am, fmaxf(fmaxf(fabsf(h.x), fabsf(h.y)), fmaxf(fabsf(h.z), fabsf(h.w)))); } }
;         am = max8_dpp(am);
;         const float sc = am > 0.f ? 119.f / am : 0.f;
;         v4u oa, ob;
; #pragma unroll
;         for (int k = 0; k < 4; ++k) { unsigned wa = 0u, wb = 0u;
; #pragma unroll
;             for (int i = 0; i < 8; ++i) { const float f = (i < 4) ? hv[2 * k][i] : hv[2 * k + 1][i - 4]; const int q = (int)rintf(f * sc); const int ahi = (q + 8) >> 4, blo = q - 16 * ahi;
;                 wa |= ((unsigned)ahi & 15u) << (4 * i); wb |= ((unsigned)blo & 15u) << (4 * i); }
	v_fma_f32 v26, v38, v36, v48
	v_fma_f32 v27, v38, v37, v49
	v_fma_f32 v30, v38, v30, v46
	v_fma_f32 v31, v38, v31, v47
	v_max_f32_e64 v36, |v26|, |v27|
	v_max3_f32 v46, |v30|, |v31|, v36
	v_lshlrev_b32_e32 v36, 16, v14
	v_and_b32_e32 v37, 0xffff0000, v14
	v_lshlrev_b32_e32 v14, 16, v15
	v_and_b32_e32 v15, 0xffff0000, v15
	v_fma_f32 v14, v38, v14, v18
	v_fma_f32 v15, v38, v15, v19
	v_fma_f32 v16, v38, v36, v16
	v_fma_f32 v17, v38, v37, v17
	v_max_f32_e64 v18, |v14|, |v15|
	v_max3_f32 v18, |v16|, |v17|, v18
	v_max3_f32 v39, v39, v46, v18
	v_lshlrev_b32_e32 v18, 16, v2
	v_and_b32_e32 v19, 0xffff0000, v2
	v_lshlrev_b32_e32 v2, 16, v3
	v_and_b32_e32 v3, 0xffff0000, v3
	v_fma_f32 v12, v38, v2, v12
	v_fma_f32 v13, v38, v3, v13
	v_fma_f32 v36, v38, v18, v10
	v_fma_f32 v37, v38, v19, v11
	v_max_f32_e64 v2, |v12|, |v13|
	v_max3_f32 v46, |v36|, |v37|, v2
	v_lshlrev_b32_e32 v2, 16, v4
	v_and_b32_e32 v3, 0xffff0000, v4
	v_lshlrev_b32_e32 v4, 16, v5
	v_and_b32_e32 v5, 0xffff0000, v5
	v_fma_f32 v10, v38, v4, v8
	v_fma_f32 v11, v38, v5, v9
	v_fma_f32 v18, v38, v2, v6
	v_fma_f32 v19, v38, v3, v7
	v_max_f32_e64 v2, |v10|, |v11|
	v_max3_f32 v2, |v18|, |v19|, v2
	v_max3_f32 v2, v39, v46, v2
	s_nop 1
	v_mov_b32_dpp v3, v2 quad_perm:[1,0,3,2] row_mask:0xf bank_mask:0xf bound_ctrl:1
	v_max_f32_e32 v3, v3, v3
	v_max_f32_e32 v2, v2, v3
	s_nop 1
	v_mov_b32_dpp v3, v2 quad_perm:[2,3,0,1] row_mask:0xf bank_mask:0xf bound_ctrl:1
	v_max_f32_e32 v3, v3, v3
	v_max_f32_e32 v2, v2, v3
	s_nop 1
	v_mov_b32_dpp v3, v2 row_half_mirror row_mask:0xf bank_mask:0xf bound_ctrl:1
	v_max_f32_e32 v3, v3, v3
	v_max_f32_e32 v38, v2, v3
	v_div_scale_f32 v2, s[36:37], v38, v38, s35
	v_rcp_f32_e32 v3, v2
	v_cmp_lt_f32_e64 s[0:1], 0, v38
	v_fma_f32 v4, -v2, v3, 1.0
	v_fmac_f32_e32 v3, v4, v3
	v_div_scale_f32 v4, vcc, s35, v38, s35
	v_mul_f32_e32 v5, v4, v3
	v_fma_f32 v6, -v2, v5, v4
	v_fmac_f32_e32 v5, v6, v3
	v_fma_f32 v2, -v2, v5, v4
	v_div_fmas_f32 v2, v2, v3, v5
	v_div_fixup_f32 v2, v2, v38, s35
	v_cndmask_b32_e64 v5, 0, v2, s[0:1]
	v_mul_f32_e32 v2, v44, v5
	v_rndne_f32_e32 v2, v2
	v_cvt_i32_f32_e32 v2, v2
	v_mul_f32_e32 v12, v12, v5
	v_mul_f32_e32 v13, v13, v5
	v_rndne_f32_e32 v12, v12
	v_add_u32_e32 v3, 8, v2
	v_and_b32_e32 v4, 15, v2
	v_mul_f32_e32 v2, v45, v5
	v_rndne_f32_e32 v2, v2
	v_cvt_i32_f32_e32 v2, v2
	v_lshrrev_b32_e32 v3, 4, v3
	v_rndne_f32_e32 v13, v13
	v_cvt_i32_f32_e32 v12, v12
	v_add_u32_e32 v6, 8, v2
	v_and_b32_e32 v6, 0xf0, v6
	v_lshlrev_b32_e32 v2, 4, v2
	v_and_or_b32 v3, v3, 15, v6
	v_and_b32_e32 v6, 0xf0, v2
	v_mul_f32_e32 v2, v42, v5
	v_rndne_f32_e32 v2, v2
	v_cvt_i32_f32_e32 v2, v2
	v_cvt_i32_f32_e32 v13, v13
	v_mul_f32_e32 v10, v10, v5
	v_rndne_f32_e32 v10, v10
	v_lshl_add_u32 v7, v2, 4, v161
	v_lshlrev_b32_e32 v2, 8, v2
	v_and_b32_e32 v8, 0xf00, v2
	v_mul_f32_e32 v2, v43, v5
	v_rndne_f32_e32 v2, v2
	v_cvt_i32_f32_e32 v2, v2
	v_and_b32_e32 v7, 0xf00, v7
	v_cvt_i32_f32_e32 v10, v10
	v_lshl_add_u32 v9, v2, 8, v162
	v_and_b32_e32 v9, 0xf000, v9
	v_lshlrev_b32_e32 v2, 12, v2
	v_or3_b32 v3, v3, v7, v9
	v_and_b32_e32 v7, 0xf000, v2
	v_mul_f32_e32 v2, v40, v5
	v_rndne_f32_e32 v2, v2
	v_cvt_i32_f32_e32 v2, v2
	v_lshl_add_u32 v9, v2, 12, v163
	v_lshlrev_b32_e32 v2, 16, v2
	v_and_b32_e32 v39, 0xf0000, v2
	v_mul_f32_e32 v2, v41, v5
	v_rndne_f32_e32 v2, v2
	v_cvt_i32_f32_e32 v2, v2
	v_and_b32_e32 v9, 0xf0000, v9
	v_lshl_add_u32 v40, v2, 16, v164
	v_and_b32_e32 v40, 0xf00000, v40
	v_lshlrev_b32_e32 v2, 20, v2
	v_or3_b32 v3, v3, v9, v40
	v_and_b32_e32 v9, 0xf00000, v2
	v_mul_f32_e32 v2, v34, v5
	v_rndne_f32_e32 v2, v2
	v_cvt_i32_f32_e32 v2, v2
	v_lshl_add_u32 v34, v2, 20, v165
	v_lshlrev_b32_e32 v2, 24, v2
	v_and_b32_e32 v40, 0xf000000, v2
	v_mul_f32_e32 v2, v35, v5
	v_rndne_f32_e32 v2, v2
	v_cvt_i32_f32_e32 v35, v2
	v_and_b32_e32 v34, 0xf000000, v34
	v_lshl_add_u32 v2, v35, 24, v166
	v_and_b32_e32 v2, 0xf0000000, v2
	v_or3_b32 v2, v3, v34, v2
	v_lshl_or_b32 v3, v35, 28, v4
	v_or3_b32 v3, v3, v6, v8
	v_or3_b32 v3, v3, v7, v39
	v_or3_b32 v6, v3, v9, v40
	v_mul_f32_e32 v3, v32, v5
	v_rndne_f32_e32 v3, v3
	v_cvt_i32_f32_e32 v3, v3
	v_add_u32_e32 v4, 8, v3
	v_and_b32_e32 v7, 15, v3
	v_mul_f32_e32 v3, v33, v5
	v_rndne_f32_e32 v3, v3
	v_cvt_i32_f32_e32 v3, v3
	v_lshrrev_b32_e32 v4, 4, v4
	v_add_u32_e32 v8, 8, v3
	v_and_b32_e32 v8, 0xf0, v8
	v_lshlrev_b32_e32 v3, 4, v3
	v_and_or_b32 v4, v4, 15, v8
	v_and_b32_e32 v8, 0xf0, v3
	v_mul_f32_e32 v3, v28, v5
	v_rndne_f32_e32 v3, v3
	v_cvt_i32_f32_e32 v3, v3
	v_lshl_add_u32 v9, v3, 4, v161
	v_lshlrev_b32_e32 v3, 8, v3
	v_and_b32_e32 v28, 0xf00, v3
	v_mul_f32_e32 v3, v29, v5
	v_rndne_f32_e32 v3, v3
	v_cvt_i32_f32_e32 v3, v3
	v_and_b32_e32 v9, 0xf00, v9
	v_lshl_add_u32 v29, v3, 8, v162
	v_and_b32_e32 v29, 0xf000, v29
	v_lshlrev_b32_e32 v3, 12, v3
; __device__ __forceinline__ void quant_h2_wave(int t0w, int c, const bf16* __restrict__ x1a, const float* __restrict__ ssq, const float* __restrict__ mod,
;                                               unsigned char* __restrict__ HQ, float* __restrict__ HS, int lane) {
;     ...
;         for (int k = 0; k < 4; ++k) { unsigned wa = 0u, wb = 0u;
; #pragma unroll
;             for (int i = 0; i < 8; ++i) { const float f = (i < 4) ? hv[2 * k][i] : hv[2 * k + 1][i - 4]; const int q = (int)rintf(f * sc); const int ahi = (q + 8) >> 4, blo = q - 16 * ahi;
;                 wa |= ((unsigned)ahi & 15u) << (4 * i); wb |= ((unsigned)blo & 15u) << (4 * i); }
;             oa[k] = wa; ob[k] = wb; }
;         unsigned char* dst = HQ + ((size_t)c * 16384 + t) * 256 + 32 * s;
;         *(v4u*)dst = oa; *(v4u*)(dst + 16) = ob;
;         if (s == 0) HS[(size_t)c * 16384 + t] = am * (1.f / 119.f);
;     }
; }
	v_or3_b32 v4, v4, v9, v29
	v_and_b32_e32 v9, 0xf000, v3
	v_mul_f32_e32 v3, v24, v5
	v_rndne_f32_e32 v3, v3
	v_cvt_i32_f32_e32 v3, v3
	v_lshl_add_u32 v24, v3, 12, v163
	v_lshlrev_b32_e32 v3, 16, v3
	v_and_b32_e32 v29, 0xf0000, v3
	v_mul_f32_e32 v3, v25, v5
	v_rndne_f32_e32 v3, v3
	v_cvt_i32_f32_e32 v3, v3
	v_and_b32_e32 v24, 0xf0000, v24
	v_lshl_add_u32 v25, v3, 16, v164
	v_and_b32_e32 v25, 0xf00000, v25
	v_lshlrev_b32_e32 v3, 20, v3
	v_or3_b32 v4, v4, v24, v25
	v_and_b32_e32 v24, 0xf00000, v3
	v_mul_f32_e32 v3, v22, v5
	v_rndne_f32_e32 v3, v3
	v_cvt_i32_f32_e32 v3, v3
	v_lshl_add_u32 v22, v3, 20, v165
	v_lshlrev_b32_e32 v3, 24, v3
	v_and_b32_e32 v25, 0xf000000, v3
	v_mul_f32_e32 v3, v23, v5
	v_rndne_f32_e32 v3, v3
	v_cvt_i32_f32_e32 v23, v3
	v_and_b32_e32 v22, 0xf000000, v22
	v_lshl_add_u32 v3, v23, 24, v166
	v_and_b32_e32 v3, 0xf0000000, v3
	v_or3_b32 v3, v4, v22, v3
	v_lshl_or_b32 v4, v23, 28, v7
	v_or3_b32 v4, v4, v8, v28
	v_or3_b32 v4, v4, v9, v29
	v_or3_b32 v7, v4, v24, v25
	v_mul_f32_e32 v4, v30, v5
	v_rndne_f32_e32 v4, v4
	v_cvt_i32_f32_e32 v4, v4
	v_add_u32_e32 v8, 8, v4
	v_and_b32_e32 v9, 15, v4
	v_mul_f32_e32 v4, v31, v5
	v_rndne_f32_e32 v4, v4
	v_cvt_i32_f32_e32 v4, v4
	v_lshrrev_b32_e32 v8, 4, v8
	v_add_u32_e32 v22, 8, v4
	v_and_b32_e32 v22, 0xf0, v22
	v_lshlrev_b32_e32 v4, 4, v4
	v_and_or_b32 v8, v8, 15, v22
	v_and_b32_e32 v22, 0xf0, v4
	v_mul_f32_e32 v4, v26, v5
	v_rndne_f32_e32 v4, v4
	v_cvt_i32_f32_e32 v4, v4
	v_lshl_add_u32 v23, v4, 4, v161
	v_lshlrev_b32_e32 v4, 8, v4
	v_and_b32_e32 v24, 0xf00, v4
	v_mul_f32_e32 v4, v27, v5
	v_rndne_f32_e32 v4, v4
	v_cvt_i32_f32_e32 v4, v4
	v_and_b32_e32 v23, 0xf00, v23
	v_lshl_add_u32 v25, v4, 8, v162
	v_and_b32_e32 v25, 0xf000, v25
	v_lshlrev_b32_e32 v4, 12, v4
	v_or3_b32 v8, v8, v23, v25
	v_and_b32_e32 v23, 0xf000, v4
	v_mul_f32_e32 v4, v16, v5
	v_rndne_f32_e32 v4, v4
	v_cvt_i32_f32_e32 v4, v4
	v_lshl_add_u32 v16, v4, 12, v163
	v_lshlrev_b32_e32 v4, 16, v4
	v_and_b32_e32 v25, 0xf0000, v4
	v_mul_f32_e32 v4, v17, v5
	v_rndne_f32_e32 v4, v4
	v_cvt_i32_f32_e32 v4, v4
	v_and_b32_e32 v16, 0xf0000, v16
	v_lshl_add_u32 v17, v4, 16, v164
	v_and_b32_e32 v17, 0xf00000, v17
	v_lshlrev_b32_e32 v4, 20, v4
	v_or3_b32 v8, v8, v16, v17
	v_and_b32_e32 v16, 0xf00000, v4
	v_mul_f32_e32 v4, v14, v5
	v_rndne_f32_e32 v4, v4
	v_cvt_i32_f32_e32 v4, v4
	v_lshl_add_u32 v14, v4, 20, v165
	v_lshlrev_b32_e32 v4, 24, v4
	v_and_b32_e32 v17, 0xf000000, v4
	v_mul_f32_e32 v4, v15, v5
	v_rndne_f32_e32 v4, v4
	v_cvt_i32_f32_e32 v15, v4
	v_and_b32_e32 v14, 0xf000000, v14
	v_lshl_add_u32 v4, v15, 24, v166
	v_and_b32_e32 v4, 0xf0000000, v4
	v_or3_b32 v4, v8, v14, v4
	v_lshl_or_b32 v8, v15, 28, v9
	v_mul_f32_e32 v9, v36, v5
	v_mul_f32_e32 v15, v37, v5
	v_rndne_f32_e32 v9, v9
	v_rndne_f32_e32 v15, v15
	v_cvt_i32_f32_e32 v9, v9
	v_cvt_i32_f32_e32 v15, v15
	v_or3_b32 v8, v8, v22, v24
	v_or3_b32 v8, v8, v23, v25
	v_or3_b32 v8, v8, v16, v17
	v_add_u32_e32 v14, 8, v9
	v_add_u32_e32 v16, 8, v15
	v_lshrrev_b32_e32 v14, 4, v14
	v_and_b32_e32 v16, 0xf0, v16
	v_and_or_b32 v14, v14, 15, v16
	v_lshl_add_u32 v16, v12, 4, v161
	v_lshl_add_u32 v17, v13, 8, v162
	v_and_b32_e32 v16, 0xf00, v16
	v_and_b32_e32 v17, 0xf000, v17
	v_or3_b32 v14, v14, v16, v17
	v_mul_f32_e32 v16, v18, v5
	v_mul_f32_e32 v18, v19, v5
	v_rndne_f32_e32 v16, v16
	v_rndne_f32_e32 v18, v18
	v_mul_f32_e32 v5, v11, v5
	v_cvt_i32_f32_e32 v16, v16
	v_cvt_i32_f32_e32 v18, v18
	v_rndne_f32_e32 v5, v5
	v_cvt_i32_f32_e32 v11, v5
	v_and_b32_e32 v9, 15, v9
	v_lshlrev_b32_e32 v15, 4, v15
	v_lshlrev_b32_e32 v12, 8, v12
	v_lshl_add_u32 v17, v16, 12, v163
	v_lshl_add_u32 v19, v18, 16, v164
	v_and_b32_e32 v15, 0xf0, v15
	v_and_b32_e32 v12, 0xf00, v12
	v_lshlrev_b32_e32 v13, 12, v13
	v_and_b32_e32 v17, 0xf0000, v17
	v_lshlrev_b32_e32 v16, 16, v16
	v_and_b32_e32 v19, 0xf00000, v19
	v_lshl_or_b32 v9, v11, 28, v9
	v_and_b32_e32 v13, 0xf000, v13
	v_and_b32_e32 v16, 0xf0000, v16
	v_or3_b32 v14, v14, v17, v19
	v_lshlrev_b32_e32 v17, 20, v18
	v_lshl_add_u32 v18, v10, 20, v165
	v_lshlrev_b32_e32 v10, 24, v10
	v_or3_b32 v9, v9, v15, v12
	v_and_b32_e32 v17, 0xf00000, v17
	v_and_b32_e32 v10, 0xf000000, v10
	v_or3_b32 v9, v9, v13, v16
	v_lshl_add_u32 v5, v11, 24, v166
	v_or3_b32 v9, v9, v17, v10
	v_lshl_add_u64 v[10:11], s[16:17], 0, v[20:21]
	v_and_b32_e32 v18, 0xf000000, v18
	v_and_b32_e32 v5, 0xf0000000, v5
	v_lshlrev_b64 v[12:13], 8, v[10:11]
	v_or3_b32 v5, v14, v18, v5
	v_lshl_add_u64 v[12:13], v[150:151], 0, v[12:13]
	global_store_dwordx4 v[12:13], v[2:5], off
	global_store_dwordx4 v[12:13], v[6:9], off offset:16
	s_and_saveexec_b64 s[0:1], s[4:5]
	s_cbranch_execz .LBB0_792
	v_mul_f32_e32 v4, 0x3c09ae41, v38
	v_lshl_add_u64 v[2:3], v[10:11], 2, s[10:11]
	global_store_dword v[2:3], v4, off
	s_branch .LBB0_792
